# phase 0: weight-column staging and mem_prompt conversion loops unrolled (all loads issued before the first wait); pooling fast path defers its stores until all row loads landed
# baseline (speedup 1.0000x reference)
; DI void phase_prep(const Params& p, char* smem) {
;     ...
;     for (int i = blockIdx.x * 256 + threadIdx.x; i < 4 * NROW; i += gridDim.x * 256) p.SS[i] = 0.f;
;     const int n4 = 2048 * 1024 / 4;
;     for (int i = blockIdx.x * 256 + threadIdx.x; i < n4; i += gridDim.x * 256) {
;       float4 v = ((const float4*)p.mem_prompt)[i];
;       uint2 o;
;       o.x = pack2(v.x, v.y);
;       o.y = pack2(v.z, v.w);
;       ((uint2*)p.MPB)[i] = o;
;     }
.LBB0_42:
	s_or_b64 exec, exec, s[0:1]
	s_mov_b32 s0, 0x80000
	v_cmp_gt_i32_e32 vcc, s0, v0
	s_and_saveexec_b64 s[0:1], vcc
	s_cbranch_execz .LBB0_45
	s_load_dwordx2 s[2:3], s[92:93], 0x40
	s_load_dwordx2 s[4:5], s[92:93], 0x180
	s_cmp_eq_u32 s34, 0x200
	s_cbranch_scc0 .Lprep_mp_slow
	v_lshlrev_b32_e32 v1, 4, v0
	v_lshlrev_b32_e32 v2, 3, v0
	s_waitcnt lgkmcnt(0)
	global_load_dwordx4 v[4:7], v1, s[2:3]
	s_add_u32 s2, s2, 0x200000
	s_addc_u32 s3, s3, 0
	global_load_dwordx4 v[8:11], v1, s[2:3]
	s_add_u32 s2, s2, 0x200000
	s_addc_u32 s3, s3, 0
	global_load_dwordx4 v[12:15], v1, s[2:3]
	s_add_u32 s2, s2, 0x200000
	s_addc_u32 s3, s3, 0
	global_load_dwordx4 v[16:19], v1, s[2:3]
	s_waitcnt vmcnt(3)
	v_cvt_pk_bf16_f32 v4, v4, v5
	v_cvt_pk_bf16_f32 v5, v6, v7
	s_waitcnt vmcnt(2)
	v_cvt_pk_bf16_f32 v8, v8, v9
	v_cvt_pk_bf16_f32 v9, v10, v11
	s_waitcnt vmcnt(1)
	v_cvt_pk_bf16_f32 v12, v12, v13
	v_cvt_pk_bf16_f32 v13, v14, v15
	s_waitcnt vmcnt(0)
	v_cvt_pk_bf16_f32 v16, v16, v17
	v_cvt_pk_bf16_f32 v17, v18, v19
	global_store_dwordx2 v2, v[4:5], s[4:5]
	s_add_u32 s4, s4, 0x100000
	s_addc_u32 s5, s5, 0
	global_store_dwordx2 v2, v[8:9], s[4:5]
	s_add_u32 s4, s4, 0x100000
	s_addc_u32 s5, s5, 0
	global_store_dwordx2 v2, v[12:13], s[4:5]
	s_add_u32 s4, s4, 0x100000
	s_addc_u32 s5, s5, 0
	global_store_dwordx2 v2, v[16:17], s[4:5]
	s_branch .LBB0_45
.Lprep_mp_slow:
	s_lshl_b32 s8, s34, 8
	s_mov_b64 s[6:7], 0
	s_mov_b32 s9, 0x7ffff

; DI int opaque_tid() { int t = threadIdx.x; asm volatile("" : "+v"(t)); return t; }
; DI void phase_prep(const Params& p, char* smem) {
;     ...
;     for (int i = opaque_tid(); i < 2048; i += 256) {
;       const int k = i >> 1, hf = i & 1;
;       float4 w = *(const float4*)(p.w_in_even + (size_t)k * EIN + EINP + hf * 4);
;       wT[(hf * 4 + 0) * 1024 + k] = w.x; wT[(hf * 4 + 1) * 1024 + k] = w.y;
;       wT[(hf * 4 + 2) * 1024 + k] = w.z; wT[(hf * 4 + 3) * 1024 + k] = w.w;
;     }
.LBB0_45:
	s_or_b64 exec, exec, s[0:1]
	v_mov_b32_e32 v4, v196
	s_movk_i32 s0, 0x800
	s_nop 0
	v_cmp_gt_i32_e32 vcc, s0, v4
	s_and_saveexec_b64 s[0:1], vcc
	s_cbranch_execz .LBB0_48
	s_load_dwordx2 s[6:7], s[92:93], 0x60
	v_lshrrev_b32_e32 v10, 1, v4
	v_and_b32_e32 v11, 1, v4
	v_mul_u32_u24_e32 v12, 0x3820, v10
	v_lshlrev_b32_e32 v13, 2, v10
	v_lshl_add_u32 v12, v11, 4, v12
	v_lshl_add_u32 v13, v11, 14, v13
	s_waitcnt lgkmcnt(0)
	s_add_u32 s6, s6, 0x3800
	s_addc_u32 s7, s7, 0
	global_load_dwordx4 v[16:19], v12, s[6:7]
	s_add_u32 s6, s6, 0x1c1000
	s_addc_u32 s7, s7, 0
	global_load_dwordx4 v[20:23], v12, s[6:7]
	s_add_u32 s6, s6, 0x1c1000
	s_addc_u32 s7, s7, 0
	global_load_dwordx4 v[24:27], v12, s[6:7]
	s_add_u32 s6, s6, 0x1c1000
	s_addc_u32 s7, s7, 0
	global_load_dwordx4 v[28:31], v12, s[6:7]
	s_add_u32 s6, s6, 0x1c1000
	s_addc_u32 s7, s7, 0
	global_load_dwordx4 v[32:35], v12, s[6:7]
	s_add_u32 s6, s6, 0x1c1000
	s_addc_u32 s7, s7, 0
	global_load_dwordx4 v[36:39], v12, s[6:7]
	s_add_u32 s6, s6, 0x1c1000
	s_addc_u32 s7, s7, 0
	global_load_dwordx4 v[40:43], v12, s[6:7]
	s_add_u32 s6, s6, 0x1c1000
	s_addc_u32 s7, s7, 0
	global_load_dwordx4 v[44:47], v12, s[6:7]
	s_waitcnt vmcnt(7)
	ds_write2st64_b32 v13, v16, v17 offset0:0 offset1:16
	ds_write2st64_b32 v13, v18, v19 offset0:32 offset1:48
	s_waitcnt vmcnt(6)
	ds_write2st64_b32 v13, v20, v21 offset0:2 offset1:18
	ds_write2st64_b32 v13, v22, v23 offset0:34 offset1:50
	s_waitcnt vmcnt(5)
	ds_write2st64_b32 v13, v24, v25 offset0:4 offset1:20
	ds_write2st64_b32 v13, v26, v27 offset0:36 offset1:52
	s_waitcnt vmcnt(4)
	ds_write2st64_b32 v13, v28, v29 offset0:6 offset1:22
	ds_write2st64_b32 v13, v30, v31 offset0:38 offset1:54
	s_waitcnt vmcnt(3)
	ds_write2st64_b32 v13, v32, v33 offset0:8 offset1:24
	ds_write2st64_b32 v13, v34, v35 offset0:40 offset1:56
	s_waitcnt vmcnt(2)
	ds_write2st64_b32 v13, v36, v37 offset0:10 offset1:26
	ds_write2st64_b32 v13, v38, v39 offset0:42 offset1:58
	s_waitcnt vmcnt(1)
	ds_write2st64_b32 v13, v40, v41 offset0:12 offset1:28
	ds_write2st64_b32 v13, v42, v43 offset0:44 offset1:60
	s_waitcnt vmcnt(0)
	ds_write2st64_b32 v13, v44, v45 offset0:14 offset1:30
	ds_write2st64_b32 v13, v46, v47 offset0:46 offset1:62

; DI float bflo(unsigned u) { return __uint_as_float(u << 16); }
; DI float bfhi(unsigned u) { return __uint_as_float(u & 0xffff0000u); }
; template <int WIN>
; DI void pool_elem(const Params& p, int row, int c) {
;   const bfr* P2 = p.PB;
;   unsigned uu = *(const unsigned*)(P2 + (size_t)row * 2048 + c);
;   const float u0 = bflo(uu), u1 = bfhi(uu);
;   float s0 = u0, s1 = u1, cnt;
;   if (row < NPR) {
;     const int t = row & 2047, b = row >> 11;
;     if (t >= WIN - 1) {
;       cnt = (float)WIN;
;       unsigned w[WIN - 1];
; #pragma unroll
;       for (int j = 1; j < WIN; ++j) w[j - 1] = *(const unsigned*)(P2 + (size_t)(row - j) * 2048 + c);
; #pragma unroll
;       for (int j = 1; j < WIN; ++j) { s0 += bflo(w[j - 1]); s1 += bfhi(w[j - 1]); }
;     ...
;   *(unsigned*)(p.MIX + (size_t)row * 1024 + c) = pack2(s0 / cnt - u0, s1 / cnt - u1);
.Lp13f_w0:
	s_sub_u32 s26, s20, 1
	s_lshl_b32 s27, s26, 12
	s_lshr_b32 s28, s26, 20
	s_add_u32 s22, s8, s27
	s_addc_u32 s23, s9, s28
	global_load_dwordx2 v[16:17], v11, s[22:23]
	s_add_u32 s22, s22, 0x1000
	s_addc_u32 s23, s23, 0
	global_load_dwordx2 v[20:21], v11, s[22:23]
	s_add_u32 s22, s22, 0x1000
	s_addc_u32 s23, s23, 0
	global_load_dwordx2 v[24:25], v11, s[22:23]
	s_add_u32 s22, s22, 0x1000
	s_addc_u32 s23, s23, 0
	global_load_dwordx2 v[28:29], v11, s[22:23]
	s_add_u32 s22, s22, 0x1000
	s_addc_u32 s23, s23, 0
	global_load_dwordx2 v[32:33], v11, s[22:23]
	s_add_u32 s22, s22, 0x1000
	s_addc_u32 s23, s23, 0
	global_load_dwordx2 v[36:37], v11, s[22:23]
	s_add_u32 s22, s22, 0x1000
	s_addc_u32 s23, s23, 0
	global_load_dwordx2 v[40:41], v11, s[22:23]
	s_add_u32 s22, s22, 0x1000
	s_addc_u32 s23, s23, 0
	global_load_dwordx2 v[44:45], v11, s[22:23]
	s_add_u32 s22, s22, 0x1000
	s_addc_u32 s23, s23, 0
	global_load_dwordx2 v[48:49], v11, s[22:23]
	s_add_u32 s22, s22, 0x1000
	s_addc_u32 s23, s23, 0
	global_load_dwordx2 v[52:53], v11, s[22:23]
	s_add_u32 s22, s22, 0x1000
	s_addc_u32 s23, s23, 0
	global_load_dwordx2 v[56:57], v11, s[22:23]
	s_add_u32 s22, s22, 0x1000
	s_addc_u32 s23, s23, 0
	global_load_dwordx2 v[60:61], v11, s[22:23]
	s_add_u32 s22, s22, 0x1000
	s_addc_u32 s23, s23, 0
	global_load_dwordx2 v[64:65], v11, s[22:23]
	s_add_u32 s22, s22, 0x1000
	s_addc_u32 s23, s23, 0
	global_load_dwordx2 v[68:69], v11, s[22:23]
	s_add_u32 s22, s22, 0x1000
	s_addc_u32 s23, s23, 0
	global_load_dwordx2 v[72:73], v11, s[22:23]
	s_add_u32 s22, s22, 0x1000
	s_addc_u32 s23, s23, 0
	global_load_dwordx2 v[76:77], v11, s[22:23]
	s_add_u32 s22, s22, 0x1000
	s_addc_u32 s23, s23, 0
	global_load_dwordx2 v[80:81], v11, s[22:23]
	s_add_u32 s22, s22, 0x1000
	s_addc_u32 s23, s23, 0
	s_waitcnt vmcnt(15)
	v_and_b32_e32 v19, 0xffff0000, v17
	v_lshlrev_b32_e32 v18, 16, v17
	v_and_b32_e32 v17, 0xffff0000, v16
	v_lshlrev_b32_e32 v16, 16, v16
	v_and_b32_e32 v23, 0xffff0000, v21
	v_lshlrev_b32_e32 v22, 16, v21
	v_and_b32_e32 v21, 0xffff0000, v20
	v_lshlrev_b32_e32 v20, 16, v20
	v_add_f32_e32 v140, v20, v16
	v_add_f32_e32 v141, v21, v17
	v_add_f32_e32 v142, v22, v18
	v_add_f32_e32 v143, v23, v19
	v_mul_f32_e32 v140, 0.5, v140
	v_mul_f32_e32 v141, 0.5, v141
	v_mul_f32_e32 v142, 0.5, v142
	v_mul_f32_e32 v143, 0.5, v143
	v_sub_f32_e32 v140, v140, v20
	v_sub_f32_e32 v141, v141, v21
	v_sub_f32_e32 v142, v142, v22
	v_sub_f32_e32 v143, v143, v23
	v_cvt_pk_bf16_f32 v152, v140, v141
	v_cvt_pk_bf16_f32 v153, v142, v143
	s_waitcnt vmcnt(14)
	v_and_b32_e32 v27, 0xffff0000, v25
	v_lshlrev_b32_e32 v26, 16, v25
	v_and_b32_e32 v25, 0xffff0000, v24
	v_lshlrev_b32_e32 v24, 16, v24
	v_add_f32_e32 v140, v24, v20
	v_add_f32_e32 v141, v25, v21
	v_add_f32_e32 v142, v26, v22
	v_add_f32_e32 v143, v27, v23
	v_mul_f32_e32 v140, 0.5, v140
	v_mul_f32_e32 v141, 0.5, v141
	v_mul_f32_e32 v142, 0.5, v142
	v_mul_f32_e32 v143, 0.5, v143
	v_sub_f32_e32 v140, v140, v24
	v_sub_f32_e32 v141, v141, v25
	v_sub_f32_e32 v142, v142, v26
	v_sub_f32_e32 v143, v143, v27
	v_cvt_pk_bf16_f32 v154, v140, v141
	v_cvt_pk_bf16_f32 v155, v142, v143
	s_waitcnt vmcnt(13)
	v_and_b32_e32 v31, 0xffff0000, v29
	v_lshlrev_b32_e32 v30, 16, v29
	v_and_b32_e32 v29, 0xffff0000, v28
	v_lshlrev_b32_e32 v28, 16, v28
	v_add_f32_e32 v140, v28, v24
	v_add_f32_e32 v141, v29, v25
	v_add_f32_e32 v142, v30, v26
	v_add_f32_e32 v143, v31, v27
	v_mul_f32_e32 v140, 0.5, v140
	v_mul_f32_e32 v141, 0.5, v141
	v_mul_f32_e32 v142, 0.5, v142
	v_mul_f32_e32 v143, 0.5, v143
	v_sub_f32_e32 v140, v140, v28
	v_sub_f32_e32 v141, v141, v29
	v_sub_f32_e32 v142, v142, v30
	v_sub_f32_e32 v143, v143, v31
	v_cvt_pk_bf16_f32 v156, v140, v141
	v_cvt_pk_bf16_f32 v157, v142, v143
	s_waitcnt vmcnt(12)
	v_and_b32_e32 v35, 0xffff0000, v33
	v_lshlrev_b32_e32 v34, 16, v33
	v_and_b32_e32 v33, 0xffff0000, v32
	v_lshlrev_b32_e32 v32, 16, v32
	v_add_f32_e32 v140, v32, v28
	v_add_f32_e32 v141, v33, v29
	v_add_f32_e32 v142, v34, v30
	v_add_f32_e32 v143, v35, v31
	v_mul_f32_e32 v140, 0.5, v140
	v_mul_f32_e32 v141, 0.5, v141
	v_mul_f32_e32 v142, 0.5, v142
	v_mul_f32_e32 v143, 0.5, v143
	v_sub_f32_e32 v140, v140, v32
	v_sub_f32_e32 v141, v141, v33
	v_sub_f32_e32 v142, v142, v34
	v_sub_f32_e32 v143, v143, v35
	v_cvt_pk_bf16_f32 v158, v140, v141
	v_cvt_pk_bf16_f32 v159, v142, v143
	s_waitcnt vmcnt(11)
	v_and_b32_e32 v39, 0xffff0000, v37
	v_lshlrev_b32_e32 v38, 16, v37
	v_and_b32_e32 v37, 0xffff0000, v36
	v_lshlrev_b32_e32 v36, 16, v36
	v_add_f32_e32 v140, v36, v32
	v_add_f32_e32 v141, v37, v33
	v_add_f32_e32 v142, v38, v34
	v_add_f32_e32 v143, v39, v35
	v_mul_f32_e32 v140, 0.5, v140
	v_mul_f32_e32 v141, 0.5, v141
	v_mul_f32_e32 v142, 0.5, v142
	v_mul_f32_e32 v143, 0.5, v143
	v_sub_f32_e32 v140, v140, v36
	v_sub_f32_e32 v141, v141, v37
	v_sub_f32_e32 v142, v142, v38
	v_sub_f32_e32 v143, v143, v39
	v_cvt_pk_bf16_f32 v160, v140, v141
	v_cvt_pk_bf16_f32 v161, v142, v143
	s_waitcnt vmcnt(10)
	v_and_b32_e32 v43, 0xffff0000, v41
	v_lshlrev_b32_e32 v42, 16, v41
	v_and_b32_e32 v41, 0xffff0000, v40
	v_lshlrev_b32_e32 v40, 16, v40
	v_add_f32_e32 v140, v40, v36
	v_add_f32_e32 v141, v41, v37
	v_add_f32_e32 v142, v42, v38
	v_add_f32_e32 v143, v43, v39
	v_mul_f32_e32 v140, 0.5, v140
	v_mul_f32_e32 v141, 0.5, v141
	v_mul_f32_e32 v142, 0.5, v142
	v_mul_f32_e32 v143, 0.5, v143
	v_sub_f32_e32 v140, v140, v40
	v_sub_f32_e32 v141, v141, v41
	v_sub_f32_e32 v142, v142, v42
	v_sub_f32_e32 v143, v143, v43
	v_cvt_pk_bf16_f32 v162, v140, v141
	v_cvt_pk_bf16_f32 v163, v142, v143
	s_waitcnt vmcnt(9)
; DI float bflo(unsigned u) { return __uint_as_float(u << 16); }
; DI float bfhi(unsigned u) { return __uint_as_float(u & 0xffff0000u); }
; template <int WIN>
; DI void pool_elem(const Params& p, int row, int c) {
;     ...
;     if (t >= WIN - 1) {
;       cnt = (float)WIN;
;       unsigned w[WIN - 1];
; #pragma unroll
;       for (int j = 1; j < WIN; ++j) w[j - 1] = *(const unsigned*)(P2 + (size_t)(row - j) * 2048 + c);
; #pragma unroll
;       for (int j = 1; j < WIN; ++j) { s0 += bflo(w[j - 1]); s1 += bfhi(w[j - 1]); }
;     ...
;   *(unsigned*)(p.MIX + (size_t)row * 1024 + c) = pack2(s0 / cnt - u0, s1 / cnt - u1);
	v_and_b32_e32 v47, 0xffff0000, v45
	v_lshlrev_b32_e32 v46, 16, v45
	v_and_b32_e32 v45, 0xffff0000, v44
	v_lshlrev_b32_e32 v44, 16, v44
	v_add_f32_e32 v140, v44, v40
	v_add_f32_e32 v141, v45, v41
	v_add_f32_e32 v142, v46, v42
	v_add_f32_e32 v143, v47, v43
	v_mul_f32_e32 v140, 0.5, v140
	v_mul_f32_e32 v141, 0.5, v141
	v_mul_f32_e32 v142, 0.5, v142
	v_mul_f32_e32 v143, 0.5, v143
	v_sub_f32_e32 v140, v140, v44
	v_sub_f32_e32 v141, v141, v45
	v_sub_f32_e32 v142, v142, v46
	v_sub_f32_e32 v143, v143, v47
	v_cvt_pk_bf16_f32 v164, v140, v141
	v_cvt_pk_bf16_f32 v165, v142, v143
	s_waitcnt vmcnt(8)
	v_and_b32_e32 v51, 0xffff0000, v49
	v_lshlrev_b32_e32 v50, 16, v49
	v_and_b32_e32 v49, 0xffff0000, v48
	v_lshlrev_b32_e32 v48, 16, v48
	v_add_f32_e32 v140, v48, v44
	v_add_f32_e32 v141, v49, v45
	v_add_f32_e32 v142, v50, v46
	v_add_f32_e32 v143, v51, v47
	v_mul_f32_e32 v140, 0.5, v140
	v_mul_f32_e32 v141, 0.5, v141
	v_mul_f32_e32 v142, 0.5, v142
	v_mul_f32_e32 v143, 0.5, v143
	v_sub_f32_e32 v140, v140, v48
	v_sub_f32_e32 v141, v141, v49
	v_sub_f32_e32 v142, v142, v50
	v_sub_f32_e32 v143, v143, v51
	v_cvt_pk_bf16_f32 v166, v140, v141
	v_cvt_pk_bf16_f32 v167, v142, v143
	s_waitcnt vmcnt(7)
	v_and_b32_e32 v55, 0xffff0000, v53
	v_lshlrev_b32_e32 v54, 16, v53
	v_and_b32_e32 v53, 0xffff0000, v52
	v_lshlrev_b32_e32 v52, 16, v52
	v_add_f32_e32 v140, v52, v48
	v_add_f32_e32 v141, v53, v49
	v_add_f32_e32 v142, v54, v50
	v_add_f32_e32 v143, v55, v51
	v_mul_f32_e32 v140, 0.5, v140
	v_mul_f32_e32 v141, 0.5, v141
	v_mul_f32_e32 v142, 0.5, v142
	v_mul_f32_e32 v143, 0.5, v143
	v_sub_f32_e32 v140, v140, v52
	v_sub_f32_e32 v141, v141, v53
	v_sub_f32_e32 v142, v142, v54
	v_sub_f32_e32 v143, v143, v55
	v_cvt_pk_bf16_f32 v168, v140, v141
	v_cvt_pk_bf16_f32 v169, v142, v143
	s_waitcnt vmcnt(6)
	v_and_b32_e32 v59, 0xffff0000, v57
	v_lshlrev_b32_e32 v58, 16, v57
	v_and_b32_e32 v57, 0xffff0000, v56
	v_lshlrev_b32_e32 v56, 16, v56
	v_add_f32_e32 v140, v56, v52
	v_add_f32_e32 v141, v57, v53
	v_add_f32_e32 v142, v58, v54
	v_add_f32_e32 v143, v59, v55
	v_mul_f32_e32 v140, 0.5, v140
	v_mul_f32_e32 v141, 0.5, v141
	v_mul_f32_e32 v142, 0.5, v142
	v_mul_f32_e32 v143, 0.5, v143
	v_sub_f32_e32 v140, v140, v56
	v_sub_f32_e32 v141, v141, v57
	v_sub_f32_e32 v142, v142, v58
	v_sub_f32_e32 v143, v143, v59
	v_cvt_pk_bf16_f32 v170, v140, v141
	v_cvt_pk_bf16_f32 v171, v142, v143
	s_waitcnt vmcnt(5)
	v_and_b32_e32 v63, 0xffff0000, v61
	v_lshlrev_b32_e32 v62, 16, v61
	v_and_b32_e32 v61, 0xffff0000, v60
	v_lshlrev_b32_e32 v60, 16, v60
	v_add_f32_e32 v140, v60, v56
	v_add_f32_e32 v141, v61, v57
	v_add_f32_e32 v142, v62, v58
	v_add_f32_e32 v143, v63, v59
	v_mul_f32_e32 v140, 0.5, v140
	v_mul_f32_e32 v141, 0.5, v141
	v_mul_f32_e32 v142, 0.5, v142
	v_mul_f32_e32 v143, 0.5, v143
	v_sub_f32_e32 v140, v140, v60
	v_sub_f32_e32 v141, v141, v61
	v_sub_f32_e32 v142, v142, v62
	v_sub_f32_e32 v143, v143, v63
	v_cvt_pk_bf16_f32 v172, v140, v141
	v_cvt_pk_bf16_f32 v173, v142, v143
	s_waitcnt vmcnt(4)
	v_and_b32_e32 v67, 0xffff0000, v65
	v_lshlrev_b32_e32 v66, 16, v65
	v_and_b32_e32 v65, 0xffff0000, v64
	v_lshlrev_b32_e32 v64, 16, v64
	v_add_f32_e32 v140, v64, v60
	v_add_f32_e32 v141, v65, v61
	v_add_f32_e32 v142, v66, v62
	v_add_f32_e32 v143, v67, v63
	v_mul_f32_e32 v140, 0.5, v140
	v_mul_f32_e32 v141, 0.5, v141
	v_mul_f32_e32 v142, 0.5, v142
	v_mul_f32_e32 v143, 0.5, v143
	v_sub_f32_e32 v140, v140, v64
	v_sub_f32_e32 v141, v141, v65
	v_sub_f32_e32 v142, v142, v66
	v_sub_f32_e32 v143, v143, v67
	v_cvt_pk_bf16_f32 v174, v140, v141
	v_cvt_pk_bf16_f32 v175, v142, v143
	s_waitcnt vmcnt(3)
	v_and_b32_e32 v71, 0xffff0000, v69
	v_lshlrev_b32_e32 v70, 16, v69
	v_and_b32_e32 v69, 0xffff0000, v68
	v_lshlrev_b32_e32 v68, 16, v68
	v_add_f32_e32 v140, v68, v64
	v_add_f32_e32 v141, v69, v65
	v_add_f32_e32 v142, v70, v66
	v_add_f32_e32 v143, v71, v67
	v_mul_f32_e32 v140, 0.5, v140
	v_mul_f32_e32 v141, 0.5, v141
	v_mul_f32_e32 v142, 0.5, v142
	v_mul_f32_e32 v143, 0.5, v143
	v_sub_f32_e32 v140, v140, v68
	v_sub_f32_e32 v141, v141, v69
	v_sub_f32_e32 v142, v142, v70
	v_sub_f32_e32 v143, v143, v71
	v_cvt_pk_bf16_f32 v176, v140, v141
	v_cvt_pk_bf16_f32 v177, v142, v143
	s_waitcnt vmcnt(2)
	v_and_b32_e32 v75, 0xffff0000, v73
	v_lshlrev_b32_e32 v74, 16, v73
	v_and_b32_e32 v73, 0xffff0000, v72
	v_lshlrev_b32_e32 v72, 16, v72
	v_add_f32_e32 v140, v72, v68
	v_add_f32_e32 v141, v73, v69
	v_add_f32_e32 v142, v74, v70
	v_add_f32_e32 v143, v75, v71
	v_mul_f32_e32 v140, 0.5, v140
	v_mul_f32_e32 v141, 0.5, v141
	v_mul_f32_e32 v142, 0.5, v142
	v_mul_f32_e32 v143, 0.5, v143
	v_sub_f32_e32 v140, v140, v72
	v_sub_f32_e32 v141, v141, v73
	v_sub_f32_e32 v142, v142, v74
	v_sub_f32_e32 v143, v143, v75
	v_cvt_pk_bf16_f32 v178, v140, v141
	v_cvt_pk_bf16_f32 v179, v142, v143
	s_waitcnt vmcnt(1)
	v_and_b32_e32 v79, 0xffff0000, v77
	v_lshlrev_b32_e32 v78, 16, v77
	v_and_b32_e32 v77, 0xffff0000, v76
	v_lshlrev_b32_e32 v76, 16, v76
	v_add_f32_e32 v140, v76, v72
	v_add_f32_e32 v141, v77, v73
	v_add_f32_e32 v142, v78, v74
	v_add_f32_e32 v143, v79, v75
	v_mul_f32_e32 v140, 0.5, v140
	v_mul_f32_e32 v141, 0.5, v141
	v_mul_f32_e32 v142, 0.5, v142
	v_mul_f32_e32 v143, 0.5, v143
	v_sub_f32_e32 v140, v140, v76
	v_sub_f32_e32 v141, v141, v77
	v_sub_f32_e32 v142, v142, v78
	v_sub_f32_e32 v143, v143, v79
	v_cvt_pk_bf16_f32 v180, v140, v141
	v_cvt_pk_bf16_f32 v181, v142, v143
	s_waitcnt vmcnt(0)
; DI float bflo(unsigned u) { return __uint_as_float(u << 16); }
; DI float bfhi(unsigned u) { return __uint_as_float(u & 0xffff0000u); }
; template <int WIN>
; DI void pool_elem(const Params& p, int row, int c) {
;     ...
;     if (t >= WIN - 1) {
;       cnt = (float)WIN;
;       unsigned w[WIN - 1];
; #pragma unroll
;       for (int j = 1; j < WIN; ++j) w[j - 1] = *(const unsigned*)(P2 + (size_t)(row - j) * 2048 + c);
; #pragma unroll
;       for (int j = 1; j < WIN; ++j) { s0 += bflo(w[j - 1]); s1 += bfhi(w[j - 1]); }
;     } else {
;       cnt = (float)(t + 1);
;       for (int j = 1; j <= t; ++j) {
;         unsigned w = *(const unsigned*)(P2 + (size_t)(row - j) * 2048 + c);
;         s0 += bflo(w); s1 += bfhi(w);
;       }
;     }
;     if (t >= 2033) {
;       float2 o = {u0, u1};
;       *(float2*)(p.out + O_POOLP + ((size_t)b * 15 + (t - 2033)) * 1024 + c) = o;
;     }
;     ...
;   *(unsigned*)(p.MIX + (size_t)row * 1024 + c) = pack2(s0 / cnt - u0, s1 / cnt - u1);
	v_and_b32_e32 v83, 0xffff0000, v81
	v_lshlrev_b32_e32 v82, 16, v81
	v_and_b32_e32 v81, 0xffff0000, v80
	v_lshlrev_b32_e32 v80, 16, v80
	v_add_f32_e32 v140, v80, v76
	v_add_f32_e32 v141, v81, v77
	v_add_f32_e32 v142, v82, v78
	v_add_f32_e32 v143, v83, v79
	v_mul_f32_e32 v140, 0.5, v140
	v_mul_f32_e32 v141, 0.5, v141
	v_mul_f32_e32 v142, 0.5, v142
	v_mul_f32_e32 v143, 0.5, v143
	v_sub_f32_e32 v140, v140, v80
	v_sub_f32_e32 v141, v141, v81
	v_sub_f32_e32 v142, v142, v82
	v_sub_f32_e32 v143, v143, v83
	v_cvt_pk_bf16_f32 v182, v140, v141
	v_cvt_pk_bf16_f32 v183, v142, v143
	global_store_dwordx2 v11, v[152:153], s[24:25]
	s_add_u32 s24, s24, 0x800
	s_addc_u32 s25, s25, 0
	global_store_dwordx2 v11, v[154:155], s[24:25]
	s_add_u32 s24, s24, 0x800
	s_addc_u32 s25, s25, 0
	global_store_dwordx2 v11, v[156:157], s[24:25]
	s_add_u32 s24, s24, 0x800
	s_addc_u32 s25, s25, 0
	global_store_dwordx2 v11, v[158:159], s[24:25]
	s_add_u32 s24, s24, 0x800
	s_addc_u32 s25, s25, 0
	global_store_dwordx2 v11, v[160:161], s[24:25]
	s_add_u32 s24, s24, 0x800
	s_addc_u32 s25, s25, 0
	global_store_dwordx2 v11, v[162:163], s[24:25]
	s_add_u32 s24, s24, 0x800
	s_addc_u32 s25, s25, 0
	global_store_dwordx2 v11, v[164:165], s[24:25]
	s_add_u32 s24, s24, 0x800
	s_addc_u32 s25, s25, 0
	global_store_dwordx2 v11, v[166:167], s[24:25]
	s_add_u32 s24, s24, 0x800
	s_addc_u32 s25, s25, 0
	global_store_dwordx2 v11, v[168:169], s[24:25]
	s_add_u32 s24, s24, 0x800
	s_addc_u32 s25, s25, 0
	global_store_dwordx2 v11, v[170:171], s[24:25]
	s_add_u32 s24, s24, 0x800
	s_addc_u32 s25, s25, 0
	global_store_dwordx2 v11, v[172:173], s[24:25]
	s_add_u32 s24, s24, 0x800
	s_addc_u32 s25, s25, 0
	global_store_dwordx2 v11, v[174:175], s[24:25]
	s_add_u32 s24, s24, 0x800
	s_addc_u32 s25, s25, 0
	global_store_dwordx2 v11, v[176:177], s[24:25]
	s_add_u32 s24, s24, 0x800
	s_addc_u32 s25, s25, 0
	global_store_dwordx2 v11, v[178:179], s[24:25]
	s_add_u32 s24, s24, 0x800
	s_addc_u32 s25, s25, 0
	global_store_dwordx2 v11, v[180:181], s[24:25]
	s_add_u32 s24, s24, 0x800
	s_addc_u32 s25, s25, 0
	global_store_dwordx2 v11, v[182:183], s[24:25]
	s_add_u32 s24, s24, 0x800
	s_addc_u32 s25, s25, 0
	s_cmp_eq_u32 s18, 127
	s_cbranch_scc0 .Lp13f_next
	s_mul_i32 s26, s17, 61440
	s_add_u32 s26, s26, 0x431c000
	s_add_u32 s22, s12, s26
	s_addc_u32 s23, s13, 0
	global_store_dwordx4 v12, v[24:27], s[22:23]
	s_add_u32 s22, s22, 0x1000
	s_addc_u32 s23, s23, 0
	global_store_dwordx4 v12, v[28:31], s[22:23]
	s_add_u32 s22, s22, 0x1000
	s_addc_u32 s23, s23, 0
	global_store_dwordx4 v12, v[32:35], s[22:23]
	s_add_u32 s22, s22, 0x1000
	s_addc_u32 s23, s23, 0
	global_store_dwordx4 v12, v[36:39], s[22:23]
	s_add_u32 s22, s22, 0x1000
	s_addc_u32 s23, s23, 0
	global_store_dwordx4 v12, v[40:43], s[22:23]
	s_add_u32 s22, s22, 0x1000
	s_addc_u32 s23, s23, 0
	global_store_dwordx4 v12, v[44:47], s[22:23]
	s_add_u32 s22, s22, 0x1000
	s_addc_u32 s23, s23, 0
	global_store_dwordx4 v12, v[48:51], s[22:23]
	s_add_u32 s22, s22, 0x1000
	s_addc_u32 s23, s23, 0
	global_store_dwordx4 v12, v[52:55], s[22:23]
	s_add_u32 s22, s22, 0x1000
	s_addc_u32 s23, s23, 0
	global_store_dwordx4 v12, v[56:59], s[22:23]
	s_add_u32 s22, s22, 0x1000
	s_addc_u32 s23, s23, 0
	global_store_dwordx4 v12, v[60:63], s[22:23]
	s_add_u32 s22, s22, 0x1000
	s_addc_u32 s23, s23, 0
	global_store_dwordx4 v12, v[64:67], s[22:23]
	s_add_u32 s22, s22, 0x1000
	s_addc_u32 s23, s23, 0
	global_store_dwordx4 v12, v[68:71], s[22:23]
	s_add_u32 s22, s22, 0x1000
	s_addc_u32 s23, s23, 0
	global_store_dwordx4 v12, v[72:75], s[22:23]
	s_add_u32 s22, s22, 0x1000
	s_addc_u32 s23, s23, 0
	global_store_dwordx4 v12, v[76:79], s[22:23]
	s_add_u32 s22, s22, 0x1000
	s_addc_u32 s23, s23, 0
	global_store_dwordx4 v12, v[80:83], s[22:23]
	s_add_u32 s22, s22, 0x1000
	s_addc_u32 s23, s23, 0
	s_branch .Lp13f_next
.Lp13f_w1:
	s_sub_u32 s26, s20, 3
	s_lshl_b32 s27, s26, 12
	s_lshr_b32 s28, s26, 20
	s_add_u32 s22, s8, s27
	s_addc_u32 s23, s9, s28
	global_load_dwordx2 v[16:17], v11, s[22:23]
	s_add_u32 s22, s22, 0x1000
	s_addc_u32 s23, s23, 0
	global_load_dwordx2 v[20:21], v11, s[22:23]
	s_add_u32 s22, s22, 0x1000
	s_addc_u32 s23, s23, 0
	global_load_dwordx2 v[24:25], v11, s[22:23]
	s_add_u32 s22, s22, 0x1000
	s_addc_u32 s23, s23, 0
	global_load_dwordx2 v[28:29], v11, s[22:23]
	s_add_u32 s22, s22, 0x1000
	s_addc_u32 s23, s23, 0
	global_load_dwordx2 v[32:33], v11, s[22:23]
	s_add_u32 s22, s22, 0x1000
	s_addc_u32 s23, s23, 0
	global_load_dwordx2 v[36:37], v11, s[22:23]
	s_add_u32 s22, s22, 0x1000
	s_addc_u32 s23, s23, 0
	global_load_dwordx2 v[40:41], v11, s[22:23]
	s_add_u32 s22, s22, 0x1000
	s_addc_u32 s23, s23, 0
	global_load_dwordx2 v[44:45], v11, s[22:23]
	s_add_u32 s22, s22, 0x1000
	s_addc_u32 s23, s23, 0
	global_load_dwordx2 v[48:49], v11, s[22:23]
	s_add_u32 s22, s22, 0x1000
	s_addc_u32 s23, s23, 0
	global_load_dwordx2 v[52:53], v11, s[22:23]
	s_add_u32 s22, s22, 0x1000
	s_addc_u32 s23, s23, 0
	global_load_dwordx2 v[56:57], v11, s[22:23]
	s_add_u32 s22, s22, 0x1000
	s_addc_u32 s23, s23, 0
	global_load_dwordx2 v[60:61], v11, s[22:23]
	s_add_u32 s22, s22, 0x1000
	s_addc_u32 s23, s23, 0
	global_load_dwordx2 v[64:65], v11, s[22:23]
	s_add_u32 s22, s22, 0x1000
	s_addc_u32 s23, s23, 0
	global_load_dwordx2 v[68:69], v11, s[22:23]
	s_add_u32 s22, s22, 0x1000
	s_addc_u32 s23, s23, 0
	global_load_dwordx2 v[72:73], v11, s[22:23]
	s_add_u32 s22, s22, 0x1000
	s_addc_u32 s23, s23, 0
	global_load_dwordx2 v[76:77], v11, s[22:23]
	s_add_u32 s22, s22, 0x1000
	s_addc_u32 s23, s23, 0
	global_load_dwordx2 v[80:81], v11, s[22:23]
	s_add_u32 s22, s22, 0x1000
	s_addc_u32 s23, s23, 0
	global_load_dwordx2 v[84:85], v11, s[22:23]
	s_add_u32 s22, s22, 0x1000
	s_addc_u32 s23, s23, 0
	global_load_dwordx2 v[88:89], v11, s[22:23]
	s_add_u32 s22, s22, 0x1000
	s_addc_u32 s23, s23, 0
	s_waitcnt vmcnt(15)
; DI float bflo(unsigned u) { return __uint_as_float(u << 16); }
; DI float bfhi(unsigned u) { return __uint_as_float(u & 0xffff0000u); }
; template <int WIN>
; DI void pool_elem(const Params& p, int row, int c) {
;     ...
;     if (t >= WIN - 1) {
;       cnt = (float)WIN;
;       unsigned w[WIN - 1];
; #pragma unroll
;       for (int j = 1; j < WIN; ++j) w[j - 1] = *(const unsigned*)(P2 + (size_t)(row - j) * 2048 + c);
; #pragma unroll
;       for (int j = 1; j < WIN; ++j) { s0 += bflo(w[j - 1]); s1 += bfhi(w[j - 1]); }
;     ...
;   *(unsigned*)(p.MIX + (size_t)row * 1024 + c) = pack2(s0 / cnt - u0, s1 / cnt - u1);
	v_and_b32_e32 v19, 0xffff0000, v17
	v_lshlrev_b32_e32 v18, 16, v17
	v_and_b32_e32 v17, 0xffff0000, v16
	v_lshlrev_b32_e32 v16, 16, v16
	v_and_b32_e32 v23, 0xffff0000, v21
	v_lshlrev_b32_e32 v22, 16, v21
	v_and_b32_e32 v21, 0xffff0000, v20
	v_lshlrev_b32_e32 v20, 16, v20
	v_and_b32_e32 v27, 0xffff0000, v25
	v_lshlrev_b32_e32 v26, 16, v25
	v_and_b32_e32 v25, 0xffff0000, v24
	v_lshlrev_b32_e32 v24, 16, v24
	v_and_b32_e32 v31, 0xffff0000, v29
	v_lshlrev_b32_e32 v30, 16, v29
	v_and_b32_e32 v29, 0xffff0000, v28
	v_lshlrev_b32_e32 v28, 16, v28
	v_add_f32_e32 v140, v28, v24
	v_add_f32_e32 v141, v29, v25
	v_add_f32_e32 v142, v30, v26
	v_add_f32_e32 v143, v31, v27
	v_add_f32_e32 v140, v140, v20
	v_add_f32_e32 v141, v141, v21
	v_add_f32_e32 v142, v142, v22
	v_add_f32_e32 v143, v143, v23
	v_add_f32_e32 v140, v140, v16
	v_add_f32_e32 v141, v141, v17
	v_add_f32_e32 v142, v142, v18
	v_add_f32_e32 v143, v143, v19
	v_mul_f32_e32 v140, 0x3e800000, v140
	v_mul_f32_e32 v141, 0x3e800000, v141
	v_mul_f32_e32 v142, 0x3e800000, v142
	v_mul_f32_e32 v143, 0x3e800000, v143
	v_sub_f32_e32 v140, v140, v28
	v_sub_f32_e32 v141, v141, v29
	v_sub_f32_e32 v142, v142, v30
	v_sub_f32_e32 v143, v143, v31
	v_cvt_pk_bf16_f32 v152, v140, v141
	v_cvt_pk_bf16_f32 v153, v142, v143
	s_waitcnt vmcnt(14)
	v_and_b32_e32 v35, 0xffff0000, v33
	v_lshlrev_b32_e32 v34, 16, v33
	v_and_b32_e32 v33, 0xffff0000, v32
	v_lshlrev_b32_e32 v32, 16, v32
	v_add_f32_e32 v140, v32, v28
	v_add_f32_e32 v141, v33, v29
	v_add_f32_e32 v142, v34, v30
	v_add_f32_e32 v143, v35, v31
	v_add_f32_e32 v140, v140, v24
	v_add_f32_e32 v141, v141, v25
	v_add_f32_e32 v142, v142, v26
	v_add_f32_e32 v143, v143, v27
	v_add_f32_e32 v140, v140, v20
	v_add_f32_e32 v141, v141, v21
	v_add_f32_e32 v142, v142, v22
	v_add_f32_e32 v143, v143, v23
	v_mul_f32_e32 v140, 0x3e800000, v140
	v_mul_f32_e32 v141, 0x3e800000, v141
	v_mul_f32_e32 v142, 0x3e800000, v142
	v_mul_f32_e32 v143, 0x3e800000, v143
	v_sub_f32_e32 v140, v140, v32
	v_sub_f32_e32 v141, v141, v33
	v_sub_f32_e32 v142, v142, v34
	v_sub_f32_e32 v143, v143, v35
	v_cvt_pk_bf16_f32 v154, v140, v141
	v_cvt_pk_bf16_f32 v155, v142, v143
	s_waitcnt vmcnt(13)
	v_and_b32_e32 v39, 0xffff0000, v37
	v_lshlrev_b32_e32 v38, 16, v37
	v_and_b32_e32 v37, 0xffff0000, v36
	v_lshlrev_b32_e32 v36, 16, v36
	v_add_f32_e32 v140, v36, v32
	v_add_f32_e32 v141, v37, v33
	v_add_f32_e32 v142, v38, v34
	v_add_f32_e32 v143, v39, v35
	v_add_f32_e32 v140, v140, v28
	v_add_f32_e32 v141, v141, v29
	v_add_f32_e32 v142, v142, v30
	v_add_f32_e32 v143, v143, v31
	v_add_f32_e32 v140, v140, v24
	v_add_f32_e32 v141, v141, v25
	v_add_f32_e32 v142, v142, v26
	v_add_f32_e32 v143, v143, v27
	v_mul_f32_e32 v140, 0x3e800000, v140
	v_mul_f32_e32 v141, 0x3e800000, v141
	v_mul_f32_e32 v142, 0x3e800000, v142
	v_mul_f32_e32 v143, 0x3e800000, v143
	v_sub_f32_e32 v140, v140, v36
	v_sub_f32_e32 v141, v141, v37
	v_sub_f32_e32 v142, v142, v38
	v_sub_f32_e32 v143, v143, v39
	v_cvt_pk_bf16_f32 v156, v140, v141
	v_cvt_pk_bf16_f32 v157, v142, v143
	s_waitcnt vmcnt(12)
	v_and_b32_e32 v43, 0xffff0000, v41
	v_lshlrev_b32_e32 v42, 16, v41
	v_and_b32_e32 v41, 0xffff0000, v40
	v_lshlrev_b32_e32 v40, 16, v40
	v_add_f32_e32 v140, v40, v36
	v_add_f32_e32 v141, v41, v37
	v_add_f32_e32 v142, v42, v38
	v_add_f32_e32 v143, v43, v39
	v_add_f32_e32 v140, v140, v32
	v_add_f32_e32 v141, v141, v33
	v_add_f32_e32 v142, v142, v34
	v_add_f32_e32 v143, v143, v35
	v_add_f32_e32 v140, v140, v28
	v_add_f32_e32 v141, v141, v29
	v_add_f32_e32 v142, v142, v30
	v_add_f32_e32 v143, v143, v31
	v_mul_f32_e32 v140, 0x3e800000, v140
	v_mul_f32_e32 v141, 0x3e800000, v141
	v_mul_f32_e32 v142, 0x3e800000, v142
	v_mul_f32_e32 v143, 0x3e800000, v143
	v_sub_f32_e32 v140, v140, v40
	v_sub_f32_e32 v141, v141, v41
	v_sub_f32_e32 v142, v142, v42
	v_sub_f32_e32 v143, v143, v43
	v_cvt_pk_bf16_f32 v158, v140, v141
	v_cvt_pk_bf16_f32 v159, v142, v143
	s_waitcnt vmcnt(11)
	v_and_b32_e32 v47, 0xffff0000, v45
	v_lshlrev_b32_e32 v46, 16, v45
	v_and_b32_e32 v45, 0xffff0000, v44
	v_lshlrev_b32_e32 v44, 16, v44
	v_add_f32_e32 v140, v44, v40
	v_add_f32_e32 v141, v45, v41
	v_add_f32_e32 v142, v46, v42
	v_add_f32_e32 v143, v47, v43
	v_add_f32_e32 v140, v140, v36
	v_add_f32_e32 v141, v141, v37
	v_add_f32_e32 v142, v142, v38
	v_add_f32_e32 v143, v143, v39
	v_add_f32_e32 v140, v140, v32
	v_add_f32_e32 v141, v141, v33
	v_add_f32_e32 v142, v142, v34
	v_add_f32_e32 v143, v143, v35
	v_mul_f32_e32 v140, 0x3e800000, v140
	v_mul_f32_e32 v141, 0x3e800000, v141
	v_mul_f32_e32 v142, 0x3e800000, v142
	v_mul_f32_e32 v143, 0x3e800000, v143
	v_sub_f32_e32 v140, v140, v44
	v_sub_f32_e32 v141, v141, v45
	v_sub_f32_e32 v142, v142, v46
	v_sub_f32_e32 v143, v143, v47
	v_cvt_pk_bf16_f32 v160, v140, v141
	v_cvt_pk_bf16_f32 v161, v142, v143
	s_waitcnt vmcnt(10)
	v_and_b32_e32 v51, 0xffff0000, v49
	v_lshlrev_b32_e32 v50, 16, v49
	v_and_b32_e32 v49, 0xffff0000, v48
	v_lshlrev_b32_e32 v48, 16, v48
	v_add_f32_e32 v140, v48, v44
	v_add_f32_e32 v141, v49, v45
	v_add_f32_e32 v142, v50, v46
	v_add_f32_e32 v143, v51, v47
	v_add_f32_e32 v140, v140, v40
	v_add_f32_e32 v141, v141, v41
	v_add_f32_e32 v142, v142, v42
	v_add_f32_e32 v143, v143, v43
	v_add_f32_e32 v140, v140, v36
	v_add_f32_e32 v141, v141, v37
	v_add_f32_e32 v142, v142, v38
	v_add_f32_e32 v143, v143, v39
	v_mul_f32_e32 v140, 0x3e800000, v140
	v_mul_f32_e32 v141, 0x3e800000, v141
	v_mul_f32_e32 v142, 0x3e800000, v142
	v_mul_f32_e32 v143, 0x3e800000, v143
	v_sub_f32_e32 v140, v140, v48
	v_sub_f32_e32 v141, v141, v49
	v_sub_f32_e32 v142, v142, v50
	v_sub_f32_e32 v143, v143, v51
	v_cvt_pk_bf16_f32 v162, v140, v141
	v_cvt_pk_bf16_f32 v163, v142, v143
	s_waitcnt vmcnt(9)
; DI float bflo(unsigned u) { return __uint_as_float(u << 16); }
; DI float bfhi(unsigned u) { return __uint_as_float(u & 0xffff0000u); }
; template <int WIN>
; DI void pool_elem(const Params& p, int row, int c) {
;     ...
;     if (t >= WIN - 1) {
;       cnt = (float)WIN;
;       unsigned w[WIN - 1];
; #pragma unroll
;       for (int j = 1; j < WIN; ++j) w[j - 1] = *(const unsigned*)(P2 + (size_t)(row - j) * 2048 + c);
; #pragma unroll
;       for (int j = 1; j < WIN; ++j) { s0 += bflo(w[j - 1]); s1 += bfhi(w[j - 1]); }
;     ...
;   *(unsigned*)(p.MIX + (size_t)row * 1024 + c) = pack2(s0 / cnt - u0, s1 / cnt - u1);
	v_and_b32_e32 v55, 0xffff0000, v53
	v_lshlrev_b32_e32 v54, 16, v53
	v_and_b32_e32 v53, 0xffff0000, v52
	v_lshlrev_b32_e32 v52, 16, v52
	v_add_f32_e32 v140, v52, v48
	v_add_f32_e32 v141, v53, v49
	v_add_f32_e32 v142, v54, v50
	v_add_f32_e32 v143, v55, v51
	v_add_f32_e32 v140, v140, v44
	v_add_f32_e32 v141, v141, v45
	v_add_f32_e32 v142, v142, v46
	v_add_f32_e32 v143, v143, v47
	v_add_f32_e32 v140, v140, v40
	v_add_f32_e32 v141, v141, v41
	v_add_f32_e32 v142, v142, v42
	v_add_f32_e32 v143, v143, v43
	v_mul_f32_e32 v140, 0x3e800000, v140
	v_mul_f32_e32 v141, 0x3e800000, v141
	v_mul_f32_e32 v142, 0x3e800000, v142
	v_mul_f32_e32 v143, 0x3e800000, v143
	v_sub_f32_e32 v140, v140, v52
	v_sub_f32_e32 v141, v141, v53
	v_sub_f32_e32 v142, v142, v54
	v_sub_f32_e32 v143, v143, v55
	v_cvt_pk_bf16_f32 v164, v140, v141
	v_cvt_pk_bf16_f32 v165, v142, v143
	s_waitcnt vmcnt(8)
	v_and_b32_e32 v59, 0xffff0000, v57
	v_lshlrev_b32_e32 v58, 16, v57
	v_and_b32_e32 v57, 0xffff0000, v56
	v_lshlrev_b32_e32 v56, 16, v56
	v_add_f32_e32 v140, v56, v52
	v_add_f32_e32 v141, v57, v53
	v_add_f32_e32 v142, v58, v54
	v_add_f32_e32 v143, v59, v55
	v_add_f32_e32 v140, v140, v48
	v_add_f32_e32 v141, v141, v49
	v_add_f32_e32 v142, v142, v50
	v_add_f32_e32 v143, v143, v51
	v_add_f32_e32 v140, v140, v44
	v_add_f32_e32 v141, v141, v45
	v_add_f32_e32 v142, v142, v46
	v_add_f32_e32 v143, v143, v47
	v_mul_f32_e32 v140, 0x3e800000, v140
	v_mul_f32_e32 v141, 0x3e800000, v141
	v_mul_f32_e32 v142, 0x3e800000, v142
	v_mul_f32_e32 v143, 0x3e800000, v143
	v_sub_f32_e32 v140, v140, v56
	v_sub_f32_e32 v141, v141, v57
	v_sub_f32_e32 v142, v142, v58
	v_sub_f32_e32 v143, v143, v59
	v_cvt_pk_bf16_f32 v166, v140, v141
	v_cvt_pk_bf16_f32 v167, v142, v143
	s_waitcnt vmcnt(7)
	v_and_b32_e32 v63, 0xffff0000, v61
	v_lshlrev_b32_e32 v62, 16, v61
	v_and_b32_e32 v61, 0xffff0000, v60
	v_lshlrev_b32_e32 v60, 16, v60
	v_add_f32_e32 v140, v60, v56
	v_add_f32_e32 v141, v61, v57
	v_add_f32_e32 v142, v62, v58
	v_add_f32_e32 v143, v63, v59
	v_add_f32_e32 v140, v140, v52
	v_add_f32_e32 v141, v141, v53
	v_add_f32_e32 v142, v142, v54
	v_add_f32_e32 v143, v143, v55
	v_add_f32_e32 v140, v140, v48
	v_add_f32_e32 v141, v141, v49
	v_add_f32_e32 v142, v142, v50
	v_add_f32_e32 v143, v143, v51
	v_mul_f32_e32 v140, 0x3e800000, v140
	v_mul_f32_e32 v141, 0x3e800000, v141
	v_mul_f32_e32 v142, 0x3e800000, v142
	v_mul_f32_e32 v143, 0x3e800000, v143
	v_sub_f32_e32 v140, v140, v60
	v_sub_f32_e32 v141, v141, v61
	v_sub_f32_e32 v142, v142, v62
	v_sub_f32_e32 v143, v143, v63
	v_cvt_pk_bf16_f32 v168, v140, v141
	v_cvt_pk_bf16_f32 v169, v142, v143
	s_waitcnt vmcnt(6)
	v_and_b32_e32 v67, 0xffff0000, v65
	v_lshlrev_b32_e32 v66, 16, v65
	v_and_b32_e32 v65, 0xffff0000, v64
	v_lshlrev_b32_e32 v64, 16, v64
	v_add_f32_e32 v140, v64, v60
	v_add_f32_e32 v141, v65, v61
	v_add_f32_e32 v142, v66, v62
	v_add_f32_e32 v143, v67, v63
	v_add_f32_e32 v140, v140, v56
	v_add_f32_e32 v141, v141, v57
	v_add_f32_e32 v142, v142, v58
	v_add_f32_e32 v143, v143, v59
	v_add_f32_e32 v140, v140, v52
	v_add_f32_e32 v141, v141, v53
	v_add_f32_e32 v142, v142, v54
	v_add_f32_e32 v143, v143, v55
	v_mul_f32_e32 v140, 0x3e800000, v140
	v_mul_f32_e32 v141, 0x3e800000, v141
	v_mul_f32_e32 v142, 0x3e800000, v142
	v_mul_f32_e32 v143, 0x3e800000, v143
	v_sub_f32_e32 v140, v140, v64
	v_sub_f32_e32 v141, v141, v65
	v_sub_f32_e32 v142, v142, v66
	v_sub_f32_e32 v143, v143, v67
	v_cvt_pk_bf16_f32 v170, v140, v141
	v_cvt_pk_bf16_f32 v171, v142, v143
	s_waitcnt vmcnt(5)
	v_and_b32_e32 v71, 0xffff0000, v69
	v_lshlrev_b32_e32 v70, 16, v69
	v_and_b32_e32 v69, 0xffff0000, v68
	v_lshlrev_b32_e32 v68, 16, v68
	v_add_f32_e32 v140, v68, v64
	v_add_f32_e32 v141, v69, v65
	v_add_f32_e32 v142, v70, v66
	v_add_f32_e32 v143, v71, v67
	v_add_f32_e32 v140, v140, v60
	v_add_f32_e32 v141, v141, v61
	v_add_f32_e32 v142, v142, v62
	v_add_f32_e32 v143, v143, v63
	v_add_f32_e32 v140, v140, v56
	v_add_f32_e32 v141, v141, v57
	v_add_f32_e32 v142, v142, v58
	v_add_f32_e32 v143, v143, v59
	v_mul_f32_e32 v140, 0x3e800000, v140
	v_mul_f32_e32 v141, 0x3e800000, v141
	v_mul_f32_e32 v142, 0x3e800000, v142
	v_mul_f32_e32 v143, 0x3e800000, v143
	v_sub_f32_e32 v140, v140, v68
	v_sub_f32_e32 v141, v141, v69
	v_sub_f32_e32 v142, v142, v70
	v_sub_f32_e32 v143, v143, v71
	v_cvt_pk_bf16_f32 v172, v140, v141
	v_cvt_pk_bf16_f32 v173, v142, v143
	s_waitcnt vmcnt(4)
	v_and_b32_e32 v75, 0xffff0000, v73
	v_lshlrev_b32_e32 v74, 16, v73
	v_and_b32_e32 v73, 0xffff0000, v72
	v_lshlrev_b32_e32 v72, 16, v72
	v_add_f32_e32 v140, v72, v68
	v_add_f32_e32 v141, v73, v69
	v_add_f32_e32 v142, v74, v70
	v_add_f32_e32 v143, v75, v71
	v_add_f32_e32 v140, v140, v64
	v_add_f32_e32 v141, v141, v65
	v_add_f32_e32 v142, v142, v66
	v_add_f32_e32 v143, v143, v67
	v_add_f32_e32 v140, v140, v60
	v_add_f32_e32 v141, v141, v61
	v_add_f32_e32 v142, v142, v62
	v_add_f32_e32 v143, v143, v63
	v_mul_f32_e32 v140, 0x3e800000, v140
	v_mul_f32_e32 v141, 0x3e800000, v141
	v_mul_f32_e32 v142, 0x3e800000, v142
	v_mul_f32_e32 v143, 0x3e800000, v143
	v_sub_f32_e32 v140, v140, v72
	v_sub_f32_e32 v141, v141, v73
	v_sub_f32_e32 v142, v142, v74
	v_sub_f32_e32 v143, v143, v75
	v_cvt_pk_bf16_f32 v174, v140, v141
	v_cvt_pk_bf16_f32 v175, v142, v143
	s_waitcnt vmcnt(3)
; DI float bflo(unsigned u) { return __uint_as_float(u << 16); }
; DI float bfhi(unsigned u) { return __uint_as_float(u & 0xffff0000u); }
; template <int WIN>
; DI void pool_elem(const Params& p, int row, int c) {
;     ...
;     if (t >= WIN - 1) {
;       cnt = (float)WIN;
;       unsigned w[WIN - 1];
; #pragma unroll
;       for (int j = 1; j < WIN; ++j) w[j - 1] = *(const unsigned*)(P2 + (size_t)(row - j) * 2048 + c);
; #pragma unroll
;       for (int j = 1; j < WIN; ++j) { s0 += bflo(w[j - 1]); s1 += bfhi(w[j - 1]); }
;     } else {
;       cnt = (float)(t + 1);
;       for (int j = 1; j <= t; ++j) {
;         unsigned w = *(const unsigned*)(P2 + (size_t)(row - j) * 2048 + c);
;         s0 += bflo(w); s1 += bfhi(w);
;       }
;     }
;     if (t >= 2033) {
;       float2 o = {u0, u1};
;       *(float2*)(p.out + O_POOLP + ((size_t)b * 15 + (t - 2033)) * 1024 + c) = o;
;     }
;     ...
;   *(unsigned*)(p.MIX + (size_t)row * 1024 + c) = pack2(s0 / cnt - u0, s1 / cnt - u1);
	v_and_b32_e32 v79, 0xffff0000, v77
	v_lshlrev_b32_e32 v78, 16, v77
	v_and_b32_e32 v77, 0xffff0000, v76
	v_lshlrev_b32_e32 v76, 16, v76
	v_add_f32_e32 v140, v76, v72
	v_add_f32_e32 v141, v77, v73
	v_add_f32_e32 v142, v78, v74
	v_add_f32_e32 v143, v79, v75
	v_add_f32_e32 v140, v140, v68
	v_add_f32_e32 v141, v141, v69
	v_add_f32_e32 v142, v142, v70
	v_add_f32_e32 v143, v143, v71
	v_add_f32_e32 v140, v140, v64
	v_add_f32_e32 v141, v141, v65
	v_add_f32_e32 v142, v142, v66
	v_add_f32_e32 v143, v143, v67
	v_mul_f32_e32 v140, 0x3e800000, v140
	v_mul_f32_e32 v141, 0x3e800000, v141
	v_mul_f32_e32 v142, 0x3e800000, v142
	v_mul_f32_e32 v143, 0x3e800000, v143
	v_sub_f32_e32 v140, v140, v76
	v_sub_f32_e32 v141, v141, v77
	v_sub_f32_e32 v142, v142, v78
	v_sub_f32_e32 v143, v143, v79
	v_cvt_pk_bf16_f32 v176, v140, v141
	v_cvt_pk_bf16_f32 v177, v142, v143
	s_waitcnt vmcnt(2)
	v_and_b32_e32 v83, 0xffff0000, v81
	v_lshlrev_b32_e32 v82, 16, v81
	v_and_b32_e32 v81, 0xffff0000, v80
	v_lshlrev_b32_e32 v80, 16, v80
	v_add_f32_e32 v140, v80, v76
	v_add_f32_e32 v141, v81, v77
	v_add_f32_e32 v142, v82, v78
	v_add_f32_e32 v143, v83, v79
	v_add_f32_e32 v140, v140, v72
	v_add_f32_e32 v141, v141, v73
	v_add_f32_e32 v142, v142, v74
	v_add_f32_e32 v143, v143, v75
	v_add_f32_e32 v140, v140, v68
	v_add_f32_e32 v141, v141, v69
	v_add_f32_e32 v142, v142, v70
	v_add_f32_e32 v143, v143, v71
	v_mul_f32_e32 v140, 0x3e800000, v140
	v_mul_f32_e32 v141, 0x3e800000, v141
	v_mul_f32_e32 v142, 0x3e800000, v142
	v_mul_f32_e32 v143, 0x3e800000, v143
	v_sub_f32_e32 v140, v140, v80
	v_sub_f32_e32 v141, v141, v81
	v_sub_f32_e32 v142, v142, v82
	v_sub_f32_e32 v143, v143, v83
	v_cvt_pk_bf16_f32 v178, v140, v141
	v_cvt_pk_bf16_f32 v179, v142, v143
	s_waitcnt vmcnt(1)
	v_and_b32_e32 v87, 0xffff0000, v85
	v_lshlrev_b32_e32 v86, 16, v85
	v_and_b32_e32 v85, 0xffff0000, v84
	v_lshlrev_b32_e32 v84, 16, v84
	v_add_f32_e32 v140, v84, v80
	v_add_f32_e32 v141, v85, v81
	v_add_f32_e32 v142, v86, v82
	v_add_f32_e32 v143, v87, v83
	v_add_f32_e32 v140, v140, v76
	v_add_f32_e32 v141, v141, v77
	v_add_f32_e32 v142, v142, v78
	v_add_f32_e32 v143, v143, v79
	v_add_f32_e32 v140, v140, v72
	v_add_f32_e32 v141, v141, v73
	v_add_f32_e32 v142, v142, v74
	v_add_f32_e32 v143, v143, v75
	v_mul_f32_e32 v140, 0x3e800000, v140
	v_mul_f32_e32 v141, 0x3e800000, v141
	v_mul_f32_e32 v142, 0x3e800000, v142
	v_mul_f32_e32 v143, 0x3e800000, v143
	v_sub_f32_e32 v140, v140, v84
	v_sub_f32_e32 v141, v141, v85
	v_sub_f32_e32 v142, v142, v86
	v_sub_f32_e32 v143, v143, v87
	v_cvt_pk_bf16_f32 v180, v140, v141
	v_cvt_pk_bf16_f32 v181, v142, v143
	s_waitcnt vmcnt(0)
	v_and_b32_e32 v91, 0xffff0000, v89
	v_lshlrev_b32_e32 v90, 16, v89
	v_and_b32_e32 v89, 0xffff0000, v88
	v_lshlrev_b32_e32 v88, 16, v88
	v_add_f32_e32 v140, v88, v84
	v_add_f32_e32 v141, v89, v85
	v_add_f32_e32 v142, v90, v86
	v_add_f32_e32 v143, v91, v87
	v_add_f32_e32 v140, v140, v80
	v_add_f32_e32 v141, v141, v81
	v_add_f32_e32 v142, v142, v82
	v_add_f32_e32 v143, v143, v83
	v_add_f32_e32 v140, v140, v76
	v_add_f32_e32 v141, v141, v77
	v_add_f32_e32 v142, v142, v78
	v_add_f32_e32 v143, v143, v79
	v_mul_f32_e32 v140, 0x3e800000, v140
	v_mul_f32_e32 v141, 0x3e800000, v141
	v_mul_f32_e32 v142, 0x3e800000, v142
	v_mul_f32_e32 v143, 0x3e800000, v143
	v_sub_f32_e32 v140, v140, v88
	v_sub_f32_e32 v141, v141, v89
	v_sub_f32_e32 v142, v142, v90
	v_sub_f32_e32 v143, v143, v91
	v_cvt_pk_bf16_f32 v182, v140, v141
	v_cvt_pk_bf16_f32 v183, v142, v143
	global_store_dwordx2 v11, v[152:153], s[24:25]
	s_add_u32 s24, s24, 0x800
	s_addc_u32 s25, s25, 0
	global_store_dwordx2 v11, v[154:155], s[24:25]
	s_add_u32 s24, s24, 0x800
	s_addc_u32 s25, s25, 0
	global_store_dwordx2 v11, v[156:157], s[24:25]
	s_add_u32 s24, s24, 0x800
	s_addc_u32 s25, s25, 0
	global_store_dwordx2 v11, v[158:159], s[24:25]
	s_add_u32 s24, s24, 0x800
	s_addc_u32 s25, s25, 0
	global_store_dwordx2 v11, v[160:161], s[24:25]
	s_add_u32 s24, s24, 0x800
	s_addc_u32 s25, s25, 0
	global_store_dwordx2 v11, v[162:163], s[24:25]
	s_add_u32 s24, s24, 0x800
	s_addc_u32 s25, s25, 0
	global_store_dwordx2 v11, v[164:165], s[24:25]
	s_add_u32 s24, s24, 0x800
	s_addc_u32 s25, s25, 0
	global_store_dwordx2 v11, v[166:167], s[24:25]
	s_add_u32 s24, s24, 0x800
	s_addc_u32 s25, s25, 0
	global_store_dwordx2 v11, v[168:169], s[24:25]
	s_add_u32 s24, s24, 0x800
	s_addc_u32 s25, s25, 0
	global_store_dwordx2 v11, v[170:171], s[24:25]
	s_add_u32 s24, s24, 0x800
	s_addc_u32 s25, s25, 0
	global_store_dwordx2 v11, v[172:173], s[24:25]
	s_add_u32 s24, s24, 0x800
	s_addc_u32 s25, s25, 0
	global_store_dwordx2 v11, v[174:175], s[24:25]
	s_add_u32 s24, s24, 0x800
	s_addc_u32 s25, s25, 0
	global_store_dwordx2 v11, v[176:177], s[24:25]
	s_add_u32 s24, s24, 0x800
	s_addc_u32 s25, s25, 0
	global_store_dwordx2 v11, v[178:179], s[24:25]
	s_add_u32 s24, s24, 0x800
	s_addc_u32 s25, s25, 0
	global_store_dwordx2 v11, v[180:181], s[24:25]
	s_add_u32 s24, s24, 0x800
	s_addc_u32 s25, s25, 0
	global_store_dwordx2 v11, v[182:183], s[24:25]
	s_add_u32 s24, s24, 0x800
	s_addc_u32 s25, s25, 0
	s_cmp_eq_u32 s18, 127
	s_cbranch_scc0 .Lp13f_next
	s_mul_i32 s26, s17, 61440
	s_add_u32 s26, s26, 0x431c000
	s_add_u32 s22, s12, s26
	s_addc_u32 s23, s13, 0
	global_store_dwordx4 v12, v[32:35], s[22:23]
	s_add_u32 s22, s22, 0x1000
	s_addc_u32 s23, s23, 0
	global_store_dwordx4 v12, v[36:39], s[22:23]
	s_add_u32 s22, s22, 0x1000
	s_addc_u32 s23, s23, 0
	global_store_dwordx4 v12, v[40:43], s[22:23]
	s_add_u32 s22, s22, 0x1000
	s_addc_u32 s23, s23, 0
	global_store_dwordx4 v12, v[44:47], s[22:23]
	s_add_u32 s22, s22, 0x1000
	s_addc_u32 s23, s23, 0
	global_store_dwordx4 v12, v[48:51], s[22:23]
	s_add_u32 s22, s22, 0x1000
	s_addc_u32 s23, s23, 0
	global_store_dwordx4 v12, v[52:55], s[22:23]
	s_add_u32 s22, s22, 0x1000
	s_addc_u32 s23, s23, 0
	global_store_dwordx4 v12, v[56:59], s[22:23]
	s_add_u32 s22, s22, 0x1000
	s_addc_u32 s23, s23, 0
	global_store_dwordx4 v12, v[60:63], s[22:23]
	s_add_u32 s22, s22, 0x1000
	s_addc_u32 s23, s23, 0
	global_store_dwordx4 v12, v[64:67], s[22:23]
	s_add_u32 s22, s22, 0x1000
	s_addc_u32 s23, s23, 0
	global_store_dwordx4 v12, v[68:71], s[22:23]
	s_add_u32 s22, s22, 0x1000
	s_addc_u32 s23, s23, 0
	global_store_dwordx4 v12, v[72:75], s[22:23]
	s_add_u32 s22, s22, 0x1000
	s_addc_u32 s23, s23, 0
	global_store_dwordx4 v12, v[76:79], s[22:23]
	s_add_u32 s22, s22, 0x1000
	s_addc_u32 s23, s23, 0
	global_store_dwordx4 v12, v[80:83], s[22:23]
	s_add_u32 s22, s22, 0x1000
	s_addc_u32 s23, s23, 0
	global_store_dwordx4 v12, v[84:87], s[22:23]
	s_add_u32 s22, s22, 0x1000
	s_addc_u32 s23, s23, 0
	global_store_dwordx4 v12, v[88:91], s[22:23]
	s_add_u32 s22, s22, 0x1000
	s_addc_u32 s23, s23, 0
	s_branch .Lp13f_next
; DI float bflo(unsigned u) { return __uint_as_float(u << 16); }
; DI float bfhi(unsigned u) { return __uint_as_float(u & 0xffff0000u); }
; template <int WIN>
; DI void pool_elem(const Params& p, int row, int c) {
;     ...
;     if (t >= WIN - 1) {
;       cnt = (float)WIN;
;       unsigned w[WIN - 1];
; #pragma unroll
;       for (int j = 1; j < WIN; ++j) w[j - 1] = *(const unsigned*)(P2 + (size_t)(row - j) * 2048 + c);
; #pragma unroll
;       for (int j = 1; j < WIN; ++j) { s0 += bflo(w[j - 1]); s1 += bfhi(w[j - 1]); }
;     ...
;   *(unsigned*)(p.MIX + (size_t)row * 1024 + c) = pack2(s0 / cnt - u0, s1 / cnt - u1);
.Lp13f_w2:
	s_sub_u32 s26, s20, 7
	s_lshl_b32 s27, s26, 12
	s_lshr_b32 s28, s26, 20
	s_add_u32 s22, s8, s27
	s_addc_u32 s23, s9, s28
	global_load_dwordx2 v[16:17], v11, s[22:23]
	s_add_u32 s22, s22, 0x1000
	s_addc_u32 s23, s23, 0
	global_load_dwordx2 v[20:21], v11, s[22:23]
	s_add_u32 s22, s22, 0x1000
	s_addc_u32 s23, s23, 0
	global_load_dwordx2 v[24:25], v11, s[22:23]
	s_add_u32 s22, s22, 0x1000
	s_addc_u32 s23, s23, 0
	global_load_dwordx2 v[28:29], v11, s[22:23]
	s_add_u32 s22, s22, 0x1000
	s_addc_u32 s23, s23, 0
	global_load_dwordx2 v[32:33], v11, s[22:23]
	s_add_u32 s22, s22, 0x1000
	s_addc_u32 s23, s23, 0
	global_load_dwordx2 v[36:37], v11, s[22:23]
	s_add_u32 s22, s22, 0x1000
	s_addc_u32 s23, s23, 0
	global_load_dwordx2 v[40:41], v11, s[22:23]
	s_add_u32 s22, s22, 0x1000
	s_addc_u32 s23, s23, 0
	global_load_dwordx2 v[44:45], v11, s[22:23]
	s_add_u32 s22, s22, 0x1000
	s_addc_u32 s23, s23, 0
	global_load_dwordx2 v[48:49], v11, s[22:23]
	s_add_u32 s22, s22, 0x1000
	s_addc_u32 s23, s23, 0
	global_load_dwordx2 v[52:53], v11, s[22:23]
	s_add_u32 s22, s22, 0x1000
	s_addc_u32 s23, s23, 0
	global_load_dwordx2 v[56:57], v11, s[22:23]
	s_add_u32 s22, s22, 0x1000
	s_addc_u32 s23, s23, 0
	global_load_dwordx2 v[60:61], v11, s[22:23]
	s_add_u32 s22, s22, 0x1000
	s_addc_u32 s23, s23, 0
	global_load_dwordx2 v[64:65], v11, s[22:23]
	s_add_u32 s22, s22, 0x1000
	s_addc_u32 s23, s23, 0
	global_load_dwordx2 v[68:69], v11, s[22:23]
	s_add_u32 s22, s22, 0x1000
	s_addc_u32 s23, s23, 0
	global_load_dwordx2 v[72:73], v11, s[22:23]
	s_add_u32 s22, s22, 0x1000
	s_addc_u32 s23, s23, 0
	global_load_dwordx2 v[76:77], v11, s[22:23]
	s_add_u32 s22, s22, 0x1000
	s_addc_u32 s23, s23, 0
	global_load_dwordx2 v[80:81], v11, s[22:23]
	s_add_u32 s22, s22, 0x1000
	s_addc_u32 s23, s23, 0
	global_load_dwordx2 v[84:85], v11, s[22:23]
	s_add_u32 s22, s22, 0x1000
	s_addc_u32 s23, s23, 0
	global_load_dwordx2 v[88:89], v11, s[22:23]
	s_add_u32 s22, s22, 0x1000
	s_addc_u32 s23, s23, 0
	global_load_dwordx2 v[92:93], v11, s[22:23]
	s_add_u32 s22, s22, 0x1000
	s_addc_u32 s23, s23, 0
	global_load_dwordx2 v[96:97], v11, s[22:23]
	s_add_u32 s22, s22, 0x1000
	s_addc_u32 s23, s23, 0
	global_load_dwordx2 v[100:101], v11, s[22:23]
	s_add_u32 s22, s22, 0x1000
	s_addc_u32 s23, s23, 0
	global_load_dwordx2 v[104:105], v11, s[22:23]
	s_add_u32 s22, s22, 0x1000
	s_addc_u32 s23, s23, 0
	s_waitcnt vmcnt(15)
	v_and_b32_e32 v19, 0xffff0000, v17
	v_lshlrev_b32_e32 v18, 16, v17
	v_and_b32_e32 v17, 0xffff0000, v16
	v_lshlrev_b32_e32 v16, 16, v16
	v_and_b32_e32 v23, 0xffff0000, v21
	v_lshlrev_b32_e32 v22, 16, v21
	v_and_b32_e32 v21, 0xffff0000, v20
	v_lshlrev_b32_e32 v20, 16, v20
	v_and_b32_e32 v27, 0xffff0000, v25
	v_lshlrev_b32_e32 v26, 16, v25
	v_and_b32_e32 v25, 0xffff0000, v24
	v_lshlrev_b32_e32 v24, 16, v24
	v_and_b32_e32 v31, 0xffff0000, v29
	v_lshlrev_b32_e32 v30, 16, v29
	v_and_b32_e32 v29, 0xffff0000, v28
	v_lshlrev_b32_e32 v28, 16, v28
	v_and_b32_e32 v35, 0xffff0000, v33
	v_lshlrev_b32_e32 v34, 16, v33
	v_and_b32_e32 v33, 0xffff0000, v32
	v_lshlrev_b32_e32 v32, 16, v32
	v_and_b32_e32 v39, 0xffff0000, v37
	v_lshlrev_b32_e32 v38, 16, v37
	v_and_b32_e32 v37, 0xffff0000, v36
	v_lshlrev_b32_e32 v36, 16, v36
	v_and_b32_e32 v43, 0xffff0000, v41
	v_lshlrev_b32_e32 v42, 16, v41
	v_and_b32_e32 v41, 0xffff0000, v40
	v_lshlrev_b32_e32 v40, 16, v40
	v_and_b32_e32 v47, 0xffff0000, v45
	v_lshlrev_b32_e32 v46, 16, v45
	v_and_b32_e32 v45, 0xffff0000, v44
	v_lshlrev_b32_e32 v44, 16, v44
	v_add_f32_e32 v140, v44, v40
	v_add_f32_e32 v141, v45, v41
	v_add_f32_e32 v142, v46, v42
	v_add_f32_e32 v143, v47, v43
	v_add_f32_e32 v140, v140, v36
	v_add_f32_e32 v141, v141, v37
	v_add_f32_e32 v142, v142, v38
	v_add_f32_e32 v143, v143, v39
	v_add_f32_e32 v140, v140, v32
	v_add_f32_e32 v141, v141, v33
	v_add_f32_e32 v142, v142, v34
	v_add_f32_e32 v143, v143, v35
	v_add_f32_e32 v140, v140, v28
	v_add_f32_e32 v141, v141, v29
	v_add_f32_e32 v142, v142, v30
	v_add_f32_e32 v143, v143, v31
	v_add_f32_e32 v140, v140, v24
	v_add_f32_e32 v141, v141, v25
	v_add_f32_e32 v142, v142, v26
	v_add_f32_e32 v143, v143, v27
	v_add_f32_e32 v140, v140, v20
	v_add_f32_e32 v141, v141, v21
	v_add_f32_e32 v142, v142, v22
	v_add_f32_e32 v143, v143, v23
	v_add_f32_e32 v140, v140, v16
	v_add_f32_e32 v141, v141, v17
	v_add_f32_e32 v142, v142, v18
	v_add_f32_e32 v143, v143, v19
	v_mul_f32_e32 v140, 0x3e000000, v140
	v_mul_f32_e32 v141, 0x3e000000, v141
	v_mul_f32_e32 v142, 0x3e000000, v142
	v_mul_f32_e32 v143, 0x3e000000, v143
	v_sub_f32_e32 v140, v140, v44
	v_sub_f32_e32 v141, v141, v45
	v_sub_f32_e32 v142, v142, v46
	v_sub_f32_e32 v143, v143, v47
	v_cvt_pk_bf16_f32 v152, v140, v141
	v_cvt_pk_bf16_f32 v153, v142, v143
	s_waitcnt vmcnt(14)
	v_and_b32_e32 v51, 0xffff0000, v49
	v_lshlrev_b32_e32 v50, 16, v49
	v_and_b32_e32 v49, 0xffff0000, v48
	v_lshlrev_b32_e32 v48, 16, v48
	v_add_f32_e32 v140, v48, v44
	v_add_f32_e32 v141, v49, v45
	v_add_f32_e32 v142, v50, v46
	v_add_f32_e32 v143, v51, v47
	v_add_f32_e32 v140, v140, v40
	v_add_f32_e32 v141, v141, v41
	v_add_f32_e32 v142, v142, v42
	v_add_f32_e32 v143, v143, v43
	v_add_f32_e32 v140, v140, v36
	v_add_f32_e32 v141, v141, v37
	v_add_f32_e32 v142, v142, v38
	v_add_f32_e32 v143, v143, v39
	v_add_f32_e32 v140, v140, v32
	v_add_f32_e32 v141, v141, v33
	v_add_f32_e32 v142, v142, v34
	v_add_f32_e32 v143, v143, v35
	v_add_f32_e32 v140, v140, v28
	v_add_f32_e32 v141, v141, v29
	v_add_f32_e32 v142, v142, v30
	v_add_f32_e32 v143, v143, v31
	v_add_f32_e32 v140, v140, v24
	v_add_f32_e32 v141, v141, v25
	v_add_f32_e32 v142, v142, v26
	v_add_f32_e32 v143, v143, v27
	v_add_f32_e32 v140, v140, v20
	v_add_f32_e32 v141, v141, v21
	v_add_f32_e32 v142, v142, v22
	v_add_f32_e32 v143, v143, v23
	v_mul_f32_e32 v140, 0x3e000000, v140
	v_mul_f32_e32 v141, 0x3e000000, v141
	v_mul_f32_e32 v142, 0x3e000000, v142
	v_mul_f32_e32 v143, 0x3e000000, v143
	v_sub_f32_e32 v140, v140, v48
	v_sub_f32_e32 v141, v141, v49
	v_sub_f32_e32 v142, v142, v50
	v_sub_f32_e32 v143, v143, v51
	v_cvt_pk_bf16_f32 v154, v140, v141
	v_cvt_pk_bf16_f32 v155, v142, v143
	s_waitcnt vmcnt(13)
; DI float bflo(unsigned u) { return __uint_as_float(u << 16); }
; DI float bfhi(unsigned u) { return __uint_as_float(u & 0xffff0000u); }
; template <int WIN>
; DI void pool_elem(const Params& p, int row, int c) {
;     ...
;     if (t >= WIN - 1) {
;       cnt = (float)WIN;
;       unsigned w[WIN - 1];
; #pragma unroll
;       for (int j = 1; j < WIN; ++j) w[j - 1] = *(const unsigned*)(P2 + (size_t)(row - j) * 2048 + c);
; #pragma unroll
;       for (int j = 1; j < WIN; ++j) { s0 += bflo(w[j - 1]); s1 += bfhi(w[j - 1]); }
;     ...
;   *(unsigned*)(p.MIX + (size_t)row * 1024 + c) = pack2(s0 / cnt - u0, s1 / cnt - u1);
	v_and_b32_e32 v55, 0xffff0000, v53
	v_lshlrev_b32_e32 v54, 16, v53
	v_and_b32_e32 v53, 0xffff0000, v52
	v_lshlrev_b32_e32 v52, 16, v52
	v_add_f32_e32 v140, v52, v48
	v_add_f32_e32 v141, v53, v49
	v_add_f32_e32 v142, v54, v50
	v_add_f32_e32 v143, v55, v51
	v_add_f32_e32 v140, v140, v44
	v_add_f32_e32 v141, v141, v45
	v_add_f32_e32 v142, v142, v46
	v_add_f32_e32 v143, v143, v47
	v_add_f32_e32 v140, v140, v40
	v_add_f32_e32 v141, v141, v41
	v_add_f32_e32 v142, v142, v42
	v_add_f32_e32 v143, v143, v43
	v_add_f32_e32 v140, v140, v36
	v_add_f32_e32 v141, v141, v37
	v_add_f32_e32 v142, v142, v38
	v_add_f32_e32 v143, v143, v39
	v_add_f32_e32 v140, v140, v32
	v_add_f32_e32 v141, v141, v33
	v_add_f32_e32 v142, v142, v34
	v_add_f32_e32 v143, v143, v35
	v_add_f32_e32 v140, v140, v28
	v_add_f32_e32 v141, v141, v29
	v_add_f32_e32 v142, v142, v30
	v_add_f32_e32 v143, v143, v31
	v_add_f32_e32 v140, v140, v24
	v_add_f32_e32 v141, v141, v25
	v_add_f32_e32 v142, v142, v26
	v_add_f32_e32 v143, v143, v27
	v_mul_f32_e32 v140, 0x3e000000, v140
	v_mul_f32_e32 v141, 0x3e000000, v141
	v_mul_f32_e32 v142, 0x3e000000, v142
	v_mul_f32_e32 v143, 0x3e000000, v143
	v_sub_f32_e32 v140, v140, v52
	v_sub_f32_e32 v141, v141, v53
	v_sub_f32_e32 v142, v142, v54
	v_sub_f32_e32 v143, v143, v55
	v_cvt_pk_bf16_f32 v156, v140, v141
	v_cvt_pk_bf16_f32 v157, v142, v143
	s_waitcnt vmcnt(12)
	v_and_b32_e32 v59, 0xffff0000, v57
	v_lshlrev_b32_e32 v58, 16, v57
	v_and_b32_e32 v57, 0xffff0000, v56
	v_lshlrev_b32_e32 v56, 16, v56
	v_add_f32_e32 v140, v56, v52
	v_add_f32_e32 v141, v57, v53
	v_add_f32_e32 v142, v58, v54
	v_add_f32_e32 v143, v59, v55
	v_add_f32_e32 v140, v140, v48
	v_add_f32_e32 v141, v141, v49
	v_add_f32_e32 v142, v142, v50
	v_add_f32_e32 v143, v143, v51
	v_add_f32_e32 v140, v140, v44
	v_add_f32_e32 v141, v141, v45
	v_add_f32_e32 v142, v142, v46
	v_add_f32_e32 v143, v143, v47
	v_add_f32_e32 v140, v140, v40
	v_add_f32_e32 v141, v141, v41
	v_add_f32_e32 v142, v142, v42
	v_add_f32_e32 v143, v143, v43
	v_add_f32_e32 v140, v140, v36
	v_add_f32_e32 v141, v141, v37
	v_add_f32_e32 v142, v142, v38
	v_add_f32_e32 v143, v143, v39
	v_add_f32_e32 v140, v140, v32
	v_add_f32_e32 v141, v141, v33
	v_add_f32_e32 v142, v142, v34
	v_add_f32_e32 v143, v143, v35
	v_add_f32_e32 v140, v140, v28
	v_add_f32_e32 v141, v141, v29
	v_add_f32_e32 v142, v142, v30
	v_add_f32_e32 v143, v143, v31
	v_mul_f32_e32 v140, 0x3e000000, v140
	v_mul_f32_e32 v141, 0x3e000000, v141
	v_mul_f32_e32 v142, 0x3e000000, v142
	v_mul_f32_e32 v143, 0x3e000000, v143
	v_sub_f32_e32 v140, v140, v56
	v_sub_f32_e32 v141, v141, v57
	v_sub_f32_e32 v142, v142, v58
	v_sub_f32_e32 v143, v143, v59
	v_cvt_pk_bf16_f32 v158, v140, v141
	v_cvt_pk_bf16_f32 v159, v142, v143
	s_waitcnt vmcnt(11)
	v_and_b32_e32 v63, 0xffff0000, v61
	v_lshlrev_b32_e32 v62, 16, v61
	v_and_b32_e32 v61, 0xffff0000, v60
	v_lshlrev_b32_e32 v60, 16, v60
	v_add_f32_e32 v140, v60, v56
	v_add_f32_e32 v141, v61, v57
	v_add_f32_e32 v142, v62, v58
	v_add_f32_e32 v143, v63, v59
	v_add_f32_e32 v140, v140, v52
	v_add_f32_e32 v141, v141, v53
	v_add_f32_e32 v142, v142, v54
	v_add_f32_e32 v143, v143, v55
	v_add_f32_e32 v140, v140, v48
	v_add_f32_e32 v141, v141, v49
	v_add_f32_e32 v142, v142, v50
	v_add_f32_e32 v143, v143, v51
	v_add_f32_e32 v140, v140, v44
	v_add_f32_e32 v141, v141, v45
	v_add_f32_e32 v142, v142, v46
	v_add_f32_e32 v143, v143, v47
	v_add_f32_e32 v140, v140, v40
	v_add_f32_e32 v141, v141, v41
	v_add_f32_e32 v142, v142, v42
	v_add_f32_e32 v143, v143, v43
	v_add_f32_e32 v140, v140, v36
	v_add_f32_e32 v141, v141, v37
	v_add_f32_e32 v142, v142, v38
	v_add_f32_e32 v143, v143, v39
	v_add_f32_e32 v140, v140, v32
	v_add_f32_e32 v141, v141, v33
	v_add_f32_e32 v142, v142, v34
	v_add_f32_e32 v143, v143, v35
	v_mul_f32_e32 v140, 0x3e000000, v140
	v_mul_f32_e32 v141, 0x3e000000, v141
	v_mul_f32_e32 v142, 0x3e000000, v142
	v_mul_f32_e32 v143, 0x3e000000, v143
	v_sub_f32_e32 v140, v140, v60
	v_sub_f32_e32 v141, v141, v61
	v_sub_f32_e32 v142, v142, v62
	v_sub_f32_e32 v143, v143, v63
	v_cvt_pk_bf16_f32 v160, v140, v141
	v_cvt_pk_bf16_f32 v161, v142, v143
	s_waitcnt vmcnt(10)
	v_and_b32_e32 v67, 0xffff0000, v65
	v_lshlrev_b32_e32 v66, 16, v65
	v_and_b32_e32 v65, 0xffff0000, v64
	v_lshlrev_b32_e32 v64, 16, v64
	v_add_f32_e32 v140, v64, v60
	v_add_f32_e32 v141, v65, v61
	v_add_f32_e32 v142, v66, v62
	v_add_f32_e32 v143, v67, v63
	v_add_f32_e32 v140, v140, v56
	v_add_f32_e32 v141, v141, v57
	v_add_f32_e32 v142, v142, v58
	v_add_f32_e32 v143, v143, v59
	v_add_f32_e32 v140, v140, v52
	v_add_f32_e32 v141, v141, v53
	v_add_f32_e32 v142, v142, v54
	v_add_f32_e32 v143, v143, v55
	v_add_f32_e32 v140, v140, v48
	v_add_f32_e32 v141, v141, v49
	v_add_f32_e32 v142, v142, v50
	v_add_f32_e32 v143, v143, v51
	v_add_f32_e32 v140, v140, v44
	v_add_f32_e32 v141, v141, v45
	v_add_f32_e32 v142, v142, v46
	v_add_f32_e32 v143, v143, v47
	v_add_f32_e32 v140, v140, v40
	v_add_f32_e32 v141, v141, v41
	v_add_f32_e32 v142, v142, v42
	v_add_f32_e32 v143, v143, v43
	v_add_f32_e32 v140, v140, v36
	v_add_f32_e32 v141, v141, v37
	v_add_f32_e32 v142, v142, v38
	v_add_f32_e32 v143, v143, v39
	v_mul_f32_e32 v140, 0x3e000000, v140
	v_mul_f32_e32 v141, 0x3e000000, v141
	v_mul_f32_e32 v142, 0x3e000000, v142
	v_mul_f32_e32 v143, 0x3e000000, v143
	v_sub_f32_e32 v140, v140, v64
	v_sub_f32_e32 v141, v141, v65
	v_sub_f32_e32 v142, v142, v66
	v_sub_f32_e32 v143, v143, v67
	v_cvt_pk_bf16_f32 v162, v140, v141
	v_cvt_pk_bf16_f32 v163, v142, v143
	s_waitcnt vmcnt(9)
; DI float bflo(unsigned u) { return __uint_as_float(u << 16); }
; DI float bfhi(unsigned u) { return __uint_as_float(u & 0xffff0000u); }
; template <int WIN>
; DI void pool_elem(const Params& p, int row, int c) {
;     ...
;     if (t >= WIN - 1) {
;       cnt = (float)WIN;
;       unsigned w[WIN - 1];
; #pragma unroll
;       for (int j = 1; j < WIN; ++j) w[j - 1] = *(const unsigned*)(P2 + (size_t)(row - j) * 2048 + c);
; #pragma unroll
;       for (int j = 1; j < WIN; ++j) { s0 += bflo(w[j - 1]); s1 += bfhi(w[j - 1]); }
;     ...
;   *(unsigned*)(p.MIX + (size_t)row * 1024 + c) = pack2(s0 / cnt - u0, s1 / cnt - u1);
	v_and_b32_e32 v71, 0xffff0000, v69
	v_lshlrev_b32_e32 v70, 16, v69
	v_and_b32_e32 v69, 0xffff0000, v68
	v_lshlrev_b32_e32 v68, 16, v68
	v_add_f32_e32 v140, v68, v64
	v_add_f32_e32 v141, v69, v65
	v_add_f32_e32 v142, v70, v66
	v_add_f32_e32 v143, v71, v67
	v_add_f32_e32 v140, v140, v60
	v_add_f32_e32 v141, v141, v61
	v_add_f32_e32 v142, v142, v62
	v_add_f32_e32 v143, v143, v63
	v_add_f32_e32 v140, v140, v56
	v_add_f32_e32 v141, v141, v57
	v_add_f32_e32 v142, v142, v58
	v_add_f32_e32 v143, v143, v59
	v_add_f32_e32 v140, v140, v52
	v_add_f32_e32 v141, v141, v53
	v_add_f32_e32 v142, v142, v54
	v_add_f32_e32 v143, v143, v55
	v_add_f32_e32 v140, v140, v48
	v_add_f32_e32 v141, v141, v49
	v_add_f32_e32 v142, v142, v50
	v_add_f32_e32 v143, v143, v51
	v_add_f32_e32 v140, v140, v44
	v_add_f32_e32 v141, v141, v45
	v_add_f32_e32 v142, v142, v46
	v_add_f32_e32 v143, v143, v47
	v_add_f32_e32 v140, v140, v40
	v_add_f32_e32 v141, v141, v41
	v_add_f32_e32 v142, v142, v42
	v_add_f32_e32 v143, v143, v43
	v_mul_f32_e32 v140, 0x3e000000, v140
	v_mul_f32_e32 v141, 0x3e000000, v141
	v_mul_f32_e32 v142, 0x3e000000, v142
	v_mul_f32_e32 v143, 0x3e000000, v143
	v_sub_f32_e32 v140, v140, v68
	v_sub_f32_e32 v141, v141, v69
	v_sub_f32_e32 v142, v142, v70
	v_sub_f32_e32 v143, v143, v71
	v_cvt_pk_bf16_f32 v164, v140, v141
	v_cvt_pk_bf16_f32 v165, v142, v143
	s_waitcnt vmcnt(8)
	v_and_b32_e32 v75, 0xffff0000, v73
	v_lshlrev_b32_e32 v74, 16, v73
	v_and_b32_e32 v73, 0xffff0000, v72
	v_lshlrev_b32_e32 v72, 16, v72
	v_add_f32_e32 v140, v72, v68
	v_add_f32_e32 v141, v73, v69
	v_add_f32_e32 v142, v74, v70
	v_add_f32_e32 v143, v75, v71
	v_add_f32_e32 v140, v140, v64
	v_add_f32_e32 v141, v141, v65
	v_add_f32_e32 v142, v142, v66
	v_add_f32_e32 v143, v143, v67
	v_add_f32_e32 v140, v140, v60
	v_add_f32_e32 v141, v141, v61
	v_add_f32_e32 v142, v142, v62
	v_add_f32_e32 v143, v143, v63
	v_add_f32_e32 v140, v140, v56
	v_add_f32_e32 v141, v141, v57
	v_add_f32_e32 v142, v142, v58
	v_add_f32_e32 v143, v143, v59
	v_add_f32_e32 v140, v140, v52
	v_add_f32_e32 v141, v141, v53
	v_add_f32_e32 v142, v142, v54
	v_add_f32_e32 v143, v143, v55
	v_add_f32_e32 v140, v140, v48
	v_add_f32_e32 v141, v141, v49
	v_add_f32_e32 v142, v142, v50
	v_add_f32_e32 v143, v143, v51
	v_add_f32_e32 v140, v140, v44
	v_add_f32_e32 v141, v141, v45
	v_add_f32_e32 v142, v142, v46
	v_add_f32_e32 v143, v143, v47
	v_mul_f32_e32 v140, 0x3e000000, v140
	v_mul_f32_e32 v141, 0x3e000000, v141
	v_mul_f32_e32 v142, 0x3e000000, v142
	v_mul_f32_e32 v143, 0x3e000000, v143
	v_sub_f32_e32 v140, v140, v72
	v_sub_f32_e32 v141, v141, v73
	v_sub_f32_e32 v142, v142, v74
	v_sub_f32_e32 v143, v143, v75
	v_cvt_pk_bf16_f32 v166, v140, v141
	v_cvt_pk_bf16_f32 v167, v142, v143
	s_waitcnt vmcnt(7)
	v_and_b32_e32 v79, 0xffff0000, v77
	v_lshlrev_b32_e32 v78, 16, v77
	v_and_b32_e32 v77, 0xffff0000, v76
	v_lshlrev_b32_e32 v76, 16, v76
	v_add_f32_e32 v140, v76, v72
	v_add_f32_e32 v141, v77, v73
	v_add_f32_e32 v142, v78, v74
	v_add_f32_e32 v143, v79, v75
	v_add_f32_e32 v140, v140, v68
	v_add_f32_e32 v141, v141, v69
	v_add_f32_e32 v142, v142, v70
	v_add_f32_e32 v143, v143, v71
	v_add_f32_e32 v140, v140, v64
	v_add_f32_e32 v141, v141, v65
	v_add_f32_e32 v142, v142, v66
	v_add_f32_e32 v143, v143, v67
	v_add_f32_e32 v140, v140, v60
	v_add_f32_e32 v141, v141, v61
	v_add_f32_e32 v142, v142, v62
	v_add_f32_e32 v143, v143, v63
	v_add_f32_e32 v140, v140, v56
	v_add_f32_e32 v141, v141, v57
	v_add_f32_e32 v142, v142, v58
	v_add_f32_e32 v143, v143, v59
	v_add_f32_e32 v140, v140, v52
	v_add_f32_e32 v141, v141, v53
	v_add_f32_e32 v142, v142, v54
	v_add_f32_e32 v143, v143, v55
	v_add_f32_e32 v140, v140, v48
	v_add_f32_e32 v141, v141, v49
	v_add_f32_e32 v142, v142, v50
	v_add_f32_e32 v143, v143, v51
	v_mul_f32_e32 v140, 0x3e000000, v140
	v_mul_f32_e32 v141, 0x3e000000, v141
	v_mul_f32_e32 v142, 0x3e000000, v142
	v_mul_f32_e32 v143, 0x3e000000, v143
	v_sub_f32_e32 v140, v140, v76
	v_sub_f32_e32 v141, v141, v77
	v_sub_f32_e32 v142, v142, v78
	v_sub_f32_e32 v143, v143, v79
	v_cvt_pk_bf16_f32 v168, v140, v141
	v_cvt_pk_bf16_f32 v169, v142, v143
	s_waitcnt vmcnt(6)
	v_and_b32_e32 v83, 0xffff0000, v81
	v_lshlrev_b32_e32 v82, 16, v81
	v_and_b32_e32 v81, 0xffff0000, v80
	v_lshlrev_b32_e32 v80, 16, v80
	v_add_f32_e32 v140, v80, v76
	v_add_f32_e32 v141, v81, v77
	v_add_f32_e32 v142, v82, v78
	v_add_f32_e32 v143, v83, v79
	v_add_f32_e32 v140, v140, v72
	v_add_f32_e32 v141, v141, v73
	v_add_f32_e32 v142, v142, v74
	v_add_f32_e32 v143, v143, v75
	v_add_f32_e32 v140, v140, v68
	v_add_f32_e32 v141, v141, v69
	v_add_f32_e32 v142, v142, v70
	v_add_f32_e32 v143, v143, v71
	v_add_f32_e32 v140, v140, v64
	v_add_f32_e32 v141, v141, v65
	v_add_f32_e32 v142, v142, v66
	v_add_f32_e32 v143, v143, v67
	v_add_f32_e32 v140, v140, v60
	v_add_f32_e32 v141, v141, v61
	v_add_f32_e32 v142, v142, v62
	v_add_f32_e32 v143, v143, v63
	v_add_f32_e32 v140, v140, v56
	v_add_f32_e32 v141, v141, v57
	v_add_f32_e32 v142, v142, v58
	v_add_f32_e32 v143, v143, v59
	v_add_f32_e32 v140, v140, v52
	v_add_f32_e32 v141, v141, v53
	v_add_f32_e32 v142, v142, v54
	v_add_f32_e32 v143, v143, v55
	v_mul_f32_e32 v140, 0x3e000000, v140
	v_mul_f32_e32 v141, 0x3e000000, v141
	v_mul_f32_e32 v142, 0x3e000000, v142
	v_mul_f32_e32 v143, 0x3e000000, v143
	v_sub_f32_e32 v140, v140, v80
	v_sub_f32_e32 v141, v141, v81
	v_sub_f32_e32 v142, v142, v82
	v_sub_f32_e32 v143, v143, v83
	v_cvt_pk_bf16_f32 v170, v140, v141
	v_cvt_pk_bf16_f32 v171, v142, v143
	s_waitcnt vmcnt(5)
; DI float bflo(unsigned u) { return __uint_as_float(u << 16); }
; DI float bfhi(unsigned u) { return __uint_as_float(u & 0xffff0000u); }
; template <int WIN>
; DI void pool_elem(const Params& p, int row, int c) {
;     ...
;     if (t >= WIN - 1) {
;       cnt = (float)WIN;
;       unsigned w[WIN - 1];
; #pragma unroll
;       for (int j = 1; j < WIN; ++j) w[j - 1] = *(const unsigned*)(P2 + (size_t)(row - j) * 2048 + c);
; #pragma unroll
;       for (int j = 1; j < WIN; ++j) { s0 += bflo(w[j - 1]); s1 += bfhi(w[j - 1]); }
;     ...
;   *(unsigned*)(p.MIX + (size_t)row * 1024 + c) = pack2(s0 / cnt - u0, s1 / cnt - u1);
	v_and_b32_e32 v87, 0xffff0000, v85
	v_lshlrev_b32_e32 v86, 16, v85
	v_and_b32_e32 v85, 0xffff0000, v84
	v_lshlrev_b32_e32 v84, 16, v84
	v_add_f32_e32 v140, v84, v80
	v_add_f32_e32 v141, v85, v81
	v_add_f32_e32 v142, v86, v82
	v_add_f32_e32 v143, v87, v83
	v_add_f32_e32 v140, v140, v76
	v_add_f32_e32 v141, v141, v77
	v_add_f32_e32 v142, v142, v78
	v_add_f32_e32 v143, v143, v79
	v_add_f32_e32 v140, v140, v72
	v_add_f32_e32 v141, v141, v73
	v_add_f32_e32 v142, v142, v74
	v_add_f32_e32 v143, v143, v75
	v_add_f32_e32 v140, v140, v68
	v_add_f32_e32 v141, v141, v69
	v_add_f32_e32 v142, v142, v70
	v_add_f32_e32 v143, v143, v71
	v_add_f32_e32 v140, v140, v64
	v_add_f32_e32 v141, v141, v65
	v_add_f32_e32 v142, v142, v66
	v_add_f32_e32 v143, v143, v67
	v_add_f32_e32 v140, v140, v60
	v_add_f32_e32 v141, v141, v61
	v_add_f32_e32 v142, v142, v62
	v_add_f32_e32 v143, v143, v63
	v_add_f32_e32 v140, v140, v56
	v_add_f32_e32 v141, v141, v57
	v_add_f32_e32 v142, v142, v58
	v_add_f32_e32 v143, v143, v59
	v_mul_f32_e32 v140, 0x3e000000, v140
	v_mul_f32_e32 v141, 0x3e000000, v141
	v_mul_f32_e32 v142, 0x3e000000, v142
	v_mul_f32_e32 v143, 0x3e000000, v143
	v_sub_f32_e32 v140, v140, v84
	v_sub_f32_e32 v141, v141, v85
	v_sub_f32_e32 v142, v142, v86
	v_sub_f32_e32 v143, v143, v87
	v_cvt_pk_bf16_f32 v172, v140, v141
	v_cvt_pk_bf16_f32 v173, v142, v143
	s_waitcnt vmcnt(4)
	v_and_b32_e32 v91, 0xffff0000, v89
	v_lshlrev_b32_e32 v90, 16, v89
	v_and_b32_e32 v89, 0xffff0000, v88
	v_lshlrev_b32_e32 v88, 16, v88
	v_add_f32_e32 v140, v88, v84
	v_add_f32_e32 v141, v89, v85
	v_add_f32_e32 v142, v90, v86
	v_add_f32_e32 v143, v91, v87
	v_add_f32_e32 v140, v140, v80
	v_add_f32_e32 v141, v141, v81
	v_add_f32_e32 v142, v142, v82
	v_add_f32_e32 v143, v143, v83
	v_add_f32_e32 v140, v140, v76
	v_add_f32_e32 v141, v141, v77
	v_add_f32_e32 v142, v142, v78
	v_add_f32_e32 v143, v143, v79
	v_add_f32_e32 v140, v140, v72
	v_add_f32_e32 v141, v141, v73
	v_add_f32_e32 v142, v142, v74
	v_add_f32_e32 v143, v143, v75
	v_add_f32_e32 v140, v140, v68
	v_add_f32_e32 v141, v141, v69
	v_add_f32_e32 v142, v142, v70
	v_add_f32_e32 v143, v143, v71
	v_add_f32_e32 v140, v140, v64
	v_add_f32_e32 v141, v141, v65
	v_add_f32_e32 v142, v142, v66
	v_add_f32_e32 v143, v143, v67
	v_add_f32_e32 v140, v140, v60
	v_add_f32_e32 v141, v141, v61
	v_add_f32_e32 v142, v142, v62
	v_add_f32_e32 v143, v143, v63
	v_mul_f32_e32 v140, 0x3e000000, v140
	v_mul_f32_e32 v141, 0x3e000000, v141
	v_mul_f32_e32 v142, 0x3e000000, v142
	v_mul_f32_e32 v143, 0x3e000000, v143
	v_sub_f32_e32 v140, v140, v88
	v_sub_f32_e32 v141, v141, v89
	v_sub_f32_e32 v142, v142, v90
	v_sub_f32_e32 v143, v143, v91
	v_cvt_pk_bf16_f32 v174, v140, v141
	v_cvt_pk_bf16_f32 v175, v142, v143
	s_waitcnt vmcnt(3)
	v_and_b32_e32 v95, 0xffff0000, v93
	v_lshlrev_b32_e32 v94, 16, v93
	v_and_b32_e32 v93, 0xffff0000, v92
	v_lshlrev_b32_e32 v92, 16, v92
	v_add_f32_e32 v140, v92, v88
	v_add_f32_e32 v141, v93, v89
	v_add_f32_e32 v142, v94, v90
	v_add_f32_e32 v143, v95, v91
	v_add_f32_e32 v140, v140, v84
	v_add_f32_e32 v141, v141, v85
	v_add_f32_e32 v142, v142, v86
	v_add_f32_e32 v143, v143, v87
	v_add_f32_e32 v140, v140, v80
	v_add_f32_e32 v141, v141, v81
	v_add_f32_e32 v142, v142, v82
	v_add_f32_e32 v143, v143, v83
	v_add_f32_e32 v140, v140, v76
	v_add_f32_e32 v141, v141, v77
	v_add_f32_e32 v142, v142, v78
	v_add_f32_e32 v143, v143, v79
	v_add_f32_e32 v140, v140, v72
	v_add_f32_e32 v141, v141, v73
	v_add_f32_e32 v142, v142, v74
	v_add_f32_e32 v143, v143, v75
	v_add_f32_e32 v140, v140, v68
	v_add_f32_e32 v141, v141, v69
	v_add_f32_e32 v142, v142, v70
	v_add_f32_e32 v143, v143, v71
	v_add_f32_e32 v140, v140, v64
	v_add_f32_e32 v141, v141, v65
	v_add_f32_e32 v142, v142, v66
	v_add_f32_e32 v143, v143, v67
	v_mul_f32_e32 v140, 0x3e000000, v140
	v_mul_f32_e32 v141, 0x3e000000, v141
	v_mul_f32_e32 v142, 0x3e000000, v142
	v_mul_f32_e32 v143, 0x3e000000, v143
	v_sub_f32_e32 v140, v140, v92
	v_sub_f32_e32 v141, v141, v93
	v_sub_f32_e32 v142, v142, v94
	v_sub_f32_e32 v143, v143, v95
	v_cvt_pk_bf16_f32 v176, v140, v141
	v_cvt_pk_bf16_f32 v177, v142, v143
	s_waitcnt vmcnt(2)
	v_and_b32_e32 v99, 0xffff0000, v97
	v_lshlrev_b32_e32 v98, 16, v97
	v_and_b32_e32 v97, 0xffff0000, v96
	v_lshlrev_b32_e32 v96, 16, v96
	v_add_f32_e32 v140, v96, v92
	v_add_f32_e32 v141, v97, v93
	v_add_f32_e32 v142, v98, v94
	v_add_f32_e32 v143, v99, v95
	v_add_f32_e32 v140, v140, v88
	v_add_f32_e32 v141, v141, v89
	v_add_f32_e32 v142, v142, v90
	v_add_f32_e32 v143, v143, v91
	v_add_f32_e32 v140, v140, v84
	v_add_f32_e32 v141, v141, v85
	v_add_f32_e32 v142, v142, v86
	v_add_f32_e32 v143, v143, v87
	v_add_f32_e32 v140, v140, v80
	v_add_f32_e32 v141, v141, v81
	v_add_f32_e32 v142, v142, v82
	v_add_f32_e32 v143, v143, v83
	v_add_f32_e32 v140, v140, v76
	v_add_f32_e32 v141, v141, v77
	v_add_f32_e32 v142, v142, v78
	v_add_f32_e32 v143, v143, v79
	v_add_f32_e32 v140, v140, v72
	v_add_f32_e32 v141, v141, v73
	v_add_f32_e32 v142, v142, v74
	v_add_f32_e32 v143, v143, v75
	v_add_f32_e32 v140, v140, v68
	v_add_f32_e32 v141, v141, v69
	v_add_f32_e32 v142, v142, v70
	v_add_f32_e32 v143, v143, v71
	v_mul_f32_e32 v140, 0x3e000000, v140
	v_mul_f32_e32 v141, 0x3e000000, v141
	v_mul_f32_e32 v142, 0x3e000000, v142
	v_mul_f32_e32 v143, 0x3e000000, v143
	v_sub_f32_e32 v140, v140, v96
	v_sub_f32_e32 v141, v141, v97
	v_sub_f32_e32 v142, v142, v98
	v_sub_f32_e32 v143, v143, v99
	v_cvt_pk_bf16_f32 v178, v140, v141
	v_cvt_pk_bf16_f32 v179, v142, v143
	s_waitcnt vmcnt(1)
; DI float bflo(unsigned u) { return __uint_as_float(u << 16); }
; DI float bfhi(unsigned u) { return __uint_as_float(u & 0xffff0000u); }
; template <int WIN>
; DI void pool_elem(const Params& p, int row, int c) {
;     ...
;     if (t >= WIN - 1) {
;       cnt = (float)WIN;
;       unsigned w[WIN - 1];
; #pragma unroll
;       for (int j = 1; j < WIN; ++j) w[j - 1] = *(const unsigned*)(P2 + (size_t)(row - j) * 2048 + c);
; #pragma unroll
;       for (int j = 1; j < WIN; ++j) { s0 += bflo(w[j - 1]); s1 += bfhi(w[j - 1]); }
;     } else {
;       cnt = (float)(t + 1);
;       for (int j = 1; j <= t; ++j) {
;         unsigned w = *(const unsigned*)(P2 + (size_t)(row - j) * 2048 + c);
;         s0 += bflo(w); s1 += bfhi(w);
;       }
;     }
;     if (t >= 2033) {
;       float2 o = {u0, u1};
;       *(float2*)(p.out + O_POOLP + ((size_t)b * 15 + (t - 2033)) * 1024 + c) = o;
;     }
;     ...
;   *(unsigned*)(p.MIX + (size_t)row * 1024 + c) = pack2(s0 / cnt - u0, s1 / cnt - u1);
	v_and_b32_e32 v103, 0xffff0000, v101
	v_lshlrev_b32_e32 v102, 16, v101
	v_and_b32_e32 v101, 0xffff0000, v100
	v_lshlrev_b32_e32 v100, 16, v100
	v_add_f32_e32 v140, v100, v96
	v_add_f32_e32 v141, v101, v97
	v_add_f32_e32 v142, v102, v98
	v_add_f32_e32 v143, v103, v99
	v_add_f32_e32 v140, v140, v92
	v_add_f32_e32 v141, v141, v93
	v_add_f32_e32 v142, v142, v94
	v_add_f32_e32 v143, v143, v95
	v_add_f32_e32 v140, v140, v88
	v_add_f32_e32 v141, v141, v89
	v_add_f32_e32 v142, v142, v90
	v_add_f32_e32 v143, v143, v91
	v_add_f32_e32 v140, v140, v84
	v_add_f32_e32 v141, v141, v85
	v_add_f32_e32 v142, v142, v86
	v_add_f32_e32 v143, v143, v87
	v_add_f32_e32 v140, v140, v80
	v_add_f32_e32 v141, v141, v81
	v_add_f32_e32 v142, v142, v82
	v_add_f32_e32 v143, v143, v83
	v_add_f32_e32 v140, v140, v76
	v_add_f32_e32 v141, v141, v77
	v_add_f32_e32 v142, v142, v78
	v_add_f32_e32 v143, v143, v79
	v_add_f32_e32 v140, v140, v72
	v_add_f32_e32 v141, v141, v73
	v_add_f32_e32 v142, v142, v74
	v_add_f32_e32 v143, v143, v75
	v_mul_f32_e32 v140, 0x3e000000, v140
	v_mul_f32_e32 v141, 0x3e000000, v141
	v_mul_f32_e32 v142, 0x3e000000, v142
	v_mul_f32_e32 v143, 0x3e000000, v143
	v_sub_f32_e32 v140, v140, v100
	v_sub_f32_e32 v141, v141, v101
	v_sub_f32_e32 v142, v142, v102
	v_sub_f32_e32 v143, v143, v103
	v_cvt_pk_bf16_f32 v180, v140, v141
	v_cvt_pk_bf16_f32 v181, v142, v143
	s_waitcnt vmcnt(0)
	v_and_b32_e32 v107, 0xffff0000, v105
	v_lshlrev_b32_e32 v106, 16, v105
	v_and_b32_e32 v105, 0xffff0000, v104
	v_lshlrev_b32_e32 v104, 16, v104
	v_add_f32_e32 v140, v104, v100
	v_add_f32_e32 v141, v105, v101
	v_add_f32_e32 v142, v106, v102
	v_add_f32_e32 v143, v107, v103
	v_add_f32_e32 v140, v140, v96
	v_add_f32_e32 v141, v141, v97
	v_add_f32_e32 v142, v142, v98
	v_add_f32_e32 v143, v143, v99
	v_add_f32_e32 v140, v140, v92
	v_add_f32_e32 v141, v141, v93
	v_add_f32_e32 v142, v142, v94
	v_add_f32_e32 v143, v143, v95
	v_add_f32_e32 v140, v140, v88
	v_add_f32_e32 v141, v141, v89
	v_add_f32_e32 v142, v142, v90
	v_add_f32_e32 v143, v143, v91
	v_add_f32_e32 v140, v140, v84
	v_add_f32_e32 v141, v141, v85
	v_add_f32_e32 v142, v142, v86
	v_add_f32_e32 v143, v143, v87
	v_add_f32_e32 v140, v140, v80
	v_add_f32_e32 v141, v141, v81
	v_add_f32_e32 v142, v142, v82
	v_add_f32_e32 v143, v143, v83
	v_add_f32_e32 v140, v140, v76
	v_add_f32_e32 v141, v141, v77
	v_add_f32_e32 v142, v142, v78
	v_add_f32_e32 v143, v143, v79
	v_mul_f32_e32 v140, 0x3e000000, v140
	v_mul_f32_e32 v141, 0x3e000000, v141
	v_mul_f32_e32 v142, 0x3e000000, v142
	v_mul_f32_e32 v143, 0x3e000000, v143
	v_sub_f32_e32 v140, v140, v104
	v_sub_f32_e32 v141, v141, v105
	v_sub_f32_e32 v142, v142, v106
	v_sub_f32_e32 v143, v143, v107
	v_cvt_pk_bf16_f32 v182, v140, v141
	v_cvt_pk_bf16_f32 v183, v142, v143
	global_store_dwordx2 v11, v[152:153], s[24:25]
	s_add_u32 s24, s24, 0x800
	s_addc_u32 s25, s25, 0
	global_store_dwordx2 v11, v[154:155], s[24:25]
	s_add_u32 s24, s24, 0x800
	s_addc_u32 s25, s25, 0
	global_store_dwordx2 v11, v[156:157], s[24:25]
	s_add_u32 s24, s24, 0x800
	s_addc_u32 s25, s25, 0
	global_store_dwordx2 v11, v[158:159], s[24:25]
	s_add_u32 s24, s24, 0x800
	s_addc_u32 s25, s25, 0
	global_store_dwordx2 v11, v[160:161], s[24:25]
	s_add_u32 s24, s24, 0x800
	s_addc_u32 s25, s25, 0
	global_store_dwordx2 v11, v[162:163], s[24:25]
	s_add_u32 s24, s24, 0x800
	s_addc_u32 s25, s25, 0
	global_store_dwordx2 v11, v[164:165], s[24:25]
	s_add_u32 s24, s24, 0x800
	s_addc_u32 s25, s25, 0
	global_store_dwordx2 v11, v[166:167], s[24:25]
	s_add_u32 s24, s24, 0x800
	s_addc_u32 s25, s25, 0
	global_store_dwordx2 v11, v[168:169], s[24:25]
	s_add_u32 s24, s24, 0x800
	s_addc_u32 s25, s25, 0
	global_store_dwordx2 v11, v[170:171], s[24:25]
	s_add_u32 s24, s24, 0x800
	s_addc_u32 s25, s25, 0
	global_store_dwordx2 v11, v[172:173], s[24:25]
	s_add_u32 s24, s24, 0x800
	s_addc_u32 s25, s25, 0
	global_store_dwordx2 v11, v[174:175], s[24:25]
	s_add_u32 s24, s24, 0x800
	s_addc_u32 s25, s25, 0
	global_store_dwordx2 v11, v[176:177], s[24:25]
	s_add_u32 s24, s24, 0x800
	s_addc_u32 s25, s25, 0
	global_store_dwordx2 v11, v[178:179], s[24:25]
	s_add_u32 s24, s24, 0x800
	s_addc_u32 s25, s25, 0
	global_store_dwordx2 v11, v[180:181], s[24:25]
	s_add_u32 s24, s24, 0x800
	s_addc_u32 s25, s25, 0
	global_store_dwordx2 v11, v[182:183], s[24:25]
	s_add_u32 s24, s24, 0x800
	s_addc_u32 s25, s25, 0
	s_cmp_eq_u32 s18, 127
	s_cbranch_scc0 .Lp13f_next
	s_mul_i32 s26, s17, 61440
	s_add_u32 s26, s26, 0x431c000
	s_add_u32 s22, s12, s26
	s_addc_u32 s23, s13, 0
	global_store_dwordx4 v12, v[48:51], s[22:23]
	s_add_u32 s22, s22, 0x1000
	s_addc_u32 s23, s23, 0
	global_store_dwordx4 v12, v[52:55], s[22:23]
	s_add_u32 s22, s22, 0x1000
	s_addc_u32 s23, s23, 0
	global_store_dwordx4 v12, v[56:59], s[22:23]
	s_add_u32 s22, s22, 0x1000
	s_addc_u32 s23, s23, 0
	global_store_dwordx4 v12, v[60:63], s[22:23]
	s_add_u32 s22, s22, 0x1000
	s_addc_u32 s23, s23, 0
	global_store_dwordx4 v12, v[64:67], s[22:23]
	s_add_u32 s22, s22, 0x1000
	s_addc_u32 s23, s23, 0
	global_store_dwordx4 v12, v[68:71], s[22:23]
	s_add_u32 s22, s22, 0x1000
	s_addc_u32 s23, s23, 0
	global_store_dwordx4 v12, v[72:75], s[22:23]
	s_add_u32 s22, s22, 0x1000
	s_addc_u32 s23, s23, 0
	global_store_dwordx4 v12, v[76:79], s[22:23]
	s_add_u32 s22, s22, 0x1000
	s_addc_u32 s23, s23, 0
	global_store_dwordx4 v12, v[80:83], s[22:23]
	s_add_u32 s22, s22, 0x1000
	s_addc_u32 s23, s23, 0
	global_store_dwordx4 v12, v[84:87], s[22:23]
	s_add_u32 s22, s22, 0x1000
	s_addc_u32 s23, s23, 0
	global_store_dwordx4 v12, v[88:91], s[22:23]
	s_add_u32 s22, s22, 0x1000
	s_addc_u32 s23, s23, 0
	global_store_dwordx4 v12, v[92:95], s[22:23]
	s_add_u32 s22, s22, 0x1000
	s_addc_u32 s23, s23, 0
	global_store_dwordx4 v12, v[96:99], s[22:23]
	s_add_u32 s22, s22, 0x1000
	s_addc_u32 s23, s23, 0
	global_store_dwordx4 v12, v[100:103], s[22:23]
	s_add_u32 s22, s22, 0x1000
	s_addc_u32 s23, s23, 0
	global_store_dwordx4 v12, v[104:107], s[22:23]
	s_add_u32 s22, s22, 0x1000
	s_addc_u32 s23, s23, 0
	s_branch .Lp13f_next
; DI float bflo(unsigned u) { return __uint_as_float(u << 16); }
; DI float bfhi(unsigned u) { return __uint_as_float(u & 0xffff0000u); }
; template <int WIN>
; DI void pool_elem(const Params& p, int row, int c) {
;     ...
;     if (t >= WIN - 1) {
;       cnt = (float)WIN;
;       unsigned w[WIN - 1];
; #pragma unroll
;       for (int j = 1; j < WIN; ++j) w[j - 1] = *(const unsigned*)(P2 + (size_t)(row - j) * 2048 + c);
; #pragma unroll
;       for (int j = 1; j < WIN; ++j) { s0 += bflo(w[j - 1]); s1 += bfhi(w[j - 1]); }
.Lp13f_w3:
	s_sub_u32 s26, s20, 15
	s_lshl_b32 s27, s26, 12
	s_lshr_b32 s28, s26, 20
	s_add_u32 s22, s8, s27
	s_addc_u32 s23, s9, s28
	global_load_dwordx2 v[16:17], v11, s[22:23]
	s_add_u32 s22, s22, 0x1000
	s_addc_u32 s23, s23, 0
	global_load_dwordx2 v[20:21], v11, s[22:23]
	s_add_u32 s22, s22, 0x1000
	s_addc_u32 s23, s23, 0
	global_load_dwordx2 v[24:25], v11, s[22:23]
	s_add_u32 s22, s22, 0x1000
	s_addc_u32 s23, s23, 0
	global_load_dwordx2 v[28:29], v11, s[22:23]
	s_add_u32 s22, s22, 0x1000
	s_addc_u32 s23, s23, 0
	global_load_dwordx2 v[32:33], v11, s[22:23]
	s_add_u32 s22, s22, 0x1000
	s_addc_u32 s23, s23, 0
	global_load_dwordx2 v[36:37], v11, s[22:23]
	s_add_u32 s22, s22, 0x1000
	s_addc_u32 s23, s23, 0
	global_load_dwordx2 v[40:41], v11, s[22:23]
	s_add_u32 s22, s22, 0x1000
	s_addc_u32 s23, s23, 0
	global_load_dwordx2 v[44:45], v11, s[22:23]
	s_add_u32 s22, s22, 0x1000
	s_addc_u32 s23, s23, 0
	global_load_dwordx2 v[48:49], v11, s[22:23]
	s_add_u32 s22, s22, 0x1000
	s_addc_u32 s23, s23, 0
	global_load_dwordx2 v[52:53], v11, s[22:23]
	s_add_u32 s22, s22, 0x1000
	s_addc_u32 s23, s23, 0
	global_load_dwordx2 v[56:57], v11, s[22:23]
	s_add_u32 s22, s22, 0x1000
	s_addc_u32 s23, s23, 0
	global_load_dwordx2 v[60:61], v11, s[22:23]
	s_add_u32 s22, s22, 0x1000
	s_addc_u32 s23, s23, 0
	global_load_dwordx2 v[64:65], v11, s[22:23]
	s_add_u32 s22, s22, 0x1000
	s_addc_u32 s23, s23, 0
	global_load_dwordx2 v[68:69], v11, s[22:23]
	s_add_u32 s22, s22, 0x1000
	s_addc_u32 s23, s23, 0
	global_load_dwordx2 v[72:73], v11, s[22:23]
	s_add_u32 s22, s22, 0x1000
	s_addc_u32 s23, s23, 0
	global_load_dwordx2 v[76:77], v11, s[22:23]
	s_add_u32 s22, s22, 0x1000
	s_addc_u32 s23, s23, 0
	global_load_dwordx2 v[80:81], v11, s[22:23]
	s_add_u32 s22, s22, 0x1000
	s_addc_u32 s23, s23, 0
	global_load_dwordx2 v[84:85], v11, s[22:23]
	s_add_u32 s22, s22, 0x1000
	s_addc_u32 s23, s23, 0
	global_load_dwordx2 v[88:89], v11, s[22:23]
	s_add_u32 s22, s22, 0x1000
	s_addc_u32 s23, s23, 0
	global_load_dwordx2 v[92:93], v11, s[22:23]
	s_add_u32 s22, s22, 0x1000
	s_addc_u32 s23, s23, 0
	global_load_dwordx2 v[96:97], v11, s[22:23]
	s_add_u32 s22, s22, 0x1000
	s_addc_u32 s23, s23, 0
	global_load_dwordx2 v[100:101], v11, s[22:23]
	s_add_u32 s22, s22, 0x1000
	s_addc_u32 s23, s23, 0
	global_load_dwordx2 v[104:105], v11, s[22:23]
	s_add_u32 s22, s22, 0x1000
	s_addc_u32 s23, s23, 0
	global_load_dwordx2 v[108:109], v11, s[22:23]
	s_add_u32 s22, s22, 0x1000
	s_addc_u32 s23, s23, 0
	global_load_dwordx2 v[112:113], v11, s[22:23]
	s_add_u32 s22, s22, 0x1000
	s_addc_u32 s23, s23, 0
	global_load_dwordx2 v[116:117], v11, s[22:23]
	s_add_u32 s22, s22, 0x1000
	s_addc_u32 s23, s23, 0
	global_load_dwordx2 v[120:121], v11, s[22:23]
	s_add_u32 s22, s22, 0x1000
	s_addc_u32 s23, s23, 0
	global_load_dwordx2 v[124:125], v11, s[22:23]
	s_add_u32 s22, s22, 0x1000
	s_addc_u32 s23, s23, 0
	global_load_dwordx2 v[128:129], v11, s[22:23]
	s_add_u32 s22, s22, 0x1000
	s_addc_u32 s23, s23, 0
	global_load_dwordx2 v[132:133], v11, s[22:23]
	s_add_u32 s22, s22, 0x1000
	s_addc_u32 s23, s23, 0
	global_load_dwordx2 v[136:137], v11, s[22:23]
	s_add_u32 s22, s22, 0x1000
	s_addc_u32 s23, s23, 0
	s_waitcnt vmcnt(15)
	v_and_b32_e32 v19, 0xffff0000, v17
	v_lshlrev_b32_e32 v18, 16, v17
	v_and_b32_e32 v17, 0xffff0000, v16
	v_lshlrev_b32_e32 v16, 16, v16
	v_and_b32_e32 v23, 0xffff0000, v21
	v_lshlrev_b32_e32 v22, 16, v21
	v_and_b32_e32 v21, 0xffff0000, v20
	v_lshlrev_b32_e32 v20, 16, v20
	v_and_b32_e32 v27, 0xffff0000, v25
	v_lshlrev_b32_e32 v26, 16, v25
	v_and_b32_e32 v25, 0xffff0000, v24
	v_lshlrev_b32_e32 v24, 16, v24
	v_and_b32_e32 v31, 0xffff0000, v29
	v_lshlrev_b32_e32 v30, 16, v29
	v_and_b32_e32 v29, 0xffff0000, v28
	v_lshlrev_b32_e32 v28, 16, v28
	v_and_b32_e32 v35, 0xffff0000, v33
	v_lshlrev_b32_e32 v34, 16, v33
	v_and_b32_e32 v33, 0xffff0000, v32
	v_lshlrev_b32_e32 v32, 16, v32
	v_and_b32_e32 v39, 0xffff0000, v37
	v_lshlrev_b32_e32 v38, 16, v37
	v_and_b32_e32 v37, 0xffff0000, v36
	v_lshlrev_b32_e32 v36, 16, v36
	v_and_b32_e32 v43, 0xffff0000, v41
	v_lshlrev_b32_e32 v42, 16, v41
	v_and_b32_e32 v41, 0xffff0000, v40
	v_lshlrev_b32_e32 v40, 16, v40
	v_and_b32_e32 v47, 0xffff0000, v45
	v_lshlrev_b32_e32 v46, 16, v45
	v_and_b32_e32 v45, 0xffff0000, v44
	v_lshlrev_b32_e32 v44, 16, v44
	v_and_b32_e32 v51, 0xffff0000, v49
	v_lshlrev_b32_e32 v50, 16, v49
	v_and_b32_e32 v49, 0xffff0000, v48
	v_lshlrev_b32_e32 v48, 16, v48
	v_and_b32_e32 v55, 0xffff0000, v53
	v_lshlrev_b32_e32 v54, 16, v53
	v_and_b32_e32 v53, 0xffff0000, v52
	v_lshlrev_b32_e32 v52, 16, v52
	v_and_b32_e32 v59, 0xffff0000, v57
	v_lshlrev_b32_e32 v58, 16, v57
	v_and_b32_e32 v57, 0xffff0000, v56
	v_lshlrev_b32_e32 v56, 16, v56
	v_and_b32_e32 v63, 0xffff0000, v61
	v_lshlrev_b32_e32 v62, 16, v61
	v_and_b32_e32 v61, 0xffff0000, v60
	v_lshlrev_b32_e32 v60, 16, v60
	v_and_b32_e32 v67, 0xffff0000, v65
	v_lshlrev_b32_e32 v66, 16, v65
	v_and_b32_e32 v65, 0xffff0000, v64
	v_lshlrev_b32_e32 v64, 16, v64
	v_and_b32_e32 v71, 0xffff0000, v69
	v_lshlrev_b32_e32 v70, 16, v69
	v_and_b32_e32 v69, 0xffff0000, v68
	v_lshlrev_b32_e32 v68, 16, v68
	v_and_b32_e32 v75, 0xffff0000, v73
	v_lshlrev_b32_e32 v74, 16, v73
	v_and_b32_e32 v73, 0xffff0000, v72
	v_lshlrev_b32_e32 v72, 16, v72
	v_and_b32_e32 v79, 0xffff0000, v77
	v_lshlrev_b32_e32 v78, 16, v77
	v_and_b32_e32 v77, 0xffff0000, v76
	v_lshlrev_b32_e32 v76, 16, v76
	v_add_f32_e32 v140, v76, v72
	v_add_f32_e32 v141, v77, v73
	v_add_f32_e32 v142, v78, v74
	v_add_f32_e32 v143, v79, v75
	v_add_f32_e32 v140, v140, v68
	v_add_f32_e32 v141, v141, v69
	v_add_f32_e32 v142, v142, v70
	v_add_f32_e32 v143, v143, v71
	v_add_f32_e32 v140, v140, v64
; DI float bflo(unsigned u) { return __uint_as_float(u << 16); }
; DI float bfhi(unsigned u) { return __uint_as_float(u & 0xffff0000u); }
; template <int WIN>
; DI void pool_elem(const Params& p, int row, int c) {
;     ...
;     if (t >= WIN - 1) {
;       cnt = (float)WIN;
;       unsigned w[WIN - 1];
; #pragma unroll
;       for (int j = 1; j < WIN; ++j) w[j - 1] = *(const unsigned*)(P2 + (size_t)(row - j) * 2048 + c);
; #pragma unroll
;       for (int j = 1; j < WIN; ++j) { s0 += bflo(w[j - 1]); s1 += bfhi(w[j - 1]); }
;     ...
;   *(unsigned*)(p.MIX + (size_t)row * 1024 + c) = pack2(s0 / cnt - u0, s1 / cnt - u1);
	v_add_f32_e32 v141, v141, v65
	v_add_f32_e32 v142, v142, v66
	v_add_f32_e32 v143, v143, v67
	v_add_f32_e32 v140, v140, v60
	v_add_f32_e32 v141, v141, v61
	v_add_f32_e32 v142, v142, v62
	v_add_f32_e32 v143, v143, v63
	v_add_f32_e32 v140, v140, v56
	v_add_f32_e32 v141, v141, v57
	v_add_f32_e32 v142, v142, v58
	v_add_f32_e32 v143, v143, v59
	v_add_f32_e32 v140, v140, v52
	v_add_f32_e32 v141, v141, v53
	v_add_f32_e32 v142, v142, v54
	v_add_f32_e32 v143, v143, v55
	v_add_f32_e32 v140, v140, v48
	v_add_f32_e32 v141, v141, v49
	v_add_f32_e32 v142, v142, v50
	v_add_f32_e32 v143, v143, v51
	v_add_f32_e32 v140, v140, v44
	v_add_f32_e32 v141, v141, v45
	v_add_f32_e32 v142, v142, v46
	v_add_f32_e32 v143, v143, v47
	v_add_f32_e32 v140, v140, v40
	v_add_f32_e32 v141, v141, v41
	v_add_f32_e32 v142, v142, v42
	v_add_f32_e32 v143, v143, v43
	v_add_f32_e32 v140, v140, v36
	v_add_f32_e32 v141, v141, v37
	v_add_f32_e32 v142, v142, v38
	v_add_f32_e32 v143, v143, v39
	v_add_f32_e32 v140, v140, v32
	v_add_f32_e32 v141, v141, v33
	v_add_f32_e32 v142, v142, v34
	v_add_f32_e32 v143, v143, v35
	v_add_f32_e32 v140, v140, v28
	v_add_f32_e32 v141, v141, v29
	v_add_f32_e32 v142, v142, v30
	v_add_f32_e32 v143, v143, v31
	v_add_f32_e32 v140, v140, v24
	v_add_f32_e32 v141, v141, v25
	v_add_f32_e32 v142, v142, v26
	v_add_f32_e32 v143, v143, v27
	v_add_f32_e32 v140, v140, v20
	v_add_f32_e32 v141, v141, v21
	v_add_f32_e32 v142, v142, v22
	v_add_f32_e32 v143, v143, v23
	v_add_f32_e32 v140, v140, v16
	v_add_f32_e32 v141, v141, v17
	v_add_f32_e32 v142, v142, v18
	v_add_f32_e32 v143, v143, v19
	v_mul_f32_e32 v140, 0x3d800000, v140
	v_mul_f32_e32 v141, 0x3d800000, v141
	v_mul_f32_e32 v142, 0x3d800000, v142
	v_mul_f32_e32 v143, 0x3d800000, v143
	v_sub_f32_e32 v140, v140, v76
	v_sub_f32_e32 v141, v141, v77
	v_sub_f32_e32 v142, v142, v78
	v_sub_f32_e32 v143, v143, v79
	v_cvt_pk_bf16_f32 v152, v140, v141
	v_cvt_pk_bf16_f32 v153, v142, v143
	s_waitcnt vmcnt(14)
	v_and_b32_e32 v83, 0xffff0000, v81
	v_lshlrev_b32_e32 v82, 16, v81
	v_and_b32_e32 v81, 0xffff0000, v80
	v_lshlrev_b32_e32 v80, 16, v80
	v_add_f32_e32 v140, v80, v76
	v_add_f32_e32 v141, v81, v77
	v_add_f32_e32 v142, v82, v78
	v_add_f32_e32 v143, v83, v79
	v_add_f32_e32 v140, v140, v72
	v_add_f32_e32 v141, v141, v73
	v_add_f32_e32 v142, v142, v74
	v_add_f32_e32 v143, v143, v75
	v_add_f32_e32 v140, v140, v68
	v_add_f32_e32 v141, v141, v69
	v_add_f32_e32 v142, v142, v70
	v_add_f32_e32 v143, v143, v71
	v_add_f32_e32 v140, v140, v64
	v_add_f32_e32 v141, v141, v65
	v_add_f32_e32 v142, v142, v66
	v_add_f32_e32 v143, v143, v67
	v_add_f32_e32 v140, v140, v60
	v_add_f32_e32 v141, v141, v61
	v_add_f32_e32 v142, v142, v62
	v_add_f32_e32 v143, v143, v63
	v_add_f32_e32 v140, v140, v56
	v_add_f32_e32 v141, v141, v57
	v_add_f32_e32 v142, v142, v58
	v_add_f32_e32 v143, v143, v59
	v_add_f32_e32 v140, v140, v52
	v_add_f32_e32 v141, v141, v53
	v_add_f32_e32 v142, v142, v54
	v_add_f32_e32 v143, v143, v55
	v_add_f32_e32 v140, v140, v48
	v_add_f32_e32 v141, v141, v49
	v_add_f32_e32 v142, v142, v50
	v_add_f32_e32 v143, v143, v51
	v_add_f32_e32 v140, v140, v44
	v_add_f32_e32 v141, v141, v45
	v_add_f32_e32 v142, v142, v46
	v_add_f32_e32 v143, v143, v47
	v_add_f32_e32 v140, v140, v40
	v_add_f32_e32 v141, v141, v41
	v_add_f32_e32 v142, v142, v42
	v_add_f32_e32 v143, v143, v43
	v_add_f32_e32 v140, v140, v36
	v_add_f32_e32 v141, v141, v37
	v_add_f32_e32 v142, v142, v38
	v_add_f32_e32 v143, v143, v39
	v_add_f32_e32 v140, v140, v32
	v_add_f32_e32 v141, v141, v33
	v_add_f32_e32 v142, v142, v34
	v_add_f32_e32 v143, v143, v35
	v_add_f32_e32 v140, v140, v28
	v_add_f32_e32 v141, v141, v29
	v_add_f32_e32 v142, v142, v30
	v_add_f32_e32 v143, v143, v31
	v_add_f32_e32 v140, v140, v24
	v_add_f32_e32 v141, v141, v25
	v_add_f32_e32 v142, v142, v26
	v_add_f32_e32 v143, v143, v27
	v_add_f32_e32 v140, v140, v20
	v_add_f32_e32 v141, v141, v21
	v_add_f32_e32 v142, v142, v22
	v_add_f32_e32 v143, v143, v23
	v_mul_f32_e32 v140, 0x3d800000, v140
	v_mul_f32_e32 v141, 0x3d800000, v141
	v_mul_f32_e32 v142, 0x3d800000, v142
	v_mul_f32_e32 v143, 0x3d800000, v143
	v_sub_f32_e32 v140, v140, v80
	v_sub_f32_e32 v141, v141, v81
	v_sub_f32_e32 v142, v142, v82
	v_sub_f32_e32 v143, v143, v83
	v_cvt_pk_bf16_f32 v154, v140, v141
	v_cvt_pk_bf16_f32 v155, v142, v143
	s_waitcnt vmcnt(13)
	v_and_b32_e32 v87, 0xffff0000, v85
	v_lshlrev_b32_e32 v86, 16, v85
	v_and_b32_e32 v85, 0xffff0000, v84
	v_lshlrev_b32_e32 v84, 16, v84
	v_add_f32_e32 v140, v84, v80
	v_add_f32_e32 v141, v85, v81
	v_add_f32_e32 v142, v86, v82
	v_add_f32_e32 v143, v87, v83
	v_add_f32_e32 v140, v140, v76
	v_add_f32_e32 v141, v141, v77
	v_add_f32_e32 v142, v142, v78
	v_add_f32_e32 v143, v143, v79
	v_add_f32_e32 v140, v140, v72
	v_add_f32_e32 v141, v141, v73
	v_add_f32_e32 v142, v142, v74
	v_add_f32_e32 v143, v143, v75
	v_add_f32_e32 v140, v140, v68
	v_add_f32_e32 v141, v141, v69
	v_add_f32_e32 v142, v142, v70
	v_add_f32_e32 v143, v143, v71
	v_add_f32_e32 v140, v140, v64
	v_add_f32_e32 v141, v141, v65
	v_add_f32_e32 v142, v142, v66
	v_add_f32_e32 v143, v143, v67
	v_add_f32_e32 v140, v140, v60
	v_add_f32_e32 v141, v141, v61
	v_add_f32_e32 v142, v142, v62
	v_add_f32_e32 v143, v143, v63
	v_add_f32_e32 v140, v140, v56
	v_add_f32_e32 v141, v141, v57
	v_add_f32_e32 v142, v142, v58
	v_add_f32_e32 v143, v143, v59
	v_add_f32_e32 v140, v140, v52
	v_add_f32_e32 v141, v141, v53
	v_add_f32_e32 v142, v142, v54
	v_add_f32_e32 v143, v143, v55
	v_add_f32_e32 v140, v140, v48
	v_add_f32_e32 v141, v141, v49
	v_add_f32_e32 v142, v142, v50
	v_add_f32_e32 v143, v143, v51
	v_add_f32_e32 v140, v140, v44
	v_add_f32_e32 v141, v141, v45
	v_add_f32_e32 v142, v142, v46
	v_add_f32_e32 v143, v143, v47
	v_add_f32_e32 v140, v140, v40
	v_add_f32_e32 v141, v141, v41
	v_add_f32_e32 v142, v142, v42
	v_add_f32_e32 v143, v143, v43
	v_add_f32_e32 v140, v140, v36
	v_add_f32_e32 v141, v141, v37
	v_add_f32_e32 v142, v142, v38
	v_add_f32_e32 v143, v143, v39
	v_add_f32_e32 v140, v140, v32
	v_add_f32_e32 v141, v141, v33
	v_add_f32_e32 v142, v142, v34
	v_add_f32_e32 v143, v143, v35
	v_add_f32_e32 v140, v140, v28
	v_add_f32_e32 v141, v141, v29
	v_add_f32_e32 v142, v142, v30
	v_add_f32_e32 v143, v143, v31
	v_add_f32_e32 v140, v140, v24
	v_add_f32_e32 v141, v141, v25
	v_add_f32_e32 v142, v142, v26
	v_add_f32_e32 v143, v143, v27
	v_mul_f32_e32 v140, 0x3d800000, v140
	v_mul_f32_e32 v141, 0x3d800000, v141
	v_mul_f32_e32 v142, 0x3d800000, v142
	v_mul_f32_e32 v143, 0x3d800000, v143
	v_sub_f32_e32 v140, v140, v84
	v_sub_f32_e32 v141, v141, v85
	v_sub_f32_e32 v142, v142, v86
	v_sub_f32_e32 v143, v143, v87
	v_cvt_pk_bf16_f32 v156, v140, v141
	v_cvt_pk_bf16_f32 v157, v142, v143
	s_waitcnt vmcnt(12)
; DI float bflo(unsigned u) { return __uint_as_float(u << 16); }
; DI float bfhi(unsigned u) { return __uint_as_float(u & 0xffff0000u); }
; template <int WIN>
; DI void pool_elem(const Params& p, int row, int c) {
;     ...
;     if (t >= WIN - 1) {
;       cnt = (float)WIN;
;       unsigned w[WIN - 1];
; #pragma unroll
;       for (int j = 1; j < WIN; ++j) w[j - 1] = *(const unsigned*)(P2 + (size_t)(row - j) * 2048 + c);
; #pragma unroll
;       for (int j = 1; j < WIN; ++j) { s0 += bflo(w[j - 1]); s1 += bfhi(w[j - 1]); }
;     ...
;   *(unsigned*)(p.MIX + (size_t)row * 1024 + c) = pack2(s0 / cnt - u0, s1 / cnt - u1);
	v_and_b32_e32 v91, 0xffff0000, v89
	v_lshlrev_b32_e32 v90, 16, v89
	v_and_b32_e32 v89, 0xffff0000, v88
	v_lshlrev_b32_e32 v88, 16, v88
	v_add_f32_e32 v140, v88, v84
	v_add_f32_e32 v141, v89, v85
	v_add_f32_e32 v142, v90, v86
	v_add_f32_e32 v143, v91, v87
	v_add_f32_e32 v140, v140, v80
	v_add_f32_e32 v141, v141, v81
	v_add_f32_e32 v142, v142, v82
	v_add_f32_e32 v143, v143, v83
	v_add_f32_e32 v140, v140, v76
	v_add_f32_e32 v141, v141, v77
	v_add_f32_e32 v142, v142, v78
	v_add_f32_e32 v143, v143, v79
	v_add_f32_e32 v140, v140, v72
	v_add_f32_e32 v141, v141, v73
	v_add_f32_e32 v142, v142, v74
	v_add_f32_e32 v143, v143, v75
	v_add_f32_e32 v140, v140, v68
	v_add_f32_e32 v141, v141, v69
	v_add_f32_e32 v142, v142, v70
	v_add_f32_e32 v143, v143, v71
	v_add_f32_e32 v140, v140, v64
	v_add_f32_e32 v141, v141, v65
	v_add_f32_e32 v142, v142, v66
	v_add_f32_e32 v143, v143, v67
	v_add_f32_e32 v140, v140, v60
	v_add_f32_e32 v141, v141, v61
	v_add_f32_e32 v142, v142, v62
	v_add_f32_e32 v143, v143, v63
	v_add_f32_e32 v140, v140, v56
	v_add_f32_e32 v141, v141, v57
	v_add_f32_e32 v142, v142, v58
	v_add_f32_e32 v143, v143, v59
	v_add_f32_e32 v140, v140, v52
	v_add_f32_e32 v141, v141, v53
	v_add_f32_e32 v142, v142, v54
	v_add_f32_e32 v143, v143, v55
	v_add_f32_e32 v140, v140, v48
	v_add_f32_e32 v141, v141, v49
	v_add_f32_e32 v142, v142, v50
	v_add_f32_e32 v143, v143, v51
	v_add_f32_e32 v140, v140, v44
	v_add_f32_e32 v141, v141, v45
	v_add_f32_e32 v142, v142, v46
	v_add_f32_e32 v143, v143, v47
	v_add_f32_e32 v140, v140, v40
	v_add_f32_e32 v141, v141, v41
	v_add_f32_e32 v142, v142, v42
	v_add_f32_e32 v143, v143, v43
	v_add_f32_e32 v140, v140, v36
	v_add_f32_e32 v141, v141, v37
	v_add_f32_e32 v142, v142, v38
	v_add_f32_e32 v143, v143, v39
	v_add_f32_e32 v140, v140, v32
	v_add_f32_e32 v141, v141, v33
	v_add_f32_e32 v142, v142, v34
	v_add_f32_e32 v143, v143, v35
	v_add_f32_e32 v140, v140, v28
	v_add_f32_e32 v141, v141, v29
	v_add_f32_e32 v142, v142, v30
	v_add_f32_e32 v143, v143, v31
	v_mul_f32_e32 v140, 0x3d800000, v140
	v_mul_f32_e32 v141, 0x3d800000, v141
	v_mul_f32_e32 v142, 0x3d800000, v142
	v_mul_f32_e32 v143, 0x3d800000, v143
	v_sub_f32_e32 v140, v140, v88
	v_sub_f32_e32 v141, v141, v89
	v_sub_f32_e32 v142, v142, v90
	v_sub_f32_e32 v143, v143, v91
	v_cvt_pk_bf16_f32 v158, v140, v141
	v_cvt_pk_bf16_f32 v159, v142, v143
	s_waitcnt vmcnt(11)
	v_and_b32_e32 v95, 0xffff0000, v93
	v_lshlrev_b32_e32 v94, 16, v93
	v_and_b32_e32 v93, 0xffff0000, v92
	v_lshlrev_b32_e32 v92, 16, v92
	v_add_f32_e32 v140, v92, v88
	v_add_f32_e32 v141, v93, v89
	v_add_f32_e32 v142, v94, v90
	v_add_f32_e32 v143, v95, v91
	v_add_f32_e32 v140, v140, v84
	v_add_f32_e32 v141, v141, v85
	v_add_f32_e32 v142, v142, v86
	v_add_f32_e32 v143, v143, v87
	v_add_f32_e32 v140, v140, v80
	v_add_f32_e32 v141, v141, v81
	v_add_f32_e32 v142, v142, v82
	v_add_f32_e32 v143, v143, v83
	v_add_f32_e32 v140, v140, v76
	v_add_f32_e32 v141, v141, v77
	v_add_f32_e32 v142, v142, v78
	v_add_f32_e32 v143, v143, v79
	v_add_f32_e32 v140, v140, v72
	v_add_f32_e32 v141, v141, v73
	v_add_f32_e32 v142, v142, v74
	v_add_f32_e32 v143, v143, v75
	v_add_f32_e32 v140, v140, v68
	v_add_f32_e32 v141, v141, v69
	v_add_f32_e32 v142, v142, v70
	v_add_f32_e32 v143, v143, v71
	v_add_f32_e32 v140, v140, v64
	v_add_f32_e32 v141, v141, v65
	v_add_f32_e32 v142, v142, v66
	v_add_f32_e32 v143, v143, v67
	v_add_f32_e32 v140, v140, v60
	v_add_f32_e32 v141, v141, v61
	v_add_f32_e32 v142, v142, v62
	v_add_f32_e32 v143, v143, v63
	v_add_f32_e32 v140, v140, v56
	v_add_f32_e32 v141, v141, v57
	v_add_f32_e32 v142, v142, v58
	v_add_f32_e32 v143, v143, v59
	v_add_f32_e32 v140, v140, v52
	v_add_f32_e32 v141, v141, v53
	v_add_f32_e32 v142, v142, v54
	v_add_f32_e32 v143, v143, v55
	v_add_f32_e32 v140, v140, v48
	v_add_f32_e32 v141, v141, v49
	v_add_f32_e32 v142, v142, v50
	v_add_f32_e32 v143, v143, v51
	v_add_f32_e32 v140, v140, v44
	v_add_f32_e32 v141, v141, v45
	v_add_f32_e32 v142, v142, v46
	v_add_f32_e32 v143, v143, v47
	v_add_f32_e32 v140, v140, v40
	v_add_f32_e32 v141, v141, v41
	v_add_f32_e32 v142, v142, v42
	v_add_f32_e32 v143, v143, v43
	v_add_f32_e32 v140, v140, v36
	v_add_f32_e32 v141, v141, v37
	v_add_f32_e32 v142, v142, v38
	v_add_f32_e32 v143, v143, v39
	v_add_f32_e32 v140, v140, v32
	v_add_f32_e32 v141, v141, v33
	v_add_f32_e32 v142, v142, v34
	v_add_f32_e32 v143, v143, v35
	v_mul_f32_e32 v140, 0x3d800000, v140
	v_mul_f32_e32 v141, 0x3d800000, v141
	v_mul_f32_e32 v142, 0x3d800000, v142
	v_mul_f32_e32 v143, 0x3d800000, v143
	v_sub_f32_e32 v140, v140, v92
	v_sub_f32_e32 v141, v141, v93
	v_sub_f32_e32 v142, v142, v94
	v_sub_f32_e32 v143, v143, v95
	v_cvt_pk_bf16_f32 v160, v140, v141
	v_cvt_pk_bf16_f32 v161, v142, v143
	s_waitcnt vmcnt(10)
; DI float bflo(unsigned u) { return __uint_as_float(u << 16); }
; DI float bfhi(unsigned u) { return __uint_as_float(u & 0xffff0000u); }
; template <int WIN>
; DI void pool_elem(const Params& p, int row, int c) {
;     ...
;     if (t >= WIN - 1) {
;       cnt = (float)WIN;
;       unsigned w[WIN - 1];
; #pragma unroll
;       for (int j = 1; j < WIN; ++j) w[j - 1] = *(const unsigned*)(P2 + (size_t)(row - j) * 2048 + c);
; #pragma unroll
;       for (int j = 1; j < WIN; ++j) { s0 += bflo(w[j - 1]); s1 += bfhi(w[j - 1]); }
;     ...
;   *(unsigned*)(p.MIX + (size_t)row * 1024 + c) = pack2(s0 / cnt - u0, s1 / cnt - u1);
	v_and_b32_e32 v99, 0xffff0000, v97
	v_lshlrev_b32_e32 v98, 16, v97
	v_and_b32_e32 v97, 0xffff0000, v96
	v_lshlrev_b32_e32 v96, 16, v96
	v_add_f32_e32 v140, v96, v92
	v_add_f32_e32 v141, v97, v93
	v_add_f32_e32 v142, v98, v94
	v_add_f32_e32 v143, v99, v95
	v_add_f32_e32 v140, v140, v88
	v_add_f32_e32 v141, v141, v89
	v_add_f32_e32 v142, v142, v90
	v_add_f32_e32 v143, v143, v91
	v_add_f32_e32 v140, v140, v84
	v_add_f32_e32 v141, v141, v85
	v_add_f32_e32 v142, v142, v86
	v_add_f32_e32 v143, v143, v87
	v_add_f32_e32 v140, v140, v80
	v_add_f32_e32 v141, v141, v81
	v_add_f32_e32 v142, v142, v82
	v_add_f32_e32 v143, v143, v83
	v_add_f32_e32 v140, v140, v76
	v_add_f32_e32 v141, v141, v77
	v_add_f32_e32 v142, v142, v78
	v_add_f32_e32 v143, v143, v79
	v_add_f32_e32 v140, v140, v72
	v_add_f32_e32 v141, v141, v73
	v_add_f32_e32 v142, v142, v74
	v_add_f32_e32 v143, v143, v75
	v_add_f32_e32 v140, v140, v68
	v_add_f32_e32 v141, v141, v69
	v_add_f32_e32 v142, v142, v70
	v_add_f32_e32 v143, v143, v71
	v_add_f32_e32 v140, v140, v64
	v_add_f32_e32 v141, v141, v65
	v_add_f32_e32 v142, v142, v66
	v_add_f32_e32 v143, v143, v67
	v_add_f32_e32 v140, v140, v60
	v_add_f32_e32 v141, v141, v61
	v_add_f32_e32 v142, v142, v62
	v_add_f32_e32 v143, v143, v63
	v_add_f32_e32 v140, v140, v56
	v_add_f32_e32 v141, v141, v57
	v_add_f32_e32 v142, v142, v58
	v_add_f32_e32 v143, v143, v59
	v_add_f32_e32 v140, v140, v52
	v_add_f32_e32 v141, v141, v53
	v_add_f32_e32 v142, v142, v54
	v_add_f32_e32 v143, v143, v55
	v_add_f32_e32 v140, v140, v48
	v_add_f32_e32 v141, v141, v49
	v_add_f32_e32 v142, v142, v50
	v_add_f32_e32 v143, v143, v51
	v_add_f32_e32 v140, v140, v44
	v_add_f32_e32 v141, v141, v45
	v_add_f32_e32 v142, v142, v46
	v_add_f32_e32 v143, v143, v47
	v_add_f32_e32 v140, v140, v40
	v_add_f32_e32 v141, v141, v41
	v_add_f32_e32 v142, v142, v42
	v_add_f32_e32 v143, v143, v43
	v_add_f32_e32 v140, v140, v36
	v_add_f32_e32 v141, v141, v37
	v_add_f32_e32 v142, v142, v38
	v_add_f32_e32 v143, v143, v39
	v_mul_f32_e32 v140, 0x3d800000, v140
	v_mul_f32_e32 v141, 0x3d800000, v141
	v_mul_f32_e32 v142, 0x3d800000, v142
	v_mul_f32_e32 v143, 0x3d800000, v143
	v_sub_f32_e32 v140, v140, v96
	v_sub_f32_e32 v141, v141, v97
	v_sub_f32_e32 v142, v142, v98
	v_sub_f32_e32 v143, v143, v99
	v_cvt_pk_bf16_f32 v162, v140, v141
	v_cvt_pk_bf16_f32 v163, v142, v143
	s_waitcnt vmcnt(9)
	v_and_b32_e32 v103, 0xffff0000, v101
	v_lshlrev_b32_e32 v102, 16, v101
	v_and_b32_e32 v101, 0xffff0000, v100
	v_lshlrev_b32_e32 v100, 16, v100
	v_add_f32_e32 v140, v100, v96
	v_add_f32_e32 v141, v101, v97
	v_add_f32_e32 v142, v102, v98
	v_add_f32_e32 v143, v103, v99
	v_add_f32_e32 v140, v140, v92
	v_add_f32_e32 v141, v141, v93
	v_add_f32_e32 v142, v142, v94
	v_add_f32_e32 v143, v143, v95
	v_add_f32_e32 v140, v140, v88
	v_add_f32_e32 v141, v141, v89
	v_add_f32_e32 v142, v142, v90
	v_add_f32_e32 v143, v143, v91
	v_add_f32_e32 v140, v140, v84
	v_add_f32_e32 v141, v141, v85
	v_add_f32_e32 v142, v142, v86
	v_add_f32_e32 v143, v143, v87
	v_add_f32_e32 v140, v140, v80
	v_add_f32_e32 v141, v141, v81
	v_add_f32_e32 v142, v142, v82
	v_add_f32_e32 v143, v143, v83
	v_add_f32_e32 v140, v140, v76
	v_add_f32_e32 v141, v141, v77
	v_add_f32_e32 v142, v142, v78
	v_add_f32_e32 v143, v143, v79
	v_add_f32_e32 v140, v140, v72
	v_add_f32_e32 v141, v141, v73
	v_add_f32_e32 v142, v142, v74
	v_add_f32_e32 v143, v143, v75
	v_add_f32_e32 v140, v140, v68
	v_add_f32_e32 v141, v141, v69
	v_add_f32_e32 v142, v142, v70
	v_add_f32_e32 v143, v143, v71
	v_add_f32_e32 v140, v140, v64
	v_add_f32_e32 v141, v141, v65
	v_add_f32_e32 v142, v142, v66
	v_add_f32_e32 v143, v143, v67
	v_add_f32_e32 v140, v140, v60
	v_add_f32_e32 v141, v141, v61
	v_add_f32_e32 v142, v142, v62
	v_add_f32_e32 v143, v143, v63
	v_add_f32_e32 v140, v140, v56
	v_add_f32_e32 v141, v141, v57
	v_add_f32_e32 v142, v142, v58
	v_add_f32_e32 v143, v143, v59
	v_add_f32_e32 v140, v140, v52
	v_add_f32_e32 v141, v141, v53
	v_add_f32_e32 v142, v142, v54
	v_add_f32_e32 v143, v143, v55
	v_add_f32_e32 v140, v140, v48
	v_add_f32_e32 v141, v141, v49
	v_add_f32_e32 v142, v142, v50
	v_add_f32_e32 v143, v143, v51
	v_add_f32_e32 v140, v140, v44
	v_add_f32_e32 v141, v141, v45
	v_add_f32_e32 v142, v142, v46
	v_add_f32_e32 v143, v143, v47
	v_add_f32_e32 v140, v140, v40
	v_add_f32_e32 v141, v141, v41
	v_add_f32_e32 v142, v142, v42
	v_add_f32_e32 v143, v143, v43
	v_mul_f32_e32 v140, 0x3d800000, v140
	v_mul_f32_e32 v141, 0x3d800000, v141
	v_mul_f32_e32 v142, 0x3d800000, v142
	v_mul_f32_e32 v143, 0x3d800000, v143
	v_sub_f32_e32 v140, v140, v100
	v_sub_f32_e32 v141, v141, v101
	v_sub_f32_e32 v142, v142, v102
	v_sub_f32_e32 v143, v143, v103
	v_cvt_pk_bf16_f32 v164, v140, v141
	v_cvt_pk_bf16_f32 v165, v142, v143
	s_waitcnt vmcnt(8)
; DI float bflo(unsigned u) { return __uint_as_float(u << 16); }
; DI float bfhi(unsigned u) { return __uint_as_float(u & 0xffff0000u); }
; template <int WIN>
; DI void pool_elem(const Params& p, int row, int c) {
;     ...
;     if (t >= WIN - 1) {
;       cnt = (float)WIN;
;       unsigned w[WIN - 1];
; #pragma unroll
;       for (int j = 1; j < WIN; ++j) w[j - 1] = *(const unsigned*)(P2 + (size_t)(row - j) * 2048 + c);
; #pragma unroll
;       for (int j = 1; j < WIN; ++j) { s0 += bflo(w[j - 1]); s1 += bfhi(w[j - 1]); }
;     ...
;   *(unsigned*)(p.MIX + (size_t)row * 1024 + c) = pack2(s0 / cnt - u0, s1 / cnt - u1);
	v_and_b32_e32 v107, 0xffff0000, v105
	v_lshlrev_b32_e32 v106, 16, v105
	v_and_b32_e32 v105, 0xffff0000, v104
	v_lshlrev_b32_e32 v104, 16, v104
	v_add_f32_e32 v140, v104, v100
	v_add_f32_e32 v141, v105, v101
	v_add_f32_e32 v142, v106, v102
	v_add_f32_e32 v143, v107, v103
	v_add_f32_e32 v140, v140, v96
	v_add_f32_e32 v141, v141, v97
	v_add_f32_e32 v142, v142, v98
	v_add_f32_e32 v143, v143, v99
	v_add_f32_e32 v140, v140, v92
	v_add_f32_e32 v141, v141, v93
	v_add_f32_e32 v142, v142, v94
	v_add_f32_e32 v143, v143, v95
	v_add_f32_e32 v140, v140, v88
	v_add_f32_e32 v141, v141, v89
	v_add_f32_e32 v142, v142, v90
	v_add_f32_e32 v143, v143, v91
	v_add_f32_e32 v140, v140, v84
	v_add_f32_e32 v141, v141, v85
	v_add_f32_e32 v142, v142, v86
	v_add_f32_e32 v143, v143, v87
	v_add_f32_e32 v140, v140, v80
	v_add_f32_e32 v141, v141, v81
	v_add_f32_e32 v142, v142, v82
	v_add_f32_e32 v143, v143, v83
	v_add_f32_e32 v140, v140, v76
	v_add_f32_e32 v141, v141, v77
	v_add_f32_e32 v142, v142, v78
	v_add_f32_e32 v143, v143, v79
	v_add_f32_e32 v140, v140, v72
	v_add_f32_e32 v141, v141, v73
	v_add_f32_e32 v142, v142, v74
	v_add_f32_e32 v143, v143, v75
	v_add_f32_e32 v140, v140, v68
	v_add_f32_e32 v141, v141, v69
	v_add_f32_e32 v142, v142, v70
	v_add_f32_e32 v143, v143, v71
	v_add_f32_e32 v140, v140, v64
	v_add_f32_e32 v141, v141, v65
	v_add_f32_e32 v142, v142, v66
	v_add_f32_e32 v143, v143, v67
	v_add_f32_e32 v140, v140, v60
	v_add_f32_e32 v141, v141, v61
	v_add_f32_e32 v142, v142, v62
	v_add_f32_e32 v143, v143, v63
	v_add_f32_e32 v140, v140, v56
	v_add_f32_e32 v141, v141, v57
	v_add_f32_e32 v142, v142, v58
	v_add_f32_e32 v143, v143, v59
	v_add_f32_e32 v140, v140, v52
	v_add_f32_e32 v141, v141, v53
	v_add_f32_e32 v142, v142, v54
	v_add_f32_e32 v143, v143, v55
	v_add_f32_e32 v140, v140, v48
	v_add_f32_e32 v141, v141, v49
	v_add_f32_e32 v142, v142, v50
	v_add_f32_e32 v143, v143, v51
	v_add_f32_e32 v140, v140, v44
	v_add_f32_e32 v141, v141, v45
	v_add_f32_e32 v142, v142, v46
	v_add_f32_e32 v143, v143, v47
	v_mul_f32_e32 v140, 0x3d800000, v140
	v_mul_f32_e32 v141, 0x3d800000, v141
	v_mul_f32_e32 v142, 0x3d800000, v142
	v_mul_f32_e32 v143, 0x3d800000, v143
	v_sub_f32_e32 v140, v140, v104
	v_sub_f32_e32 v141, v141, v105
	v_sub_f32_e32 v142, v142, v106
	v_sub_f32_e32 v143, v143, v107
	v_cvt_pk_bf16_f32 v166, v140, v141
	v_cvt_pk_bf16_f32 v167, v142, v143
	s_waitcnt vmcnt(7)
	v_and_b32_e32 v111, 0xffff0000, v109
	v_lshlrev_b32_e32 v110, 16, v109
	v_and_b32_e32 v109, 0xffff0000, v108
	v_lshlrev_b32_e32 v108, 16, v108
	v_add_f32_e32 v140, v108, v104
	v_add_f32_e32 v141, v109, v105
	v_add_f32_e32 v142, v110, v106
	v_add_f32_e32 v143, v111, v107
	v_add_f32_e32 v140, v140, v100
	v_add_f32_e32 v141, v141, v101
	v_add_f32_e32 v142, v142, v102
	v_add_f32_e32 v143, v143, v103
	v_add_f32_e32 v140, v140, v96
	v_add_f32_e32 v141, v141, v97
	v_add_f32_e32 v142, v142, v98
	v_add_f32_e32 v143, v143, v99
	v_add_f32_e32 v140, v140, v92
	v_add_f32_e32 v141, v141, v93
	v_add_f32_e32 v142, v142, v94
	v_add_f32_e32 v143, v143, v95
	v_add_f32_e32 v140, v140, v88
	v_add_f32_e32 v141, v141, v89
	v_add_f32_e32 v142, v142, v90
	v_add_f32_e32 v143, v143, v91
	v_add_f32_e32 v140, v140, v84
	v_add_f32_e32 v141, v141, v85
	v_add_f32_e32 v142, v142, v86
	v_add_f32_e32 v143, v143, v87
	v_add_f32_e32 v140, v140, v80
	v_add_f32_e32 v141, v141, v81
	v_add_f32_e32 v142, v142, v82
	v_add_f32_e32 v143, v143, v83
	v_add_f32_e32 v140, v140, v76
	v_add_f32_e32 v141, v141, v77
	v_add_f32_e32 v142, v142, v78
	v_add_f32_e32 v143, v143, v79
	v_add_f32_e32 v140, v140, v72
	v_add_f32_e32 v141, v141, v73
	v_add_f32_e32 v142, v142, v74
	v_add_f32_e32 v143, v143, v75
	v_add_f32_e32 v140, v140, v68
	v_add_f32_e32 v141, v141, v69
	v_add_f32_e32 v142, v142, v70
	v_add_f32_e32 v143, v143, v71
	v_add_f32_e32 v140, v140, v64
	v_add_f32_e32 v141, v141, v65
	v_add_f32_e32 v142, v142, v66
	v_add_f32_e32 v143, v143, v67
	v_add_f32_e32 v140, v140, v60
	v_add_f32_e32 v141, v141, v61
	v_add_f32_e32 v142, v142, v62
	v_add_f32_e32 v143, v143, v63
	v_add_f32_e32 v140, v140, v56
	v_add_f32_e32 v141, v141, v57
	v_add_f32_e32 v142, v142, v58
	v_add_f32_e32 v143, v143, v59
	v_add_f32_e32 v140, v140, v52
	v_add_f32_e32 v141, v141, v53
	v_add_f32_e32 v142, v142, v54
	v_add_f32_e32 v143, v143, v55
	v_add_f32_e32 v140, v140, v48
	v_add_f32_e32 v141, v141, v49
	v_add_f32_e32 v142, v142, v50
	v_add_f32_e32 v143, v143, v51
	v_mul_f32_e32 v140, 0x3d800000, v140
	v_mul_f32_e32 v141, 0x3d800000, v141
	v_mul_f32_e32 v142, 0x3d800000, v142
	v_mul_f32_e32 v143, 0x3d800000, v143
	v_sub_f32_e32 v140, v140, v108
	v_sub_f32_e32 v141, v141, v109
	v_sub_f32_e32 v142, v142, v110
	v_sub_f32_e32 v143, v143, v111
	v_cvt_pk_bf16_f32 v168, v140, v141
	v_cvt_pk_bf16_f32 v169, v142, v143
	s_waitcnt vmcnt(6)
; DI float bflo(unsigned u) { return __uint_as_float(u << 16); }
; DI float bfhi(unsigned u) { return __uint_as_float(u & 0xffff0000u); }
; template <int WIN>
; DI void pool_elem(const Params& p, int row, int c) {
;     ...
;   unsigned uu = *(const unsigned*)(P2 + (size_t)row * 2048 + c);
;   const float u0 = bflo(uu), u1 = bfhi(uu);
;   float s0 = u0, s1 = u1, cnt;
;   if (row < NPR) {
;     const int t = row & 2047, b = row >> 11;
;     if (t >= WIN - 1) {
;       cnt = (float)WIN;
;       unsigned w[WIN - 1];
; #pragma unroll
;       for (int j = 1; j < WIN; ++j) w[j - 1] = *(const unsigned*)(P2 + (size_t)(row - j) * 2048 + c);
; #pragma unroll
;       for (int j = 1; j < WIN; ++j) { s0 += bflo(w[j - 1]); s1 += bfhi(w[j - 1]); }
;     ...
;   *(unsigned*)(p.MIX + (size_t)row * 1024 + c) = pack2(s0 / cnt - u0, s1 / cnt - u1);
	v_and_b32_e32 v115, 0xffff0000, v113
	v_lshlrev_b32_e32 v114, 16, v113
	v_and_b32_e32 v113, 0xffff0000, v112
	v_lshlrev_b32_e32 v112, 16, v112
	v_add_f32_e32 v140, v112, v108
	v_add_f32_e32 v141, v113, v109
	v_add_f32_e32 v142, v114, v110
	v_add_f32_e32 v143, v115, v111
	v_add_f32_e32 v140, v140, v104
	v_add_f32_e32 v141, v141, v105
	v_add_f32_e32 v142, v142, v106
	v_add_f32_e32 v143, v143, v107
	v_add_f32_e32 v140, v140, v100
	v_add_f32_e32 v141, v141, v101
	v_add_f32_e32 v142, v142, v102
	v_add_f32_e32 v143, v143, v103
	v_add_f32_e32 v140, v140, v96
	v_add_f32_e32 v141, v141, v97
	v_add_f32_e32 v142, v142, v98
	v_add_f32_e32 v143, v143, v99
	v_add_f32_e32 v140, v140, v92
	v_add_f32_e32 v141, v141, v93
	v_add_f32_e32 v142, v142, v94
	v_add_f32_e32 v143, v143, v95
	v_add_f32_e32 v140, v140, v88
	v_add_f32_e32 v141, v141, v89
	v_add_f32_e32 v142, v142, v90
	v_add_f32_e32 v143, v143, v91
	v_add_f32_e32 v140, v140, v84
	v_add_f32_e32 v141, v141, v85
	v_add_f32_e32 v142, v142, v86
	v_add_f32_e32 v143, v143, v87
	v_add_f32_e32 v140, v140, v80
	v_add_f32_e32 v141, v141, v81
	v_add_f32_e32 v142, v142, v82
	v_add_f32_e32 v143, v143, v83
	v_add_f32_e32 v140, v140, v76
	v_add_f32_e32 v141, v141, v77
	v_add_f32_e32 v142, v142, v78
	v_add_f32_e32 v143, v143, v79
	v_add_f32_e32 v140, v140, v72
	v_add_f32_e32 v141, v141, v73
	v_add_f32_e32 v142, v142, v74
	v_add_f32_e32 v143, v143, v75
	v_add_f32_e32 v140, v140, v68
	v_add_f32_e32 v141, v141, v69
	v_add_f32_e32 v142, v142, v70
	v_add_f32_e32 v143, v143, v71
	v_add_f32_e32 v140, v140, v64
	v_add_f32_e32 v141, v141, v65
	v_add_f32_e32 v142, v142, v66
	v_add_f32_e32 v143, v143, v67
	v_add_f32_e32 v140, v140, v60
	v_add_f32_e32 v141, v141, v61
	v_add_f32_e32 v142, v142, v62
	v_add_f32_e32 v143, v143, v63
	v_add_f32_e32 v140, v140, v56
	v_add_f32_e32 v141, v141, v57
	v_add_f32_e32 v142, v142, v58
	v_add_f32_e32 v143, v143, v59
	v_add_f32_e32 v140, v140, v52
	v_add_f32_e32 v141, v141, v53
	v_add_f32_e32 v142, v142, v54
	v_add_f32_e32 v143, v143, v55
	v_mul_f32_e32 v140, 0x3d800000, v140
	v_mul_f32_e32 v141, 0x3d800000, v141
	v_mul_f32_e32 v142, 0x3d800000, v142
	v_mul_f32_e32 v143, 0x3d800000, v143
	v_sub_f32_e32 v140, v140, v112
	v_sub_f32_e32 v141, v141, v113
	v_sub_f32_e32 v142, v142, v114
	v_sub_f32_e32 v143, v143, v115
	v_cvt_pk_bf16_f32 v170, v140, v141
	v_cvt_pk_bf16_f32 v171, v142, v143
	s_waitcnt vmcnt(5)
	v_and_b32_e32 v119, 0xffff0000, v117
	v_lshlrev_b32_e32 v118, 16, v117
	v_and_b32_e32 v117, 0xffff0000, v116
	v_lshlrev_b32_e32 v116, 16, v116
	v_add_f32_e32 v140, v116, v112
	v_add_f32_e32 v141, v117, v113
	v_add_f32_e32 v142, v118, v114
	v_add_f32_e32 v143, v119, v115
	v_add_f32_e32 v140, v140, v108
	v_add_f32_e32 v141, v141, v109
	v_add_f32_e32 v142, v142, v110
	v_add_f32_e32 v143, v143, v111
	v_add_f32_e32 v140, v140, v104
	v_add_f32_e32 v141, v141, v105
	v_add_f32_e32 v142, v142, v106
	v_add_f32_e32 v143, v143, v107
	v_add_f32_e32 v140, v140, v100
	v_add_f32_e32 v141, v141, v101
	v_add_f32_e32 v142, v142, v102
	v_add_f32_e32 v143, v143, v103
	v_add_f32_e32 v140, v140, v96
	v_add_f32_e32 v141, v141, v97
	v_add_f32_e32 v142, v142, v98
	v_add_f32_e32 v143, v143, v99
	v_add_f32_e32 v140, v140, v92
	v_add_f32_e32 v141, v141, v93
	v_add_f32_e32 v142, v142, v94
	v_add_f32_e32 v143, v143, v95
	v_add_f32_e32 v140, v140, v88
	v_add_f32_e32 v141, v141, v89
	v_add_f32_e32 v142, v142, v90
	v_add_f32_e32 v143, v143, v91
	v_add_f32_e32 v140, v140, v84
	v_add_f32_e32 v141, v141, v85
	v_add_f32_e32 v142, v142, v86
	v_add_f32_e32 v143, v143, v87
	v_add_f32_e32 v140, v140, v80
	v_add_f32_e32 v141, v141, v81
	v_add_f32_e32 v142, v142, v82
	v_add_f32_e32 v143, v143, v83
	v_add_f32_e32 v140, v140, v76
	v_add_f32_e32 v141, v141, v77
	v_add_f32_e32 v142, v142, v78
	v_add_f32_e32 v143, v143, v79
	v_add_f32_e32 v140, v140, v72
	v_add_f32_e32 v141, v141, v73
	v_add_f32_e32 v142, v142, v74
	v_add_f32_e32 v143, v143, v75
	v_add_f32_e32 v140, v140, v68
	v_add_f32_e32 v141, v141, v69
	v_add_f32_e32 v142, v142, v70
	v_add_f32_e32 v143, v143, v71
	v_add_f32_e32 v140, v140, v64
	v_add_f32_e32 v141, v141, v65
	v_add_f32_e32 v142, v142, v66
	v_add_f32_e32 v143, v143, v67
	v_add_f32_e32 v140, v140, v60
	v_add_f32_e32 v141, v141, v61
	v_add_f32_e32 v142, v142, v62
	v_add_f32_e32 v143, v143, v63
	v_add_f32_e32 v140, v140, v56
	v_add_f32_e32 v141, v141, v57
	v_add_f32_e32 v142, v142, v58
	v_add_f32_e32 v143, v143, v59
	v_mul_f32_e32 v140, 0x3d800000, v140
	v_mul_f32_e32 v141, 0x3d800000, v141
	v_mul_f32_e32 v142, 0x3d800000, v142
	v_mul_f32_e32 v143, 0x3d800000, v143
	v_sub_f32_e32 v140, v140, v116
	v_sub_f32_e32 v141, v141, v117
	v_sub_f32_e32 v142, v142, v118
	v_sub_f32_e32 v143, v143, v119
	v_cvt_pk_bf16_f32 v172, v140, v141
	v_cvt_pk_bf16_f32 v173, v142, v143
	s_waitcnt vmcnt(4)
; DI float bflo(unsigned u) { return __uint_as_float(u << 16); }
; DI float bfhi(unsigned u) { return __uint_as_float(u & 0xffff0000u); }
; template <int WIN>
; DI void pool_elem(const Params& p, int row, int c) {
;     ...
;   unsigned uu = *(const unsigned*)(P2 + (size_t)row * 2048 + c);
;   const float u0 = bflo(uu), u1 = bfhi(uu);
;   float s0 = u0, s1 = u1, cnt;
;   if (row < NPR) {
;     const int t = row & 2047, b = row >> 11;
;     if (t >= WIN - 1) {
;       cnt = (float)WIN;
;       unsigned w[WIN - 1];
; #pragma unroll
;       for (int j = 1; j < WIN; ++j) w[j - 1] = *(const unsigned*)(P2 + (size_t)(row - j) * 2048 + c);
; #pragma unroll
;       for (int j = 1; j < WIN; ++j) { s0 += bflo(w[j - 1]); s1 += bfhi(w[j - 1]); }
;     ...
;   *(unsigned*)(p.MIX + (size_t)row * 1024 + c) = pack2(s0 / cnt - u0, s1 / cnt - u1);
	v_and_b32_e32 v123, 0xffff0000, v121
	v_lshlrev_b32_e32 v122, 16, v121
	v_and_b32_e32 v121, 0xffff0000, v120
	v_lshlrev_b32_e32 v120, 16, v120
	v_add_f32_e32 v140, v120, v116
	v_add_f32_e32 v141, v121, v117
	v_add_f32_e32 v142, v122, v118
	v_add_f32_e32 v143, v123, v119
	v_add_f32_e32 v140, v140, v112
	v_add_f32_e32 v141, v141, v113
	v_add_f32_e32 v142, v142, v114
	v_add_f32_e32 v143, v143, v115
	v_add_f32_e32 v140, v140, v108
	v_add_f32_e32 v141, v141, v109
	v_add_f32_e32 v142, v142, v110
	v_add_f32_e32 v143, v143, v111
	v_add_f32_e32 v140, v140, v104
	v_add_f32_e32 v141, v141, v105
	v_add_f32_e32 v142, v142, v106
	v_add_f32_e32 v143, v143, v107
	v_add_f32_e32 v140, v140, v100
	v_add_f32_e32 v141, v141, v101
	v_add_f32_e32 v142, v142, v102
	v_add_f32_e32 v143, v143, v103
	v_add_f32_e32 v140, v140, v96
	v_add_f32_e32 v141, v141, v97
	v_add_f32_e32 v142, v142, v98
	v_add_f32_e32 v143, v143, v99
	v_add_f32_e32 v140, v140, v92
	v_add_f32_e32 v141, v141, v93
	v_add_f32_e32 v142, v142, v94
	v_add_f32_e32 v143, v143, v95
	v_add_f32_e32 v140, v140, v88
	v_add_f32_e32 v141, v141, v89
	v_add_f32_e32 v142, v142, v90
	v_add_f32_e32 v143, v143, v91
	v_add_f32_e32 v140, v140, v84
	v_add_f32_e32 v141, v141, v85
	v_add_f32_e32 v142, v142, v86
	v_add_f32_e32 v143, v143, v87
	v_add_f32_e32 v140, v140, v80
	v_add_f32_e32 v141, v141, v81
	v_add_f32_e32 v142, v142, v82
	v_add_f32_e32 v143, v143, v83
	v_add_f32_e32 v140, v140, v76
	v_add_f32_e32 v141, v141, v77
	v_add_f32_e32 v142, v142, v78
	v_add_f32_e32 v143, v143, v79
	v_add_f32_e32 v140, v140, v72
	v_add_f32_e32 v141, v141, v73
	v_add_f32_e32 v142, v142, v74
	v_add_f32_e32 v143, v143, v75
	v_add_f32_e32 v140, v140, v68
	v_add_f32_e32 v141, v141, v69
	v_add_f32_e32 v142, v142, v70
	v_add_f32_e32 v143, v143, v71
	v_add_f32_e32 v140, v140, v64
	v_add_f32_e32 v141, v141, v65
	v_add_f32_e32 v142, v142, v66
	v_add_f32_e32 v143, v143, v67
	v_add_f32_e32 v140, v140, v60
	v_add_f32_e32 v141, v141, v61
	v_add_f32_e32 v142, v142, v62
	v_add_f32_e32 v143, v143, v63
	v_mul_f32_e32 v140, 0x3d800000, v140
	v_mul_f32_e32 v141, 0x3d800000, v141
	v_mul_f32_e32 v142, 0x3d800000, v142
	v_mul_f32_e32 v143, 0x3d800000, v143
	v_sub_f32_e32 v140, v140, v120
	v_sub_f32_e32 v141, v141, v121
	v_sub_f32_e32 v142, v142, v122
	v_sub_f32_e32 v143, v143, v123
	v_cvt_pk_bf16_f32 v174, v140, v141
	v_cvt_pk_bf16_f32 v175, v142, v143
	s_waitcnt vmcnt(3)
	v_and_b32_e32 v127, 0xffff0000, v125
	v_lshlrev_b32_e32 v126, 16, v125
	v_and_b32_e32 v125, 0xffff0000, v124
	v_lshlrev_b32_e32 v124, 16, v124
	v_add_f32_e32 v140, v124, v120
	v_add_f32_e32 v141, v125, v121
	v_add_f32_e32 v142, v126, v122
	v_add_f32_e32 v143, v127, v123
	v_add_f32_e32 v140, v140, v116
	v_add_f32_e32 v141, v141, v117
	v_add_f32_e32 v142, v142, v118
	v_add_f32_e32 v143, v143, v119
	v_add_f32_e32 v140, v140, v112
	v_add_f32_e32 v141, v141, v113
	v_add_f32_e32 v142, v142, v114
	v_add_f32_e32 v143, v143, v115
	v_add_f32_e32 v140, v140, v108
	v_add_f32_e32 v141, v141, v109
	v_add_f32_e32 v142, v142, v110
	v_add_f32_e32 v143, v143, v111
	v_add_f32_e32 v140, v140, v104
	v_add_f32_e32 v141, v141, v105
	v_add_f32_e32 v142, v142, v106
	v_add_f32_e32 v143, v143, v107
	v_add_f32_e32 v140, v140, v100
	v_add_f32_e32 v141, v141, v101
	v_add_f32_e32 v142, v142, v102
	v_add_f32_e32 v143, v143, v103
	v_add_f32_e32 v140, v140, v96
	v_add_f32_e32 v141, v141, v97
	v_add_f32_e32 v142, v142, v98
	v_add_f32_e32 v143, v143, v99
	v_add_f32_e32 v140, v140, v92
	v_add_f32_e32 v141, v141, v93
	v_add_f32_e32 v142, v142, v94
	v_add_f32_e32 v143, v143, v95
	v_add_f32_e32 v140, v140, v88
	v_add_f32_e32 v141, v141, v89
	v_add_f32_e32 v142, v142, v90
	v_add_f32_e32 v143, v143, v91
	v_add_f32_e32 v140, v140, v84
	v_add_f32_e32 v141, v141, v85
	v_add_f32_e32 v142, v142, v86
	v_add_f32_e32 v143, v143, v87
	v_add_f32_e32 v140, v140, v80
	v_add_f32_e32 v141, v141, v81
	v_add_f32_e32 v142, v142, v82
	v_add_f32_e32 v143, v143, v83
	v_add_f32_e32 v140, v140, v76
	v_add_f32_e32 v141, v141, v77
	v_add_f32_e32 v142, v142, v78
	v_add_f32_e32 v143, v143, v79
	v_add_f32_e32 v140, v140, v72
	v_add_f32_e32 v141, v141, v73
	v_add_f32_e32 v142, v142, v74
	v_add_f32_e32 v143, v143, v75
	v_add_f32_e32 v140, v140, v68
	v_add_f32_e32 v141, v141, v69
	v_add_f32_e32 v142, v142, v70
	v_add_f32_e32 v143, v143, v71
	v_add_f32_e32 v140, v140, v64
	v_add_f32_e32 v141, v141, v65
	v_add_f32_e32 v142, v142, v66
	v_add_f32_e32 v143, v143, v67
	v_mul_f32_e32 v140, 0x3d800000, v140
	v_mul_f32_e32 v141, 0x3d800000, v141
	v_mul_f32_e32 v142, 0x3d800000, v142
	v_mul_f32_e32 v143, 0x3d800000, v143
	v_sub_f32_e32 v140, v140, v124
	v_sub_f32_e32 v141, v141, v125
	v_sub_f32_e32 v142, v142, v126
	v_sub_f32_e32 v143, v143, v127
	v_cvt_pk_bf16_f32 v176, v140, v141
	v_cvt_pk_bf16_f32 v177, v142, v143
	s_waitcnt vmcnt(2)
; DI float bflo(unsigned u) { return __uint_as_float(u << 16); }
; DI float bfhi(unsigned u) { return __uint_as_float(u & 0xffff0000u); }
; template <int WIN>
; DI void pool_elem(const Params& p, int row, int c) {
;     ...
;   unsigned uu = *(const unsigned*)(P2 + (size_t)row * 2048 + c);
;   const float u0 = bflo(uu), u1 = bfhi(uu);
;   float s0 = u0, s1 = u1, cnt;
;   if (row < NPR) {
;     const int t = row & 2047, b = row >> 11;
;     if (t >= WIN - 1) {
;       cnt = (float)WIN;
;       unsigned w[WIN - 1];
; #pragma unroll
;       for (int j = 1; j < WIN; ++j) w[j - 1] = *(const unsigned*)(P2 + (size_t)(row - j) * 2048 + c);
; #pragma unroll
;       for (int j = 1; j < WIN; ++j) { s0 += bflo(w[j - 1]); s1 += bfhi(w[j - 1]); }
;     ...
;   *(unsigned*)(p.MIX + (size_t)row * 1024 + c) = pack2(s0 / cnt - u0, s1 / cnt - u1);
	v_and_b32_e32 v131, 0xffff0000, v129
	v_lshlrev_b32_e32 v130, 16, v129
	v_and_b32_e32 v129, 0xffff0000, v128
	v_lshlrev_b32_e32 v128, 16, v128
	v_add_f32_e32 v140, v128, v124
	v_add_f32_e32 v141, v129, v125
	v_add_f32_e32 v142, v130, v126
	v_add_f32_e32 v143, v131, v127
	v_add_f32_e32 v140, v140, v120
	v_add_f32_e32 v141, v141, v121
	v_add_f32_e32 v142, v142, v122
	v_add_f32_e32 v143, v143, v123
	v_add_f32_e32 v140, v140, v116
	v_add_f32_e32 v141, v141, v117
	v_add_f32_e32 v142, v142, v118
	v_add_f32_e32 v143, v143, v119
	v_add_f32_e32 v140, v140, v112
	v_add_f32_e32 v141, v141, v113
	v_add_f32_e32 v142, v142, v114
	v_add_f32_e32 v143, v143, v115
	v_add_f32_e32 v140, v140, v108
	v_add_f32_e32 v141, v141, v109
	v_add_f32_e32 v142, v142, v110
	v_add_f32_e32 v143, v143, v111
	v_add_f32_e32 v140, v140, v104
	v_add_f32_e32 v141, v141, v105
	v_add_f32_e32 v142, v142, v106
	v_add_f32_e32 v143, v143, v107
	v_add_f32_e32 v140, v140, v100
	v_add_f32_e32 v141, v141, v101
	v_add_f32_e32 v142, v142, v102
	v_add_f32_e32 v143, v143, v103
	v_add_f32_e32 v140, v140, v96
	v_add_f32_e32 v141, v141, v97
	v_add_f32_e32 v142, v142, v98
	v_add_f32_e32 v143, v143, v99
	v_add_f32_e32 v140, v140, v92
	v_add_f32_e32 v141, v141, v93
	v_add_f32_e32 v142, v142, v94
	v_add_f32_e32 v143, v143, v95
	v_add_f32_e32 v140, v140, v88
	v_add_f32_e32 v141, v141, v89
	v_add_f32_e32 v142, v142, v90
	v_add_f32_e32 v143, v143, v91
	v_add_f32_e32 v140, v140, v84
	v_add_f32_e32 v141, v141, v85
	v_add_f32_e32 v142, v142, v86
	v_add_f32_e32 v143, v143, v87
	v_add_f32_e32 v140, v140, v80
	v_add_f32_e32 v141, v141, v81
	v_add_f32_e32 v142, v142, v82
	v_add_f32_e32 v143, v143, v83
	v_add_f32_e32 v140, v140, v76
	v_add_f32_e32 v141, v141, v77
	v_add_f32_e32 v142, v142, v78
	v_add_f32_e32 v143, v143, v79
	v_add_f32_e32 v140, v140, v72
	v_add_f32_e32 v141, v141, v73
	v_add_f32_e32 v142, v142, v74
	v_add_f32_e32 v143, v143, v75
	v_add_f32_e32 v140, v140, v68
	v_add_f32_e32 v141, v141, v69
	v_add_f32_e32 v142, v142, v70
	v_add_f32_e32 v143, v143, v71
	v_mul_f32_e32 v140, 0x3d800000, v140
	v_mul_f32_e32 v141, 0x3d800000, v141
	v_mul_f32_e32 v142, 0x3d800000, v142
	v_mul_f32_e32 v143, 0x3d800000, v143
	v_sub_f32_e32 v140, v140, v128
	v_sub_f32_e32 v141, v141, v129
	v_sub_f32_e32 v142, v142, v130
	v_sub_f32_e32 v143, v143, v131
	v_cvt_pk_bf16_f32 v178, v140, v141
	v_cvt_pk_bf16_f32 v179, v142, v143
	s_waitcnt vmcnt(1)
	v_and_b32_e32 v135, 0xffff0000, v133
	v_lshlrev_b32_e32 v134, 16, v133
	v_and_b32_e32 v133, 0xffff0000, v132
	v_lshlrev_b32_e32 v132, 16, v132
	v_add_f32_e32 v140, v132, v128
	v_add_f32_e32 v141, v133, v129
	v_add_f32_e32 v142, v134, v130
	v_add_f32_e32 v143, v135, v131
	v_add_f32_e32 v140, v140, v124
	v_add_f32_e32 v141, v141, v125
	v_add_f32_e32 v142, v142, v126
	v_add_f32_e32 v143, v143, v127
	v_add_f32_e32 v140, v140, v120
	v_add_f32_e32 v141, v141, v121
	v_add_f32_e32 v142, v142, v122
	v_add_f32_e32 v143, v143, v123
	v_add_f32_e32 v140, v140, v116
	v_add_f32_e32 v141, v141, v117
	v_add_f32_e32 v142, v142, v118
	v_add_f32_e32 v143, v143, v119
	v_add_f32_e32 v140, v140, v112
	v_add_f32_e32 v141, v141, v113
	v_add_f32_e32 v142, v142, v114
	v_add_f32_e32 v143, v143, v115
	v_add_f32_e32 v140, v140, v108
	v_add_f32_e32 v141, v141, v109
	v_add_f32_e32 v142, v142, v110
	v_add_f32_e32 v143, v143, v111
	v_add_f32_e32 v140, v140, v104
	v_add_f32_e32 v141, v141, v105
	v_add_f32_e32 v142, v142, v106
	v_add_f32_e32 v143, v143, v107
	v_add_f32_e32 v140, v140, v100
	v_add_f32_e32 v141, v141, v101
	v_add_f32_e32 v142, v142, v102
	v_add_f32_e32 v143, v143, v103
	v_add_f32_e32 v140, v140, v96
	v_add_f32_e32 v141, v141, v97
	v_add_f32_e32 v142, v142, v98
	v_add_f32_e32 v143, v143, v99
	v_add_f32_e32 v140, v140, v92
	v_add_f32_e32 v141, v141, v93
	v_add_f32_e32 v142, v142, v94
	v_add_f32_e32 v143, v143, v95
	v_add_f32_e32 v140, v140, v88
	v_add_f32_e32 v141, v141, v89
	v_add_f32_e32 v142, v142, v90
	v_add_f32_e32 v143, v143, v91
	v_add_f32_e32 v140, v140, v84
	v_add_f32_e32 v141, v141, v85
	v_add_f32_e32 v142, v142, v86
	v_add_f32_e32 v143, v143, v87
	v_add_f32_e32 v140, v140, v80
	v_add_f32_e32 v141, v141, v81
	v_add_f32_e32 v142, v142, v82
	v_add_f32_e32 v143, v143, v83
	v_add_f32_e32 v140, v140, v76
	v_add_f32_e32 v141, v141, v77
	v_add_f32_e32 v142, v142, v78
	v_add_f32_e32 v143, v143, v79
	v_add_f32_e32 v140, v140, v72
	v_add_f32_e32 v141, v141, v73
	v_add_f32_e32 v142, v142, v74
	v_add_f32_e32 v143, v143, v75
	v_mul_f32_e32 v140, 0x3d800000, v140
	v_mul_f32_e32 v141, 0x3d800000, v141
	v_mul_f32_e32 v142, 0x3d800000, v142
	v_mul_f32_e32 v143, 0x3d800000, v143
	v_sub_f32_e32 v140, v140, v132
	v_sub_f32_e32 v141, v141, v133
	v_sub_f32_e32 v142, v142, v134
	v_sub_f32_e32 v143, v143, v135
	v_cvt_pk_bf16_f32 v180, v140, v141
	v_cvt_pk_bf16_f32 v181, v142, v143
	s_waitcnt vmcnt(0)
; DI float bflo(unsigned u) { return __uint_as_float(u << 16); }
; DI float bfhi(unsigned u) { return __uint_as_float(u & 0xffff0000u); }
; template <int WIN>
; DI void pool_elem(const Params& p, int row, int c) {
;     ...
;   unsigned uu = *(const unsigned*)(P2 + (size_t)row * 2048 + c);
;   const float u0 = bflo(uu), u1 = bfhi(uu);
;   float s0 = u0, s1 = u1, cnt;
;   if (row < NPR) {
;     const int t = row & 2047, b = row >> 11;
;     if (t >= WIN - 1) {
;       cnt = (float)WIN;
;       unsigned w[WIN - 1];
; #pragma unroll
;       for (int j = 1; j < WIN; ++j) w[j - 1] = *(const unsigned*)(P2 + (size_t)(row - j) * 2048 + c);
; #pragma unroll
;       for (int j = 1; j < WIN; ++j) { s0 += bflo(w[j - 1]); s1 += bfhi(w[j - 1]); }
;     } else {
;       cnt = (float)(t + 1);
;       for (int j = 1; j <= t; ++j) {
;         unsigned w = *(const unsigned*)(P2 + (size_t)(row - j) * 2048 + c);
;         s0 += bflo(w); s1 += bfhi(w);
;       }
;     }
;     if (t >= 2033) {
;       float2 o = {u0, u1};
;       *(float2*)(p.out + O_POOLP + ((size_t)b * 15 + (t - 2033)) * 1024 + c) = o;
;     }
;     ...
;   *(unsigned*)(p.MIX + (size_t)row * 1024 + c) = pack2(s0 / cnt - u0, s1 / cnt - u1);
	v_and_b32_e32 v139, 0xffff0000, v137
	v_lshlrev_b32_e32 v138, 16, v137
	v_and_b32_e32 v137, 0xffff0000, v136
	v_lshlrev_b32_e32 v136, 16, v136
	v_add_f32_e32 v140, v136, v132
	v_add_f32_e32 v141, v137, v133
	v_add_f32_e32 v142, v138, v134
	v_add_f32_e32 v143, v139, v135
	v_add_f32_e32 v140, v140, v128
	v_add_f32_e32 v141, v141, v129
	v_add_f32_e32 v142, v142, v130
	v_add_f32_e32 v143, v143, v131
	v_add_f32_e32 v140, v140, v124
	v_add_f32_e32 v141, v141, v125
	v_add_f32_e32 v142, v142, v126
	v_add_f32_e32 v143, v143, v127
	v_add_f32_e32 v140, v140, v120
	v_add_f32_e32 v141, v141, v121
	v_add_f32_e32 v142, v142, v122
	v_add_f32_e32 v143, v143, v123
	v_add_f32_e32 v140, v140, v116
	v_add_f32_e32 v141, v141, v117
	v_add_f32_e32 v142, v142, v118
	v_add_f32_e32 v143, v143, v119
	v_add_f32_e32 v140, v140, v112
	v_add_f32_e32 v141, v141, v113
	v_add_f32_e32 v142, v142, v114
	v_add_f32_e32 v143, v143, v115
	v_add_f32_e32 v140, v140, v108
	v_add_f32_e32 v141, v141, v109
	v_add_f32_e32 v142, v142, v110
	v_add_f32_e32 v143, v143, v111
	v_add_f32_e32 v140, v140, v104
	v_add_f32_e32 v141, v141, v105
	v_add_f32_e32 v142, v142, v106
	v_add_f32_e32 v143, v143, v107
	v_add_f32_e32 v140, v140, v100
	v_add_f32_e32 v141, v141, v101
	v_add_f32_e32 v142, v142, v102
	v_add_f32_e32 v143, v143, v103
	v_add_f32_e32 v140, v140, v96
	v_add_f32_e32 v141, v141, v97
	v_add_f32_e32 v142, v142, v98
	v_add_f32_e32 v143, v143, v99
	v_add_f32_e32 v140, v140, v92
	v_add_f32_e32 v141, v141, v93
	v_add_f32_e32 v142, v142, v94
	v_add_f32_e32 v143, v143, v95
	v_add_f32_e32 v140, v140, v88
	v_add_f32_e32 v141, v141, v89
	v_add_f32_e32 v142, v142, v90
	v_add_f32_e32 v143, v143, v91
	v_add_f32_e32 v140, v140, v84
	v_add_f32_e32 v141, v141, v85
	v_add_f32_e32 v142, v142, v86
	v_add_f32_e32 v143, v143, v87
	v_add_f32_e32 v140, v140, v80
	v_add_f32_e32 v141, v141, v81
	v_add_f32_e32 v142, v142, v82
	v_add_f32_e32 v143, v143, v83
	v_add_f32_e32 v140, v140, v76
	v_add_f32_e32 v141, v141, v77
	v_add_f32_e32 v142, v142, v78
	v_add_f32_e32 v143, v143, v79
	v_mul_f32_e32 v140, 0x3d800000, v140
	v_mul_f32_e32 v141, 0x3d800000, v141
	v_mul_f32_e32 v142, 0x3d800000, v142
	v_mul_f32_e32 v143, 0x3d800000, v143
	v_sub_f32_e32 v140, v140, v136
	v_sub_f32_e32 v141, v141, v137
	v_sub_f32_e32 v142, v142, v138
	v_sub_f32_e32 v143, v143, v139
	v_cvt_pk_bf16_f32 v182, v140, v141
	v_cvt_pk_bf16_f32 v183, v142, v143
	global_store_dwordx2 v11, v[152:153], s[24:25]
	s_add_u32 s24, s24, 0x800
	s_addc_u32 s25, s25, 0
	global_store_dwordx2 v11, v[154:155], s[24:25]
	s_add_u32 s24, s24, 0x800
	s_addc_u32 s25, s25, 0
	global_store_dwordx2 v11, v[156:157], s[24:25]
	s_add_u32 s24, s24, 0x800
	s_addc_u32 s25, s25, 0
	global_store_dwordx2 v11, v[158:159], s[24:25]
	s_add_u32 s24, s24, 0x800
	s_addc_u32 s25, s25, 0
	global_store_dwordx2 v11, v[160:161], s[24:25]
	s_add_u32 s24, s24, 0x800
	s_addc_u32 s25, s25, 0
	global_store_dwordx2 v11, v[162:163], s[24:25]
	s_add_u32 s24, s24, 0x800
	s_addc_u32 s25, s25, 0
	global_store_dwordx2 v11, v[164:165], s[24:25]
	s_add_u32 s24, s24, 0x800
	s_addc_u32 s25, s25, 0
	global_store_dwordx2 v11, v[166:167], s[24:25]
	s_add_u32 s24, s24, 0x800
	s_addc_u32 s25, s25, 0
	global_store_dwordx2 v11, v[168:169], s[24:25]
	s_add_u32 s24, s24, 0x800
	s_addc_u32 s25, s25, 0
	global_store_dwordx2 v11, v[170:171], s[24:25]
	s_add_u32 s24, s24, 0x800
	s_addc_u32 s25, s25, 0
	global_store_dwordx2 v11, v[172:173], s[24:25]
	s_add_u32 s24, s24, 0x800
	s_addc_u32 s25, s25, 0
	global_store_dwordx2 v11, v[174:175], s[24:25]
	s_add_u32 s24, s24, 0x800
	s_addc_u32 s25, s25, 0
	global_store_dwordx2 v11, v[176:177], s[24:25]
	s_add_u32 s24, s24, 0x800
	s_addc_u32 s25, s25, 0
	global_store_dwordx2 v11, v[178:179], s[24:25]
	s_add_u32 s24, s24, 0x800
	s_addc_u32 s25, s25, 0
	global_store_dwordx2 v11, v[180:181], s[24:25]
	s_add_u32 s24, s24, 0x800
	s_addc_u32 s25, s25, 0
	global_store_dwordx2 v11, v[182:183], s[24:25]
	s_add_u32 s24, s24, 0x800
	s_addc_u32 s25, s25, 0
	s_cmp_eq_u32 s18, 127
	s_cbranch_scc0 .Lp13f_next
	s_mul_i32 s26, s17, 61440
	s_add_u32 s26, s26, 0x431c000
	s_add_u32 s22, s12, s26
	s_addc_u32 s23, s13, 0
	global_store_dwordx4 v12, v[80:83], s[22:23]
	s_add_u32 s22, s22, 0x1000
	s_addc_u32 s23, s23, 0
	global_store_dwordx4 v12, v[84:87], s[22:23]
	s_add_u32 s22, s22, 0x1000
	s_addc_u32 s23, s23, 0
	global_store_dwordx4 v12, v[88:91], s[22:23]
	s_add_u32 s22, s22, 0x1000
	s_addc_u32 s23, s23, 0
	global_store_dwordx4 v12, v[92:95], s[22:23]
	s_add_u32 s22, s22, 0x1000
	s_addc_u32 s23, s23, 0
	global_store_dwordx4 v12, v[96:99], s[22:23]
	s_add_u32 s22, s22, 0x1000
	s_addc_u32 s23, s23, 0
	global_store_dwordx4 v12, v[100:103], s[22:23]
	s_add_u32 s22, s22, 0x1000
	s_addc_u32 s23, s23, 0
	global_store_dwordx4 v12, v[104:107], s[22:23]
	s_add_u32 s22, s22, 0x1000
	s_addc_u32 s23, s23, 0
	global_store_dwordx4 v12, v[108:111], s[22:23]
	s_add_u32 s22, s22, 0x1000
	s_addc_u32 s23, s23, 0
	global_store_dwordx4 v12, v[112:115], s[22:23]
	s_add_u32 s22, s22, 0x1000
	s_addc_u32 s23, s23, 0
	global_store_dwordx4 v12, v[116:119], s[22:23]
	s_add_u32 s22, s22, 0x1000
	s_addc_u32 s23, s23, 0
	global_store_dwordx4 v12, v[120:123], s[22:23]
	s_add_u32 s22, s22, 0x1000
	s_addc_u32 s23, s23, 0
	global_store_dwordx4 v12, v[124:127], s[22:23]
	s_add_u32 s22, s22, 0x1000
	s_addc_u32 s23, s23, 0
	global_store_dwordx4 v12, v[128:131], s[22:23]
	s_add_u32 s22, s22, 0x1000
	s_addc_u32 s23, s23, 0
	global_store_dwordx4 v12, v[132:135], s[22:23]
	s_add_u32 s22, s22, 0x1000
	s_addc_u32 s23, s23, 0
	global_store_dwordx4 v12, v[136:139], s[22:23]
	s_add_u32 s22, s22, 0x1000
	s_addc_u32 s23, s23, 0
	s_branch .Lp13f_next
; DI float bflo(unsigned u) { return __uint_as_float(u << 16); }
; DI float bfhi(unsigned u) { return __uint_as_float(u & 0xffff0000u); }
; template <int WIN>
; DI void pool_elem(const Params& p, int row, int c) {
;     ...
;   unsigned uu = *(const unsigned*)(P2 + (size_t)row * 2048 + c);
;   const float u0 = bflo(uu), u1 = bfhi(uu);
;   float s0 = u0, s1 = u1, cnt;
;   if (row < NPR) {
;     const int t = row & 2047, b = row >> 11;
;     if (t >= WIN - 1) {
;       cnt = (float)WIN;
;       unsigned w[WIN - 1];
; #pragma unroll
;       for (int j = 1; j < WIN; ++j) w[j - 1] = *(const unsigned*)(P2 + (size_t)(row - j) * 2048 + c);
; #pragma unroll
;       for (int j = 1; j < WIN; ++j) { s0 += bflo(w[j - 1]); s1 += bfhi(w[j - 1]); }
;     } else {
;       cnt = (float)(t + 1);
;       for (int j = 1; j <= t; ++j) {
;         unsigned w = *(const unsigned*)(P2 + (size_t)(row - j) * 2048 + c);
;         s0 += bflo(w); s1 += bfhi(w);
;       }
;     }
;     ...
;   *(unsigned*)(p.MIX + (size_t)row * 1024 + c) = pack2(s0 / cnt - u0, s1 / cnt - u1);
.Lp13f_f0:
	s_sub_u32 s26, s20, 0
	s_lshl_b32 s27, s26, 12
	s_lshr_b32 s28, s26, 20
	s_add_u32 s22, s8, s27
	s_addc_u32 s23, s9, s28
	global_load_dwordx2 v[16:17], v11, s[22:23]
	s_add_u32 s22, s22, 0x1000
	s_addc_u32 s23, s23, 0
	global_load_dwordx2 v[20:21], v11, s[22:23]
	s_add_u32 s22, s22, 0x1000
	s_addc_u32 s23, s23, 0
	global_load_dwordx2 v[24:25], v11, s[22:23]
	s_add_u32 s22, s22, 0x1000
	s_addc_u32 s23, s23, 0
	global_load_dwordx2 v[28:29], v11, s[22:23]
	s_add_u32 s22, s22, 0x1000
	s_addc_u32 s23, s23, 0
	global_load_dwordx2 v[32:33], v11, s[22:23]
	s_add_u32 s22, s22, 0x1000
	s_addc_u32 s23, s23, 0
	global_load_dwordx2 v[36:37], v11, s[22:23]
	s_add_u32 s22, s22, 0x1000
	s_addc_u32 s23, s23, 0
	global_load_dwordx2 v[40:41], v11, s[22:23]
	s_add_u32 s22, s22, 0x1000
	s_addc_u32 s23, s23, 0
	global_load_dwordx2 v[44:45], v11, s[22:23]
	s_add_u32 s22, s22, 0x1000
	s_addc_u32 s23, s23, 0
	global_load_dwordx2 v[48:49], v11, s[22:23]
	s_add_u32 s22, s22, 0x1000
	s_addc_u32 s23, s23, 0
	global_load_dwordx2 v[52:53], v11, s[22:23]
	s_add_u32 s22, s22, 0x1000
	s_addc_u32 s23, s23, 0
	global_load_dwordx2 v[56:57], v11, s[22:23]
	s_add_u32 s22, s22, 0x1000
	s_addc_u32 s23, s23, 0
	global_load_dwordx2 v[60:61], v11, s[22:23]
	s_add_u32 s22, s22, 0x1000
	s_addc_u32 s23, s23, 0
	global_load_dwordx2 v[64:65], v11, s[22:23]
	s_add_u32 s22, s22, 0x1000
	s_addc_u32 s23, s23, 0
	global_load_dwordx2 v[68:69], v11, s[22:23]
	s_add_u32 s22, s22, 0x1000
	s_addc_u32 s23, s23, 0
	global_load_dwordx2 v[72:73], v11, s[22:23]
	s_add_u32 s22, s22, 0x1000
	s_addc_u32 s23, s23, 0
	global_load_dwordx2 v[76:77], v11, s[22:23]
	s_add_u32 s22, s22, 0x1000
	s_addc_u32 s23, s23, 0
	s_waitcnt vmcnt(15)
	v_and_b32_e32 v19, 0xffff0000, v17
	v_lshlrev_b32_e32 v18, 16, v17
	v_and_b32_e32 v17, 0xffff0000, v16
	v_lshlrev_b32_e32 v16, 16, v16
	v_mov_b32_e32 v140, v16
	v_mov_b32_e32 v141, v17
	v_mov_b32_e32 v142, v18
	v_mov_b32_e32 v143, v19
	v_mul_f32_e32 v140, 1.0, v140
	v_mul_f32_e32 v141, 1.0, v141
	v_mul_f32_e32 v142, 1.0, v142
	v_mul_f32_e32 v143, 1.0, v143
	v_sub_f32_e32 v140, v140, v16
	v_sub_f32_e32 v141, v141, v17
	v_sub_f32_e32 v142, v142, v18
	v_sub_f32_e32 v143, v143, v19
	v_cvt_pk_bf16_f32 v152, v140, v141
	v_cvt_pk_bf16_f32 v153, v142, v143
	s_waitcnt vmcnt(14)
	v_and_b32_e32 v23, 0xffff0000, v21
	v_lshlrev_b32_e32 v22, 16, v21
	v_and_b32_e32 v21, 0xffff0000, v20
	v_lshlrev_b32_e32 v20, 16, v20
	v_add_f32_e32 v140, v20, v16
	v_add_f32_e32 v141, v21, v17
	v_add_f32_e32 v142, v22, v18
	v_add_f32_e32 v143, v23, v19
	v_mul_f32_e32 v140, 0.5, v140
	v_mul_f32_e32 v141, 0.5, v141
	v_mul_f32_e32 v142, 0.5, v142
	v_mul_f32_e32 v143, 0.5, v143
	v_sub_f32_e32 v140, v140, v20
	v_sub_f32_e32 v141, v141, v21
	v_sub_f32_e32 v142, v142, v22
	v_sub_f32_e32 v143, v143, v23
	v_cvt_pk_bf16_f32 v154, v140, v141
	v_cvt_pk_bf16_f32 v155, v142, v143
	s_waitcnt vmcnt(13)
	v_and_b32_e32 v27, 0xffff0000, v25
	v_lshlrev_b32_e32 v26, 16, v25
	v_and_b32_e32 v25, 0xffff0000, v24
	v_lshlrev_b32_e32 v24, 16, v24
	v_add_f32_e32 v140, v24, v20
	v_add_f32_e32 v141, v25, v21
	v_add_f32_e32 v142, v26, v22
	v_add_f32_e32 v143, v27, v23
	v_mul_f32_e32 v140, 0.5, v140
	v_mul_f32_e32 v141, 0.5, v141
	v_mul_f32_e32 v142, 0.5, v142
	v_mul_f32_e32 v143, 0.5, v143
	v_sub_f32_e32 v140, v140, v24
	v_sub_f32_e32 v141, v141, v25
	v_sub_f32_e32 v142, v142, v26
	v_sub_f32_e32 v143, v143, v27
	v_cvt_pk_bf16_f32 v156, v140, v141
	v_cvt_pk_bf16_f32 v157, v142, v143
	s_waitcnt vmcnt(12)
	v_and_b32_e32 v31, 0xffff0000, v29
	v_lshlrev_b32_e32 v30, 16, v29
	v_and_b32_e32 v29, 0xffff0000, v28
	v_lshlrev_b32_e32 v28, 16, v28
	v_add_f32_e32 v140, v28, v24
	v_add_f32_e32 v141, v29, v25
	v_add_f32_e32 v142, v30, v26
	v_add_f32_e32 v143, v31, v27
	v_mul_f32_e32 v140, 0.5, v140
	v_mul_f32_e32 v141, 0.5, v141
	v_mul_f32_e32 v142, 0.5, v142
	v_mul_f32_e32 v143, 0.5, v143
	v_sub_f32_e32 v140, v140, v28
	v_sub_f32_e32 v141, v141, v29
	v_sub_f32_e32 v142, v142, v30
	v_sub_f32_e32 v143, v143, v31
	v_cvt_pk_bf16_f32 v158, v140, v141
	v_cvt_pk_bf16_f32 v159, v142, v143
	s_waitcnt vmcnt(11)
	v_and_b32_e32 v35, 0xffff0000, v33
	v_lshlrev_b32_e32 v34, 16, v33
	v_and_b32_e32 v33, 0xffff0000, v32
	v_lshlrev_b32_e32 v32, 16, v32
	v_add_f32_e32 v140, v32, v28
	v_add_f32_e32 v141, v33, v29
	v_add_f32_e32 v142, v34, v30
	v_add_f32_e32 v143, v35, v31
	v_mul_f32_e32 v140, 0.5, v140
	v_mul_f32_e32 v141, 0.5, v141
	v_mul_f32_e32 v142, 0.5, v142
	v_mul_f32_e32 v143, 0.5, v143
	v_sub_f32_e32 v140, v140, v32
	v_sub_f32_e32 v141, v141, v33
	v_sub_f32_e32 v142, v142, v34
	v_sub_f32_e32 v143, v143, v35
	v_cvt_pk_bf16_f32 v160, v140, v141
	v_cvt_pk_bf16_f32 v161, v142, v143
	s_waitcnt vmcnt(10)
	v_and_b32_e32 v39, 0xffff0000, v37
	v_lshlrev_b32_e32 v38, 16, v37
	v_and_b32_e32 v37, 0xffff0000, v36
	v_lshlrev_b32_e32 v36, 16, v36
	v_add_f32_e32 v140, v36, v32
	v_add_f32_e32 v141, v37, v33
	v_add_f32_e32 v142, v38, v34
	v_add_f32_e32 v143, v39, v35
	v_mul_f32_e32 v140, 0.5, v140
	v_mul_f32_e32 v141, 0.5, v141
	v_mul_f32_e32 v142, 0.5, v142
	v_mul_f32_e32 v143, 0.5, v143
	v_sub_f32_e32 v140, v140, v36
	v_sub_f32_e32 v141, v141, v37
	v_sub_f32_e32 v142, v142, v38
	v_sub_f32_e32 v143, v143, v39
	v_cvt_pk_bf16_f32 v162, v140, v141
	v_cvt_pk_bf16_f32 v163, v142, v143
	s_waitcnt vmcnt(9)
	v_and_b32_e32 v43, 0xffff0000, v41
	v_lshlrev_b32_e32 v42, 16, v41
	v_and_b32_e32 v41, 0xffff0000, v40
	v_lshlrev_b32_e32 v40, 16, v40
	v_add_f32_e32 v140, v40, v36
	v_add_f32_e32 v141, v41, v37
	v_add_f32_e32 v142, v42, v38
	v_add_f32_e32 v143, v43, v39
	v_mul_f32_e32 v140, 0.5, v140
	v_mul_f32_e32 v141, 0.5, v141
	v_mul_f32_e32 v142, 0.5, v142
	v_mul_f32_e32 v143, 0.5, v143
	v_sub_f32_e32 v140, v140, v40
	v_sub_f32_e32 v141, v141, v41
	v_sub_f32_e32 v142, v142, v42
	v_sub_f32_e32 v143, v143, v43
	v_cvt_pk_bf16_f32 v164, v140, v141
	v_cvt_pk_bf16_f32 v165, v142, v143
	s_waitcnt vmcnt(8)
; DI float bflo(unsigned u) { return __uint_as_float(u << 16); }
; DI float bfhi(unsigned u) { return __uint_as_float(u & 0xffff0000u); }
; template <int WIN>
; DI void pool_elem(const Params& p, int row, int c) {
;     ...
;   unsigned uu = *(const unsigned*)(P2 + (size_t)row * 2048 + c);
;   const float u0 = bflo(uu), u1 = bfhi(uu);
;   float s0 = u0, s1 = u1, cnt;
;   if (row < NPR) {
;     const int t = row & 2047, b = row >> 11;
;     if (t >= WIN - 1) {
;       cnt = (float)WIN;
;       unsigned w[WIN - 1];
; #pragma unroll
;       for (int j = 1; j < WIN; ++j) w[j - 1] = *(const unsigned*)(P2 + (size_t)(row - j) * 2048 + c);
; #pragma unroll
;       for (int j = 1; j < WIN; ++j) { s0 += bflo(w[j - 1]); s1 += bfhi(w[j - 1]); }
;     } else {
;       cnt = (float)(t + 1);
;       for (int j = 1; j <= t; ++j) {
;         unsigned w = *(const unsigned*)(P2 + (size_t)(row - j) * 2048 + c);
;         s0 += bflo(w); s1 += bfhi(w);
;       }
;     }
;     ...
;   *(unsigned*)(p.MIX + (size_t)row * 1024 + c) = pack2(s0 / cnt - u0, s1 / cnt - u1);
	v_and_b32_e32 v47, 0xffff0000, v45
	v_lshlrev_b32_e32 v46, 16, v45
	v_and_b32_e32 v45, 0xffff0000, v44
	v_lshlrev_b32_e32 v44, 16, v44
	v_add_f32_e32 v140, v44, v40
	v_add_f32_e32 v141, v45, v41
	v_add_f32_e32 v142, v46, v42
	v_add_f32_e32 v143, v47, v43
	v_mul_f32_e32 v140, 0.5, v140
	v_mul_f32_e32 v141, 0.5, v141
	v_mul_f32_e32 v142, 0.5, v142
	v_mul_f32_e32 v143, 0.5, v143
	v_sub_f32_e32 v140, v140, v44
	v_sub_f32_e32 v141, v141, v45
	v_sub_f32_e32 v142, v142, v46
	v_sub_f32_e32 v143, v143, v47
	v_cvt_pk_bf16_f32 v166, v140, v141
	v_cvt_pk_bf16_f32 v167, v142, v143
	s_waitcnt vmcnt(7)
	v_and_b32_e32 v51, 0xffff0000, v49
	v_lshlrev_b32_e32 v50, 16, v49
	v_and_b32_e32 v49, 0xffff0000, v48
	v_lshlrev_b32_e32 v48, 16, v48
	v_add_f32_e32 v140, v48, v44
	v_add_f32_e32 v141, v49, v45
	v_add_f32_e32 v142, v50, v46
	v_add_f32_e32 v143, v51, v47
	v_mul_f32_e32 v140, 0.5, v140
	v_mul_f32_e32 v141, 0.5, v141
	v_mul_f32_e32 v142, 0.5, v142
	v_mul_f32_e32 v143, 0.5, v143
	v_sub_f32_e32 v140, v140, v48
	v_sub_f32_e32 v141, v141, v49
	v_sub_f32_e32 v142, v142, v50
	v_sub_f32_e32 v143, v143, v51
	v_cvt_pk_bf16_f32 v168, v140, v141
	v_cvt_pk_bf16_f32 v169, v142, v143
	s_waitcnt vmcnt(6)
	v_and_b32_e32 v55, 0xffff0000, v53
	v_lshlrev_b32_e32 v54, 16, v53
	v_and_b32_e32 v53, 0xffff0000, v52
	v_lshlrev_b32_e32 v52, 16, v52
	v_add_f32_e32 v140, v52, v48
	v_add_f32_e32 v141, v53, v49
	v_add_f32_e32 v142, v54, v50
	v_add_f32_e32 v143, v55, v51
	v_mul_f32_e32 v140, 0.5, v140
	v_mul_f32_e32 v141, 0.5, v141
	v_mul_f32_e32 v142, 0.5, v142
	v_mul_f32_e32 v143, 0.5, v143
	v_sub_f32_e32 v140, v140, v52
	v_sub_f32_e32 v141, v141, v53
	v_sub_f32_e32 v142, v142, v54
	v_sub_f32_e32 v143, v143, v55
	v_cvt_pk_bf16_f32 v170, v140, v141
	v_cvt_pk_bf16_f32 v171, v142, v143
	s_waitcnt vmcnt(5)
	v_and_b32_e32 v59, 0xffff0000, v57
	v_lshlrev_b32_e32 v58, 16, v57
	v_and_b32_e32 v57, 0xffff0000, v56
	v_lshlrev_b32_e32 v56, 16, v56
	v_add_f32_e32 v140, v56, v52
	v_add_f32_e32 v141, v57, v53
	v_add_f32_e32 v142, v58, v54
	v_add_f32_e32 v143, v59, v55
	v_mul_f32_e32 v140, 0.5, v140
	v_mul_f32_e32 v141, 0.5, v141
	v_mul_f32_e32 v142, 0.5, v142
	v_mul_f32_e32 v143, 0.5, v143
	v_sub_f32_e32 v140, v140, v56
	v_sub_f32_e32 v141, v141, v57
	v_sub_f32_e32 v142, v142, v58
	v_sub_f32_e32 v143, v143, v59
	v_cvt_pk_bf16_f32 v172, v140, v141
	v_cvt_pk_bf16_f32 v173, v142, v143
	s_waitcnt vmcnt(4)
	v_and_b32_e32 v63, 0xffff0000, v61
	v_lshlrev_b32_e32 v62, 16, v61
	v_and_b32_e32 v61, 0xffff0000, v60
	v_lshlrev_b32_e32 v60, 16, v60
	v_add_f32_e32 v140, v60, v56
	v_add_f32_e32 v141, v61, v57
	v_add_f32_e32 v142, v62, v58
	v_add_f32_e32 v143, v63, v59
	v_mul_f32_e32 v140, 0.5, v140
	v_mul_f32_e32 v141, 0.5, v141
	v_mul_f32_e32 v142, 0.5, v142
	v_mul_f32_e32 v143, 0.5, v143
	v_sub_f32_e32 v140, v140, v60
	v_sub_f32_e32 v141, v141, v61
	v_sub_f32_e32 v142, v142, v62
	v_sub_f32_e32 v143, v143, v63
	v_cvt_pk_bf16_f32 v174, v140, v141
	v_cvt_pk_bf16_f32 v175, v142, v143
	s_waitcnt vmcnt(3)
	v_and_b32_e32 v67, 0xffff0000, v65
	v_lshlrev_b32_e32 v66, 16, v65
	v_and_b32_e32 v65, 0xffff0000, v64
	v_lshlrev_b32_e32 v64, 16, v64
	v_add_f32_e32 v140, v64, v60
	v_add_f32_e32 v141, v65, v61
	v_add_f32_e32 v142, v66, v62
	v_add_f32_e32 v143, v67, v63
	v_mul_f32_e32 v140, 0.5, v140
	v_mul_f32_e32 v141, 0.5, v141
	v_mul_f32_e32 v142, 0.5, v142
	v_mul_f32_e32 v143, 0.5, v143
	v_sub_f32_e32 v140, v140, v64
	v_sub_f32_e32 v141, v141, v65
	v_sub_f32_e32 v142, v142, v66
	v_sub_f32_e32 v143, v143, v67
	v_cvt_pk_bf16_f32 v176, v140, v141
	v_cvt_pk_bf16_f32 v177, v142, v143
	s_waitcnt vmcnt(2)
	v_and_b32_e32 v71, 0xffff0000, v69
	v_lshlrev_b32_e32 v70, 16, v69
	v_and_b32_e32 v69, 0xffff0000, v68
	v_lshlrev_b32_e32 v68, 16, v68
	v_add_f32_e32 v140, v68, v64
	v_add_f32_e32 v141, v69, v65
	v_add_f32_e32 v142, v70, v66
	v_add_f32_e32 v143, v71, v67
	v_mul_f32_e32 v140, 0.5, v140
	v_mul_f32_e32 v141, 0.5, v141
	v_mul_f32_e32 v142, 0.5, v142
	v_mul_f32_e32 v143, 0.5, v143
	v_sub_f32_e32 v140, v140, v68
	v_sub_f32_e32 v141, v141, v69
	v_sub_f32_e32 v142, v142, v70
	v_sub_f32_e32 v143, v143, v71
	v_cvt_pk_bf16_f32 v178, v140, v141
	v_cvt_pk_bf16_f32 v179, v142, v143
	s_waitcnt vmcnt(1)
	v_and_b32_e32 v75, 0xffff0000, v73
	v_lshlrev_b32_e32 v74, 16, v73
	v_and_b32_e32 v73, 0xffff0000, v72
	v_lshlrev_b32_e32 v72, 16, v72
	v_add_f32_e32 v140, v72, v68
	v_add_f32_e32 v141, v73, v69
	v_add_f32_e32 v142, v74, v70
	v_add_f32_e32 v143, v75, v71
	v_mul_f32_e32 v140, 0.5, v140
	v_mul_f32_e32 v141, 0.5, v141
	v_mul_f32_e32 v142, 0.5, v142
	v_mul_f32_e32 v143, 0.5, v143
	v_sub_f32_e32 v140, v140, v72
	v_sub_f32_e32 v141, v141, v73
	v_sub_f32_e32 v142, v142, v74
	v_sub_f32_e32 v143, v143, v75
	v_cvt_pk_bf16_f32 v180, v140, v141
	v_cvt_pk_bf16_f32 v181, v142, v143
	s_waitcnt vmcnt(0)
	v_and_b32_e32 v79, 0xffff0000, v77
	v_lshlrev_b32_e32 v78, 16, v77
	v_and_b32_e32 v77, 0xffff0000, v76
	v_lshlrev_b32_e32 v76, 16, v76
	v_add_f32_e32 v140, v76, v72
	v_add_f32_e32 v141, v77, v73
	v_add_f32_e32 v142, v78, v74
	v_add_f32_e32 v143, v79, v75
	v_mul_f32_e32 v140, 0.5, v140
	v_mul_f32_e32 v141, 0.5, v141
	v_mul_f32_e32 v142, 0.5, v142
	v_mul_f32_e32 v143, 0.5, v143
	v_sub_f32_e32 v140, v140, v76
	v_sub_f32_e32 v141, v141, v77
	v_sub_f32_e32 v142, v142, v78
	v_sub_f32_e32 v143, v143, v79
	v_cvt_pk_bf16_f32 v182, v140, v141
	v_cvt_pk_bf16_f32 v183, v142, v143
	global_store_dwordx2 v11, v[152:153], s[24:25]
	s_add_u32 s24, s24, 0x800
	s_addc_u32 s25, s25, 0
	global_store_dwordx2 v11, v[154:155], s[24:25]
	s_add_u32 s24, s24, 0x800
	s_addc_u32 s25, s25, 0
	global_store_dwordx2 v11, v[156:157], s[24:25]
	s_add_u32 s24, s24, 0x800
	s_addc_u32 s25, s25, 0
	global_store_dwordx2 v11, v[158:159], s[24:25]
	s_add_u32 s24, s24, 0x800
	s_addc_u32 s25, s25, 0
	global_store_dwordx2 v11, v[160:161], s[24:25]
	s_add_u32 s24, s24, 0x800
	s_addc_u32 s25, s25, 0
	global_store_dwordx2 v11, v[162:163], s[24:25]
	s_add_u32 s24, s24, 0x800
	s_addc_u32 s25, s25, 0
	global_store_dwordx2 v11, v[164:165], s[24:25]
	s_add_u32 s24, s24, 0x800
	s_addc_u32 s25, s25, 0
	global_store_dwordx2 v11, v[166:167], s[24:25]
	s_add_u32 s24, s24, 0x800
	s_addc_u32 s25, s25, 0
	global_store_dwordx2 v11, v[168:169], s[24:25]
	s_add_u32 s24, s24, 0x800
	s_addc_u32 s25, s25, 0
	global_store_dwordx2 v11, v[170:171], s[24:25]
	s_add_u32 s24, s24, 0x800
	s_addc_u32 s25, s25, 0
	global_store_dwordx2 v11, v[172:173], s[24:25]
	s_add_u32 s24, s24, 0x800
	s_addc_u32 s25, s25, 0
	global_store_dwordx2 v11, v[174:175], s[24:25]
	s_add_u32 s24, s24, 0x800
	s_addc_u32 s25, s25, 0
	global_store_dwordx2 v11, v[176:177], s[24:25]
	s_add_u32 s24, s24, 0x800
	s_addc_u32 s25, s25, 0
	global_store_dwordx2 v11, v[178:179], s[24:25]
	s_add_u32 s24, s24, 0x800
	s_addc_u32 s25, s25, 0
	global_store_dwordx2 v11, v[180:181], s[24:25]
	s_add_u32 s24, s24, 0x800
	s_addc_u32 s25, s25, 0
	global_store_dwordx2 v11, v[182:183], s[24:25]
	s_add_u32 s24, s24, 0x800
	s_addc_u32 s25, s25, 0
	s_branch .Lp13f_next
; DI float bflo(unsigned u) { return __uint_as_float(u << 16); }
; DI float bfhi(unsigned u) { return __uint_as_float(u & 0xffff0000u); }
; template <int WIN>
; DI void pool_elem(const Params& p, int row, int c) {
;     ...
;   unsigned uu = *(const unsigned*)(P2 + (size_t)row * 2048 + c);
;   const float u0 = bflo(uu), u1 = bfhi(uu);
;   float s0 = u0, s1 = u1, cnt;
;   if (row < NPR) {
;     const int t = row & 2047, b = row >> 11;
;     if (t >= WIN - 1) {
;       cnt = (float)WIN;
;       unsigned w[WIN - 1];
; #pragma unroll
;       for (int j = 1; j < WIN; ++j) w[j - 1] = *(const unsigned*)(P2 + (size_t)(row - j) * 2048 + c);
; #pragma unroll
;       for (int j = 1; j < WIN; ++j) { s0 += bflo(w[j - 1]); s1 += bfhi(w[j - 1]); }
;     } else {
;       cnt = (float)(t + 1);
;       for (int j = 1; j <= t; ++j) {
;         unsigned w = *(const unsigned*)(P2 + (size_t)(row - j) * 2048 + c);
;         s0 += bflo(w); s1 += bfhi(w);
;       }
;     }
;     ...
;   *(unsigned*)(p.MIX + (size_t)row * 1024 + c) = pack2(s0 / cnt - u0, s1 / cnt - u1);
.Lp13f_f1:
	s_sub_u32 s26, s20, 0
	s_lshl_b32 s27, s26, 12
	s_lshr_b32 s28, s26, 20
	s_add_u32 s22, s8, s27
	s_addc_u32 s23, s9, s28
	global_load_dwordx2 v[16:17], v11, s[22:23]
	s_add_u32 s22, s22, 0x1000
	s_addc_u32 s23, s23, 0
	global_load_dwordx2 v[20:21], v11, s[22:23]
	s_add_u32 s22, s22, 0x1000
	s_addc_u32 s23, s23, 0
	global_load_dwordx2 v[24:25], v11, s[22:23]
	s_add_u32 s22, s22, 0x1000
	s_addc_u32 s23, s23, 0
	global_load_dwordx2 v[28:29], v11, s[22:23]
	s_add_u32 s22, s22, 0x1000
	s_addc_u32 s23, s23, 0
	global_load_dwordx2 v[32:33], v11, s[22:23]
	s_add_u32 s22, s22, 0x1000
	s_addc_u32 s23, s23, 0
	global_load_dwordx2 v[36:37], v11, s[22:23]
	s_add_u32 s22, s22, 0x1000
	s_addc_u32 s23, s23, 0
	global_load_dwordx2 v[40:41], v11, s[22:23]
	s_add_u32 s22, s22, 0x1000
	s_addc_u32 s23, s23, 0
	global_load_dwordx2 v[44:45], v11, s[22:23]
	s_add_u32 s22, s22, 0x1000
	s_addc_u32 s23, s23, 0
	global_load_dwordx2 v[48:49], v11, s[22:23]
	s_add_u32 s22, s22, 0x1000
	s_addc_u32 s23, s23, 0
	global_load_dwordx2 v[52:53], v11, s[22:23]
	s_add_u32 s22, s22, 0x1000
	s_addc_u32 s23, s23, 0
	global_load_dwordx2 v[56:57], v11, s[22:23]
	s_add_u32 s22, s22, 0x1000
	s_addc_u32 s23, s23, 0
	global_load_dwordx2 v[60:61], v11, s[22:23]
	s_add_u32 s22, s22, 0x1000
	s_addc_u32 s23, s23, 0
	global_load_dwordx2 v[64:65], v11, s[22:23]
	s_add_u32 s22, s22, 0x1000
	s_addc_u32 s23, s23, 0
	global_load_dwordx2 v[68:69], v11, s[22:23]
	s_add_u32 s22, s22, 0x1000
	s_addc_u32 s23, s23, 0
	global_load_dwordx2 v[72:73], v11, s[22:23]
	s_add_u32 s22, s22, 0x1000
	s_addc_u32 s23, s23, 0
	global_load_dwordx2 v[76:77], v11, s[22:23]
	s_add_u32 s22, s22, 0x1000
	s_addc_u32 s23, s23, 0
	s_waitcnt vmcnt(15)
	v_and_b32_e32 v19, 0xffff0000, v17
	v_lshlrev_b32_e32 v18, 16, v17
	v_and_b32_e32 v17, 0xffff0000, v16
	v_lshlrev_b32_e32 v16, 16, v16
	v_mov_b32_e32 v140, v16
	v_mov_b32_e32 v141, v17
	v_mov_b32_e32 v142, v18
	v_mov_b32_e32 v143, v19
	v_mul_f32_e32 v140, 1.0, v140
	v_mul_f32_e32 v141, 1.0, v141
	v_mul_f32_e32 v142, 1.0, v142
	v_mul_f32_e32 v143, 1.0, v143
	v_sub_f32_e32 v140, v140, v16
	v_sub_f32_e32 v141, v141, v17
	v_sub_f32_e32 v142, v142, v18
	v_sub_f32_e32 v143, v143, v19
	v_cvt_pk_bf16_f32 v152, v140, v141
	v_cvt_pk_bf16_f32 v153, v142, v143
	s_waitcnt vmcnt(14)
	v_and_b32_e32 v23, 0xffff0000, v21
	v_lshlrev_b32_e32 v22, 16, v21
	v_and_b32_e32 v21, 0xffff0000, v20
	v_lshlrev_b32_e32 v20, 16, v20
	v_add_f32_e32 v140, v20, v16
	v_add_f32_e32 v141, v21, v17
	v_add_f32_e32 v142, v22, v18
	v_add_f32_e32 v143, v23, v19
	v_mul_f32_e32 v140, 0.5, v140
	v_mul_f32_e32 v141, 0.5, v141
	v_mul_f32_e32 v142, 0.5, v142
	v_mul_f32_e32 v143, 0.5, v143
	v_sub_f32_e32 v140, v140, v20
	v_sub_f32_e32 v141, v141, v21
	v_sub_f32_e32 v142, v142, v22
	v_sub_f32_e32 v143, v143, v23
	v_cvt_pk_bf16_f32 v154, v140, v141
	v_cvt_pk_bf16_f32 v155, v142, v143
	s_waitcnt vmcnt(13)
	v_and_b32_e32 v27, 0xffff0000, v25
	v_lshlrev_b32_e32 v26, 16, v25
	v_and_b32_e32 v25, 0xffff0000, v24
	v_lshlrev_b32_e32 v24, 16, v24
	v_add_f32_e32 v140, v24, v20
	v_add_f32_e32 v141, v25, v21
	v_add_f32_e32 v142, v26, v22
	v_add_f32_e32 v143, v27, v23
	v_add_f32_e32 v140, v140, v16
	v_add_f32_e32 v141, v141, v17
	v_add_f32_e32 v142, v142, v18
	v_add_f32_e32 v143, v143, v19
	v_mov_b32_e32 v151, 0x40400000
	v_div_scale_f32 v146, s[26:27], v151, v151, v140
	v_rcp_f32_e32 v147, v146
	v_div_scale_f32 v148, vcc, v140, v151, v140
	v_fma_f32 v149, -v146, v147, 1.0
	v_fmac_f32_e32 v147, v149, v147
	v_mul_f32_e32 v149, v148, v147
	v_fma_f32 v150, -v146, v149, v148
	v_fmac_f32_e32 v149, v150, v147
	v_fma_f32 v146, -v146, v149, v148
	v_div_fmas_f32 v146, v146, v147, v149
	v_div_fixup_f32 v140, v146, v151, v140
	v_mov_b32_e32 v151, 0x40400000
	v_div_scale_f32 v146, s[26:27], v151, v151, v141
	v_rcp_f32_e32 v147, v146
	v_div_scale_f32 v148, vcc, v141, v151, v141
	v_fma_f32 v149, -v146, v147, 1.0
	v_fmac_f32_e32 v147, v149, v147
	v_mul_f32_e32 v149, v148, v147
	v_fma_f32 v150, -v146, v149, v148
	v_fmac_f32_e32 v149, v150, v147
	v_fma_f32 v146, -v146, v149, v148
	v_div_fmas_f32 v146, v146, v147, v149
	v_div_fixup_f32 v141, v146, v151, v141
	v_mov_b32_e32 v151, 0x40400000
	v_div_scale_f32 v146, s[26:27], v151, v151, v142
	v_rcp_f32_e32 v147, v146
	v_div_scale_f32 v148, vcc, v142, v151, v142
	v_fma_f32 v149, -v146, v147, 1.0
	v_fmac_f32_e32 v147, v149, v147
	v_mul_f32_e32 v149, v148, v147
	v_fma_f32 v150, -v146, v149, v148
	v_fmac_f32_e32 v149, v150, v147
	v_fma_f32 v146, -v146, v149, v148
	v_div_fmas_f32 v146, v146, v147, v149
	v_div_fixup_f32 v142, v146, v151, v142
	v_mov_b32_e32 v151, 0x40400000
	v_div_scale_f32 v146, s[26:27], v151, v151, v143
	v_rcp_f32_e32 v147, v146
	v_div_scale_f32 v148, vcc, v143, v151, v143
	v_fma_f32 v149, -v146, v147, 1.0
	v_fmac_f32_e32 v147, v149, v147
	v_mul_f32_e32 v149, v148, v147
	v_fma_f32 v150, -v146, v149, v148
	v_fmac_f32_e32 v149, v150, v147
	v_fma_f32 v146, -v146, v149, v148
	v_div_fmas_f32 v146, v146, v147, v149
	v_div_fixup_f32 v143, v146, v151, v143
	v_sub_f32_e32 v140, v140, v24
	v_sub_f32_e32 v141, v141, v25
	v_sub_f32_e32 v142, v142, v26
	v_sub_f32_e32 v143, v143, v27
	v_cvt_pk_bf16_f32 v156, v140, v141
	v_cvt_pk_bf16_f32 v157, v142, v143
	s_waitcnt vmcnt(12)
; DI float bflo(unsigned u) { return __uint_as_float(u << 16); }
; DI float bfhi(unsigned u) { return __uint_as_float(u & 0xffff0000u); }
; template <int WIN>
; DI void pool_elem(const Params& p, int row, int c) {
;     ...
;   unsigned uu = *(const unsigned*)(P2 + (size_t)row * 2048 + c);
;   const float u0 = bflo(uu), u1 = bfhi(uu);
;   float s0 = u0, s1 = u1, cnt;
;   if (row < NPR) {
;     const int t = row & 2047, b = row >> 11;
;     if (t >= WIN - 1) {
;       cnt = (float)WIN;
;       unsigned w[WIN - 1];
; #pragma unroll
;       for (int j = 1; j < WIN; ++j) w[j - 1] = *(const unsigned*)(P2 + (size_t)(row - j) * 2048 + c);
; #pragma unroll
;       for (int j = 1; j < WIN; ++j) { s0 += bflo(w[j - 1]); s1 += bfhi(w[j - 1]); }
;     ...
;   *(unsigned*)(p.MIX + (size_t)row * 1024 + c) = pack2(s0 / cnt - u0, s1 / cnt - u1);
	v_and_b32_e32 v31, 0xffff0000, v29
	v_lshlrev_b32_e32 v30, 16, v29
	v_and_b32_e32 v29, 0xffff0000, v28
	v_lshlrev_b32_e32 v28, 16, v28
	v_add_f32_e32 v140, v28, v24
	v_add_f32_e32 v141, v29, v25
	v_add_f32_e32 v142, v30, v26
	v_add_f32_e32 v143, v31, v27
	v_add_f32_e32 v140, v140, v20
	v_add_f32_e32 v141, v141, v21
	v_add_f32_e32 v142, v142, v22
	v_add_f32_e32 v143, v143, v23
	v_add_f32_e32 v140, v140, v16
	v_add_f32_e32 v141, v141, v17
	v_add_f32_e32 v142, v142, v18
	v_add_f32_e32 v143, v143, v19
	v_mul_f32_e32 v140, 0x3e800000, v140
	v_mul_f32_e32 v141, 0x3e800000, v141
	v_mul_f32_e32 v142, 0x3e800000, v142
	v_mul_f32_e32 v143, 0x3e800000, v143
	v_sub_f32_e32 v140, v140, v28
	v_sub_f32_e32 v141, v141, v29
	v_sub_f32_e32 v142, v142, v30
	v_sub_f32_e32 v143, v143, v31
	v_cvt_pk_bf16_f32 v158, v140, v141
	v_cvt_pk_bf16_f32 v159, v142, v143
	s_waitcnt vmcnt(11)
	v_and_b32_e32 v35, 0xffff0000, v33
	v_lshlrev_b32_e32 v34, 16, v33
	v_and_b32_e32 v33, 0xffff0000, v32
	v_lshlrev_b32_e32 v32, 16, v32
	v_add_f32_e32 v140, v32, v28
	v_add_f32_e32 v141, v33, v29
	v_add_f32_e32 v142, v34, v30
	v_add_f32_e32 v143, v35, v31
	v_add_f32_e32 v140, v140, v24
	v_add_f32_e32 v141, v141, v25
	v_add_f32_e32 v142, v142, v26
	v_add_f32_e32 v143, v143, v27
	v_add_f32_e32 v140, v140, v20
	v_add_f32_e32 v141, v141, v21
	v_add_f32_e32 v142, v142, v22
	v_add_f32_e32 v143, v143, v23
	v_mul_f32_e32 v140, 0x3e800000, v140
	v_mul_f32_e32 v141, 0x3e800000, v141
	v_mul_f32_e32 v142, 0x3e800000, v142
	v_mul_f32_e32 v143, 0x3e800000, v143
	v_sub_f32_e32 v140, v140, v32
	v_sub_f32_e32 v141, v141, v33
	v_sub_f32_e32 v142, v142, v34
	v_sub_f32_e32 v143, v143, v35
	v_cvt_pk_bf16_f32 v160, v140, v141
	v_cvt_pk_bf16_f32 v161, v142, v143
	s_waitcnt vmcnt(10)
	v_and_b32_e32 v39, 0xffff0000, v37
	v_lshlrev_b32_e32 v38, 16, v37
	v_and_b32_e32 v37, 0xffff0000, v36
	v_lshlrev_b32_e32 v36, 16, v36
	v_add_f32_e32 v140, v36, v32
	v_add_f32_e32 v141, v37, v33
	v_add_f32_e32 v142, v38, v34
	v_add_f32_e32 v143, v39, v35
	v_add_f32_e32 v140, v140, v28
	v_add_f32_e32 v141, v141, v29
	v_add_f32_e32 v142, v142, v30
	v_add_f32_e32 v143, v143, v31
	v_add_f32_e32 v140, v140, v24
	v_add_f32_e32 v141, v141, v25
	v_add_f32_e32 v142, v142, v26
	v_add_f32_e32 v143, v143, v27
	v_mul_f32_e32 v140, 0x3e800000, v140
	v_mul_f32_e32 v141, 0x3e800000, v141
	v_mul_f32_e32 v142, 0x3e800000, v142
	v_mul_f32_e32 v143, 0x3e800000, v143
	v_sub_f32_e32 v140, v140, v36
	v_sub_f32_e32 v141, v141, v37
	v_sub_f32_e32 v142, v142, v38
	v_sub_f32_e32 v143, v143, v39
	v_cvt_pk_bf16_f32 v162, v140, v141
	v_cvt_pk_bf16_f32 v163, v142, v143
	s_waitcnt vmcnt(9)
	v_and_b32_e32 v43, 0xffff0000, v41
	v_lshlrev_b32_e32 v42, 16, v41
	v_and_b32_e32 v41, 0xffff0000, v40
	v_lshlrev_b32_e32 v40, 16, v40
	v_add_f32_e32 v140, v40, v36
	v_add_f32_e32 v141, v41, v37
	v_add_f32_e32 v142, v42, v38
	v_add_f32_e32 v143, v43, v39
	v_add_f32_e32 v140, v140, v32
	v_add_f32_e32 v141, v141, v33
	v_add_f32_e32 v142, v142, v34
	v_add_f32_e32 v143, v143, v35
	v_add_f32_e32 v140, v140, v28
	v_add_f32_e32 v141, v141, v29
	v_add_f32_e32 v142, v142, v30
	v_add_f32_e32 v143, v143, v31
	v_mul_f32_e32 v140, 0x3e800000, v140
	v_mul_f32_e32 v141, 0x3e800000, v141
	v_mul_f32_e32 v142, 0x3e800000, v142
	v_mul_f32_e32 v143, 0x3e800000, v143
	v_sub_f32_e32 v140, v140, v40
	v_sub_f32_e32 v141, v141, v41
	v_sub_f32_e32 v142, v142, v42
	v_sub_f32_e32 v143, v143, v43
	v_cvt_pk_bf16_f32 v164, v140, v141
	v_cvt_pk_bf16_f32 v165, v142, v143
	s_waitcnt vmcnt(8)
	v_and_b32_e32 v47, 0xffff0000, v45
	v_lshlrev_b32_e32 v46, 16, v45
	v_and_b32_e32 v45, 0xffff0000, v44
	v_lshlrev_b32_e32 v44, 16, v44
	v_add_f32_e32 v140, v44, v40
	v_add_f32_e32 v141, v45, v41
	v_add_f32_e32 v142, v46, v42
	v_add_f32_e32 v143, v47, v43
	v_add_f32_e32 v140, v140, v36
	v_add_f32_e32 v141, v141, v37
	v_add_f32_e32 v142, v142, v38
	v_add_f32_e32 v143, v143, v39
	v_add_f32_e32 v140, v140, v32
	v_add_f32_e32 v141, v141, v33
	v_add_f32_e32 v142, v142, v34
	v_add_f32_e32 v143, v143, v35
	v_mul_f32_e32 v140, 0x3e800000, v140
	v_mul_f32_e32 v141, 0x3e800000, v141
	v_mul_f32_e32 v142, 0x3e800000, v142
	v_mul_f32_e32 v143, 0x3e800000, v143
	v_sub_f32_e32 v140, v140, v44
	v_sub_f32_e32 v141, v141, v45
	v_sub_f32_e32 v142, v142, v46
	v_sub_f32_e32 v143, v143, v47
	v_cvt_pk_bf16_f32 v166, v140, v141
	v_cvt_pk_bf16_f32 v167, v142, v143
	s_waitcnt vmcnt(7)
	v_and_b32_e32 v51, 0xffff0000, v49
	v_lshlrev_b32_e32 v50, 16, v49
	v_and_b32_e32 v49, 0xffff0000, v48
	v_lshlrev_b32_e32 v48, 16, v48
	v_add_f32_e32 v140, v48, v44
	v_add_f32_e32 v141, v49, v45
	v_add_f32_e32 v142, v50, v46
	v_add_f32_e32 v143, v51, v47
	v_add_f32_e32 v140, v140, v40
	v_add_f32_e32 v141, v141, v41
	v_add_f32_e32 v142, v142, v42
	v_add_f32_e32 v143, v143, v43
	v_add_f32_e32 v140, v140, v36
	v_add_f32_e32 v141, v141, v37
	v_add_f32_e32 v142, v142, v38
	v_add_f32_e32 v143, v143, v39
	v_mul_f32_e32 v140, 0x3e800000, v140
	v_mul_f32_e32 v141, 0x3e800000, v141
	v_mul_f32_e32 v142, 0x3e800000, v142
	v_mul_f32_e32 v143, 0x3e800000, v143
	v_sub_f32_e32 v140, v140, v48
	v_sub_f32_e32 v141, v141, v49
	v_sub_f32_e32 v142, v142, v50
	v_sub_f32_e32 v143, v143, v51
	v_cvt_pk_bf16_f32 v168, v140, v141
	v_cvt_pk_bf16_f32 v169, v142, v143
	s_waitcnt vmcnt(6)
; DI float bflo(unsigned u) { return __uint_as_float(u << 16); }
; DI float bfhi(unsigned u) { return __uint_as_float(u & 0xffff0000u); }
; template <int WIN>
; DI void pool_elem(const Params& p, int row, int c) {
;     ...
;   unsigned uu = *(const unsigned*)(P2 + (size_t)row * 2048 + c);
;   const float u0 = bflo(uu), u1 = bfhi(uu);
;   float s0 = u0, s1 = u1, cnt;
;   if (row < NPR) {
;     const int t = row & 2047, b = row >> 11;
;     if (t >= WIN - 1) {
;       cnt = (float)WIN;
;       unsigned w[WIN - 1];
; #pragma unroll
;       for (int j = 1; j < WIN; ++j) w[j - 1] = *(const unsigned*)(P2 + (size_t)(row - j) * 2048 + c);
; #pragma unroll
;       for (int j = 1; j < WIN; ++j) { s0 += bflo(w[j - 1]); s1 += bfhi(w[j - 1]); }
;     ...
;   *(unsigned*)(p.MIX + (size_t)row * 1024 + c) = pack2(s0 / cnt - u0, s1 / cnt - u1);
	v_and_b32_e32 v55, 0xffff0000, v53
	v_lshlrev_b32_e32 v54, 16, v53
	v_and_b32_e32 v53, 0xffff0000, v52
	v_lshlrev_b32_e32 v52, 16, v52
	v_add_f32_e32 v140, v52, v48
	v_add_f32_e32 v141, v53, v49
	v_add_f32_e32 v142, v54, v50
	v_add_f32_e32 v143, v55, v51
	v_add_f32_e32 v140, v140, v44
	v_add_f32_e32 v141, v141, v45
	v_add_f32_e32 v142, v142, v46
	v_add_f32_e32 v143, v143, v47
	v_add_f32_e32 v140, v140, v40
	v_add_f32_e32 v141, v141, v41
	v_add_f32_e32 v142, v142, v42
	v_add_f32_e32 v143, v143, v43
	v_mul_f32_e32 v140, 0x3e800000, v140
	v_mul_f32_e32 v141, 0x3e800000, v141
	v_mul_f32_e32 v142, 0x3e800000, v142
	v_mul_f32_e32 v143, 0x3e800000, v143
	v_sub_f32_e32 v140, v140, v52
	v_sub_f32_e32 v141, v141, v53
	v_sub_f32_e32 v142, v142, v54
	v_sub_f32_e32 v143, v143, v55
	v_cvt_pk_bf16_f32 v170, v140, v141
	v_cvt_pk_bf16_f32 v171, v142, v143
	s_waitcnt vmcnt(5)
	v_and_b32_e32 v59, 0xffff0000, v57
	v_lshlrev_b32_e32 v58, 16, v57
	v_and_b32_e32 v57, 0xffff0000, v56
	v_lshlrev_b32_e32 v56, 16, v56
	v_add_f32_e32 v140, v56, v52
	v_add_f32_e32 v141, v57, v53
	v_add_f32_e32 v142, v58, v54
	v_add_f32_e32 v143, v59, v55
	v_add_f32_e32 v140, v140, v48
	v_add_f32_e32 v141, v141, v49
	v_add_f32_e32 v142, v142, v50
	v_add_f32_e32 v143, v143, v51
	v_add_f32_e32 v140, v140, v44
	v_add_f32_e32 v141, v141, v45
	v_add_f32_e32 v142, v142, v46
	v_add_f32_e32 v143, v143, v47
	v_mul_f32_e32 v140, 0x3e800000, v140
	v_mul_f32_e32 v141, 0x3e800000, v141
	v_mul_f32_e32 v142, 0x3e800000, v142
	v_mul_f32_e32 v143, 0x3e800000, v143
	v_sub_f32_e32 v140, v140, v56
	v_sub_f32_e32 v141, v141, v57
	v_sub_f32_e32 v142, v142, v58
	v_sub_f32_e32 v143, v143, v59
	v_cvt_pk_bf16_f32 v172, v140, v141
	v_cvt_pk_bf16_f32 v173, v142, v143
	s_waitcnt vmcnt(4)
	v_and_b32_e32 v63, 0xffff0000, v61
	v_lshlrev_b32_e32 v62, 16, v61
	v_and_b32_e32 v61, 0xffff0000, v60
	v_lshlrev_b32_e32 v60, 16, v60
	v_add_f32_e32 v140, v60, v56
	v_add_f32_e32 v141, v61, v57
	v_add_f32_e32 v142, v62, v58
	v_add_f32_e32 v143, v63, v59
	v_add_f32_e32 v140, v140, v52
	v_add_f32_e32 v141, v141, v53
	v_add_f32_e32 v142, v142, v54
	v_add_f32_e32 v143, v143, v55
	v_add_f32_e32 v140, v140, v48
	v_add_f32_e32 v141, v141, v49
	v_add_f32_e32 v142, v142, v50
	v_add_f32_e32 v143, v143, v51
	v_mul_f32_e32 v140, 0x3e800000, v140
	v_mul_f32_e32 v141, 0x3e800000, v141
	v_mul_f32_e32 v142, 0x3e800000, v142
	v_mul_f32_e32 v143, 0x3e800000, v143
	v_sub_f32_e32 v140, v140, v60
	v_sub_f32_e32 v141, v141, v61
	v_sub_f32_e32 v142, v142, v62
	v_sub_f32_e32 v143, v143, v63
	v_cvt_pk_bf16_f32 v174, v140, v141
	v_cvt_pk_bf16_f32 v175, v142, v143
	s_waitcnt vmcnt(3)
	v_and_b32_e32 v67, 0xffff0000, v65
	v_lshlrev_b32_e32 v66, 16, v65
	v_and_b32_e32 v65, 0xffff0000, v64
	v_lshlrev_b32_e32 v64, 16, v64
	v_add_f32_e32 v140, v64, v60
	v_add_f32_e32 v141, v65, v61
	v_add_f32_e32 v142, v66, v62
	v_add_f32_e32 v143, v67, v63
	v_add_f32_e32 v140, v140, v56
	v_add_f32_e32 v141, v141, v57
	v_add_f32_e32 v142, v142, v58
	v_add_f32_e32 v143, v143, v59
	v_add_f32_e32 v140, v140, v52
	v_add_f32_e32 v141, v141, v53
	v_add_f32_e32 v142, v142, v54
	v_add_f32_e32 v143, v143, v55
	v_mul_f32_e32 v140, 0x3e800000, v140
	v_mul_f32_e32 v141, 0x3e800000, v141
	v_mul_f32_e32 v142, 0x3e800000, v142
	v_mul_f32_e32 v143, 0x3e800000, v143
	v_sub_f32_e32 v140, v140, v64
	v_sub_f32_e32 v141, v141, v65
	v_sub_f32_e32 v142, v142, v66
	v_sub_f32_e32 v143, v143, v67
	v_cvt_pk_bf16_f32 v176, v140, v141
	v_cvt_pk_bf16_f32 v177, v142, v143
	s_waitcnt vmcnt(2)
	v_and_b32_e32 v71, 0xffff0000, v69
	v_lshlrev_b32_e32 v70, 16, v69
	v_and_b32_e32 v69, 0xffff0000, v68
	v_lshlrev_b32_e32 v68, 16, v68
	v_add_f32_e32 v140, v68, v64
	v_add_f32_e32 v141, v69, v65
	v_add_f32_e32 v142, v70, v66
	v_add_f32_e32 v143, v71, v67
	v_add_f32_e32 v140, v140, v60
	v_add_f32_e32 v141, v141, v61
	v_add_f32_e32 v142, v142, v62
	v_add_f32_e32 v143, v143, v63
	v_add_f32_e32 v140, v140, v56
	v_add_f32_e32 v141, v141, v57
	v_add_f32_e32 v142, v142, v58
	v_add_f32_e32 v143, v143, v59
	v_mul_f32_e32 v140, 0x3e800000, v140
	v_mul_f32_e32 v141, 0x3e800000, v141
	v_mul_f32_e32 v142, 0x3e800000, v142
	v_mul_f32_e32 v143, 0x3e800000, v143
	v_sub_f32_e32 v140, v140, v68
	v_sub_f32_e32 v141, v141, v69
	v_sub_f32_e32 v142, v142, v70
	v_sub_f32_e32 v143, v143, v71
	v_cvt_pk_bf16_f32 v178, v140, v141
	v_cvt_pk_bf16_f32 v179, v142, v143
	s_waitcnt vmcnt(1)
	v_and_b32_e32 v75, 0xffff0000, v73
	v_lshlrev_b32_e32 v74, 16, v73
	v_and_b32_e32 v73, 0xffff0000, v72
	v_lshlrev_b32_e32 v72, 16, v72
	v_add_f32_e32 v140, v72, v68
	v_add_f32_e32 v141, v73, v69
	v_add_f32_e32 v142, v74, v70
	v_add_f32_e32 v143, v75, v71
	v_add_f32_e32 v140, v140, v64
	v_add_f32_e32 v141, v141, v65
	v_add_f32_e32 v142, v142, v66
	v_add_f32_e32 v143, v143, v67
	v_add_f32_e32 v140, v140, v60
	v_add_f32_e32 v141, v141, v61
	v_add_f32_e32 v142, v142, v62
	v_add_f32_e32 v143, v143, v63
	v_mul_f32_e32 v140, 0x3e800000, v140
	v_mul_f32_e32 v141, 0x3e800000, v141
	v_mul_f32_e32 v142, 0x3e800000, v142
	v_mul_f32_e32 v143, 0x3e800000, v143
	v_sub_f32_e32 v140, v140, v72
	v_sub_f32_e32 v141, v141, v73
	v_sub_f32_e32 v142, v142, v74
	v_sub_f32_e32 v143, v143, v75
	v_cvt_pk_bf16_f32 v180, v140, v141
	v_cvt_pk_bf16_f32 v181, v142, v143
	s_waitcnt vmcnt(0)
; DI float bflo(unsigned u) { return __uint_as_float(u << 16); }
; DI float bfhi(unsigned u) { return __uint_as_float(u & 0xffff0000u); }
; template <int WIN>
; DI void pool_elem(const Params& p, int row, int c) {
;     ...
;   unsigned uu = *(const unsigned*)(P2 + (size_t)row * 2048 + c);
;   const float u0 = bflo(uu), u1 = bfhi(uu);
;   float s0 = u0, s1 = u1, cnt;
;   if (row < NPR) {
;     const int t = row & 2047, b = row >> 11;
;     if (t >= WIN - 1) {
;       cnt = (float)WIN;
;       unsigned w[WIN - 1];
; #pragma unroll
;       for (int j = 1; j < WIN; ++j) w[j - 1] = *(const unsigned*)(P2 + (size_t)(row - j) * 2048 + c);
; #pragma unroll
;       for (int j = 1; j < WIN; ++j) { s0 += bflo(w[j - 1]); s1 += bfhi(w[j - 1]); }
;     } else {
;       cnt = (float)(t + 1);
;       for (int j = 1; j <= t; ++j) {
;         unsigned w = *(const unsigned*)(P2 + (size_t)(row - j) * 2048 + c);
;         s0 += bflo(w); s1 += bfhi(w);
;       }
;     }
;     ...
;   *(unsigned*)(p.MIX + (size_t)row * 1024 + c) = pack2(s0 / cnt - u0, s1 / cnt - u1);
	v_and_b32_e32 v79, 0xffff0000, v77
	v_lshlrev_b32_e32 v78, 16, v77
	v_and_b32_e32 v77, 0xffff0000, v76
	v_lshlrev_b32_e32 v76, 16, v76
	v_add_f32_e32 v140, v76, v72
	v_add_f32_e32 v141, v77, v73
	v_add_f32_e32 v142, v78, v74
	v_add_f32_e32 v143, v79, v75
	v_add_f32_e32 v140, v140, v68
	v_add_f32_e32 v141, v141, v69
	v_add_f32_e32 v142, v142, v70
	v_add_f32_e32 v143, v143, v71
	v_add_f32_e32 v140, v140, v64
	v_add_f32_e32 v141, v141, v65
	v_add_f32_e32 v142, v142, v66
	v_add_f32_e32 v143, v143, v67
	v_mul_f32_e32 v140, 0x3e800000, v140
	v_mul_f32_e32 v141, 0x3e800000, v141
	v_mul_f32_e32 v142, 0x3e800000, v142
	v_mul_f32_e32 v143, 0x3e800000, v143
	v_sub_f32_e32 v140, v140, v76
	v_sub_f32_e32 v141, v141, v77
	v_sub_f32_e32 v142, v142, v78
	v_sub_f32_e32 v143, v143, v79
	v_cvt_pk_bf16_f32 v182, v140, v141
	v_cvt_pk_bf16_f32 v183, v142, v143
	global_store_dwordx2 v11, v[152:153], s[24:25]
	s_add_u32 s24, s24, 0x800
	s_addc_u32 s25, s25, 0
	global_store_dwordx2 v11, v[154:155], s[24:25]
	s_add_u32 s24, s24, 0x800
	s_addc_u32 s25, s25, 0
	global_store_dwordx2 v11, v[156:157], s[24:25]
	s_add_u32 s24, s24, 0x800
	s_addc_u32 s25, s25, 0
	global_store_dwordx2 v11, v[158:159], s[24:25]
	s_add_u32 s24, s24, 0x800
	s_addc_u32 s25, s25, 0
	global_store_dwordx2 v11, v[160:161], s[24:25]
	s_add_u32 s24, s24, 0x800
	s_addc_u32 s25, s25, 0
	global_store_dwordx2 v11, v[162:163], s[24:25]
	s_add_u32 s24, s24, 0x800
	s_addc_u32 s25, s25, 0
	global_store_dwordx2 v11, v[164:165], s[24:25]
	s_add_u32 s24, s24, 0x800
	s_addc_u32 s25, s25, 0
	global_store_dwordx2 v11, v[166:167], s[24:25]
	s_add_u32 s24, s24, 0x800
	s_addc_u32 s25, s25, 0
	global_store_dwordx2 v11, v[168:169], s[24:25]
	s_add_u32 s24, s24, 0x800
	s_addc_u32 s25, s25, 0
	global_store_dwordx2 v11, v[170:171], s[24:25]
	s_add_u32 s24, s24, 0x800
	s_addc_u32 s25, s25, 0
	global_store_dwordx2 v11, v[172:173], s[24:25]
	s_add_u32 s24, s24, 0x800
	s_addc_u32 s25, s25, 0
	global_store_dwordx2 v11, v[174:175], s[24:25]
	s_add_u32 s24, s24, 0x800
	s_addc_u32 s25, s25, 0
	global_store_dwordx2 v11, v[176:177], s[24:25]
	s_add_u32 s24, s24, 0x800
	s_addc_u32 s25, s25, 0
	global_store_dwordx2 v11, v[178:179], s[24:25]
	s_add_u32 s24, s24, 0x800
	s_addc_u32 s25, s25, 0
	global_store_dwordx2 v11, v[180:181], s[24:25]
	s_add_u32 s24, s24, 0x800
	s_addc_u32 s25, s25, 0
	global_store_dwordx2 v11, v[182:183], s[24:25]
	s_add_u32 s24, s24, 0x800
	s_addc_u32 s25, s25, 0
	s_branch .Lp13f_next
.Lp13f_f2:
	s_sub_u32 s26, s20, 0
	s_lshl_b32 s27, s26, 12
	s_lshr_b32 s28, s26, 20
	s_add_u32 s22, s8, s27
	s_addc_u32 s23, s9, s28
	global_load_dwordx2 v[16:17], v11, s[22:23]
	s_add_u32 s22, s22, 0x1000
	s_addc_u32 s23, s23, 0
	global_load_dwordx2 v[20:21], v11, s[22:23]
	s_add_u32 s22, s22, 0x1000
	s_addc_u32 s23, s23, 0
	global_load_dwordx2 v[24:25], v11, s[22:23]
	s_add_u32 s22, s22, 0x1000
	s_addc_u32 s23, s23, 0
	global_load_dwordx2 v[28:29], v11, s[22:23]
	s_add_u32 s22, s22, 0x1000
	s_addc_u32 s23, s23, 0
	global_load_dwordx2 v[32:33], v11, s[22:23]
	s_add_u32 s22, s22, 0x1000
	s_addc_u32 s23, s23, 0
	global_load_dwordx2 v[36:37], v11, s[22:23]
	s_add_u32 s22, s22, 0x1000
	s_addc_u32 s23, s23, 0
	global_load_dwordx2 v[40:41], v11, s[22:23]
	s_add_u32 s22, s22, 0x1000
	s_addc_u32 s23, s23, 0
	global_load_dwordx2 v[44:45], v11, s[22:23]
	s_add_u32 s22, s22, 0x1000
	s_addc_u32 s23, s23, 0
	global_load_dwordx2 v[48:49], v11, s[22:23]
	s_add_u32 s22, s22, 0x1000
	s_addc_u32 s23, s23, 0
	global_load_dwordx2 v[52:53], v11, s[22:23]
	s_add_u32 s22, s22, 0x1000
	s_addc_u32 s23, s23, 0
	global_load_dwordx2 v[56:57], v11, s[22:23]
	s_add_u32 s22, s22, 0x1000
	s_addc_u32 s23, s23, 0
	global_load_dwordx2 v[60:61], v11, s[22:23]
	s_add_u32 s22, s22, 0x1000
	s_addc_u32 s23, s23, 0
	global_load_dwordx2 v[64:65], v11, s[22:23]
	s_add_u32 s22, s22, 0x1000
	s_addc_u32 s23, s23, 0
	global_load_dwordx2 v[68:69], v11, s[22:23]
	s_add_u32 s22, s22, 0x1000
	s_addc_u32 s23, s23, 0
	global_load_dwordx2 v[72:73], v11, s[22:23]
	s_add_u32 s22, s22, 0x1000
	s_addc_u32 s23, s23, 0
	global_load_dwordx2 v[76:77], v11, s[22:23]
	s_add_u32 s22, s22, 0x1000
	s_addc_u32 s23, s23, 0
	s_waitcnt vmcnt(15)
	v_and_b32_e32 v19, 0xffff0000, v17
	v_lshlrev_b32_e32 v18, 16, v17
	v_and_b32_e32 v17, 0xffff0000, v16
	v_lshlrev_b32_e32 v16, 16, v16
	v_mov_b32_e32 v140, v16
	v_mov_b32_e32 v141, v17
	v_mov_b32_e32 v142, v18
	v_mov_b32_e32 v143, v19
	v_mul_f32_e32 v140, 1.0, v140
	v_mul_f32_e32 v141, 1.0, v141
	v_mul_f32_e32 v142, 1.0, v142
	v_mul_f32_e32 v143, 1.0, v143
	v_sub_f32_e32 v140, v140, v16
	v_sub_f32_e32 v141, v141, v17
	v_sub_f32_e32 v142, v142, v18
	v_sub_f32_e32 v143, v143, v19
	v_cvt_pk_bf16_f32 v152, v140, v141
	v_cvt_pk_bf16_f32 v153, v142, v143
	s_waitcnt vmcnt(14)
	v_and_b32_e32 v23, 0xffff0000, v21
	v_lshlrev_b32_e32 v22, 16, v21
	v_and_b32_e32 v21, 0xffff0000, v20
	v_lshlrev_b32_e32 v20, 16, v20
	v_add_f32_e32 v140, v20, v16
	v_add_f32_e32 v141, v21, v17
	v_add_f32_e32 v142, v22, v18
	v_add_f32_e32 v143, v23, v19
	v_mul_f32_e32 v140, 0.5, v140
	v_mul_f32_e32 v141, 0.5, v141
	v_mul_f32_e32 v142, 0.5, v142
	v_mul_f32_e32 v143, 0.5, v143
	v_sub_f32_e32 v140, v140, v20
	v_sub_f32_e32 v141, v141, v21
	v_sub_f32_e32 v142, v142, v22
	v_sub_f32_e32 v143, v143, v23
	v_cvt_pk_bf16_f32 v154, v140, v141
	v_cvt_pk_bf16_f32 v155, v142, v143
	s_waitcnt vmcnt(13)
; DI float bflo(unsigned u) { return __uint_as_float(u << 16); }
; DI float bfhi(unsigned u) { return __uint_as_float(u & 0xffff0000u); }
; template <int WIN>
; DI void pool_elem(const Params& p, int row, int c) {
;     ...
;   unsigned uu = *(const unsigned*)(P2 + (size_t)row * 2048 + c);
;   const float u0 = bflo(uu), u1 = bfhi(uu);
;   float s0 = u0, s1 = u1, cnt;
;   if (row < NPR) {
;     const int t = row & 2047, b = row >> 11;
;     if (t >= WIN - 1) {
;       cnt = (float)WIN;
;       unsigned w[WIN - 1];
; #pragma unroll
;       for (int j = 1; j < WIN; ++j) w[j - 1] = *(const unsigned*)(P2 + (size_t)(row - j) * 2048 + c);
; #pragma unroll
;       for (int j = 1; j < WIN; ++j) { s0 += bflo(w[j - 1]); s1 += bfhi(w[j - 1]); }
;     } else {
;       cnt = (float)(t + 1);
;       for (int j = 1; j <= t; ++j) {
;         unsigned w = *(const unsigned*)(P2 + (size_t)(row - j) * 2048 + c);
;         s0 += bflo(w); s1 += bfhi(w);
;       }
;     }
;     ...
;   *(unsigned*)(p.MIX + (size_t)row * 1024 + c) = pack2(s0 / cnt - u0, s1 / cnt - u1);
	v_and_b32_e32 v27, 0xffff0000, v25
	v_lshlrev_b32_e32 v26, 16, v25
	v_and_b32_e32 v25, 0xffff0000, v24
	v_lshlrev_b32_e32 v24, 16, v24
	v_add_f32_e32 v140, v24, v20
	v_add_f32_e32 v141, v25, v21
	v_add_f32_e32 v142, v26, v22
	v_add_f32_e32 v143, v27, v23
	v_add_f32_e32 v140, v140, v16
	v_add_f32_e32 v141, v141, v17
	v_add_f32_e32 v142, v142, v18
	v_add_f32_e32 v143, v143, v19
	v_mov_b32_e32 v151, 0x40400000
	v_div_scale_f32 v146, s[26:27], v151, v151, v140
	v_rcp_f32_e32 v147, v146
	v_div_scale_f32 v148, vcc, v140, v151, v140
	v_fma_f32 v149, -v146, v147, 1.0
	v_fmac_f32_e32 v147, v149, v147
	v_mul_f32_e32 v149, v148, v147
	v_fma_f32 v150, -v146, v149, v148
	v_fmac_f32_e32 v149, v150, v147
	v_fma_f32 v146, -v146, v149, v148
	v_div_fmas_f32 v146, v146, v147, v149
	v_div_fixup_f32 v140, v146, v151, v140
	v_mov_b32_e32 v151, 0x40400000
	v_div_scale_f32 v146, s[26:27], v151, v151, v141
	v_rcp_f32_e32 v147, v146
	v_div_scale_f32 v148, vcc, v141, v151, v141
	v_fma_f32 v149, -v146, v147, 1.0
	v_fmac_f32_e32 v147, v149, v147
	v_mul_f32_e32 v149, v148, v147
	v_fma_f32 v150, -v146, v149, v148
	v_fmac_f32_e32 v149, v150, v147
	v_fma_f32 v146, -v146, v149, v148
	v_div_fmas_f32 v146, v146, v147, v149
	v_div_fixup_f32 v141, v146, v151, v141
	v_mov_b32_e32 v151, 0x40400000
	v_div_scale_f32 v146, s[26:27], v151, v151, v142
	v_rcp_f32_e32 v147, v146
	v_div_scale_f32 v148, vcc, v142, v151, v142
	v_fma_f32 v149, -v146, v147, 1.0
	v_fmac_f32_e32 v147, v149, v147
	v_mul_f32_e32 v149, v148, v147
	v_fma_f32 v150, -v146, v149, v148
	v_fmac_f32_e32 v149, v150, v147
	v_fma_f32 v146, -v146, v149, v148
	v_div_fmas_f32 v146, v146, v147, v149
	v_div_fixup_f32 v142, v146, v151, v142
	v_mov_b32_e32 v151, 0x40400000
	v_div_scale_f32 v146, s[26:27], v151, v151, v143
	v_rcp_f32_e32 v147, v146
	v_div_scale_f32 v148, vcc, v143, v151, v143
	v_fma_f32 v149, -v146, v147, 1.0
	v_fmac_f32_e32 v147, v149, v147
	v_mul_f32_e32 v149, v148, v147
	v_fma_f32 v150, -v146, v149, v148
	v_fmac_f32_e32 v149, v150, v147
	v_fma_f32 v146, -v146, v149, v148
	v_div_fmas_f32 v146, v146, v147, v149
	v_div_fixup_f32 v143, v146, v151, v143
	v_sub_f32_e32 v140, v140, v24
	v_sub_f32_e32 v141, v141, v25
	v_sub_f32_e32 v142, v142, v26
	v_sub_f32_e32 v143, v143, v27
	v_cvt_pk_bf16_f32 v156, v140, v141
	v_cvt_pk_bf16_f32 v157, v142, v143
	s_waitcnt vmcnt(12)
	v_and_b32_e32 v31, 0xffff0000, v29
	v_lshlrev_b32_e32 v30, 16, v29
	v_and_b32_e32 v29, 0xffff0000, v28
	v_lshlrev_b32_e32 v28, 16, v28
	v_add_f32_e32 v140, v28, v24
	v_add_f32_e32 v141, v29, v25
	v_add_f32_e32 v142, v30, v26
	v_add_f32_e32 v143, v31, v27
	v_add_f32_e32 v140, v140, v20
	v_add_f32_e32 v141, v141, v21
	v_add_f32_e32 v142, v142, v22
	v_add_f32_e32 v143, v143, v23
	v_add_f32_e32 v140, v140, v16
	v_add_f32_e32 v141, v141, v17
	v_add_f32_e32 v142, v142, v18
	v_add_f32_e32 v143, v143, v19
	v_mul_f32_e32 v140, 0x3e800000, v140
	v_mul_f32_e32 v141, 0x3e800000, v141
	v_mul_f32_e32 v142, 0x3e800000, v142
	v_mul_f32_e32 v143, 0x3e800000, v143
	v_sub_f32_e32 v140, v140, v28
	v_sub_f32_e32 v141, v141, v29
	v_sub_f32_e32 v142, v142, v30
	v_sub_f32_e32 v143, v143, v31
	v_cvt_pk_bf16_f32 v158, v140, v141
	v_cvt_pk_bf16_f32 v159, v142, v143
	s_waitcnt vmcnt(11)
	v_and_b32_e32 v35, 0xffff0000, v33
	v_lshlrev_b32_e32 v34, 16, v33
	v_and_b32_e32 v33, 0xffff0000, v32
	v_lshlrev_b32_e32 v32, 16, v32
	v_add_f32_e32 v140, v32, v28
	v_add_f32_e32 v141, v33, v29
	v_add_f32_e32 v142, v34, v30
	v_add_f32_e32 v143, v35, v31
	v_add_f32_e32 v140, v140, v24
	v_add_f32_e32 v141, v141, v25
	v_add_f32_e32 v142, v142, v26
	v_add_f32_e32 v143, v143, v27
	v_add_f32_e32 v140, v140, v20
	v_add_f32_e32 v141, v141, v21
	v_add_f32_e32 v142, v142, v22
	v_add_f32_e32 v143, v143, v23
	v_add_f32_e32 v140, v140, v16
	v_add_f32_e32 v141, v141, v17
	v_add_f32_e32 v142, v142, v18
	v_add_f32_e32 v143, v143, v19
	v_mov_b32_e32 v151, 0x40a00000
	v_div_scale_f32 v146, s[26:27], v151, v151, v140
	v_rcp_f32_e32 v147, v146
	v_div_scale_f32 v148, vcc, v140, v151, v140
	v_fma_f32 v149, -v146, v147, 1.0
	v_fmac_f32_e32 v147, v149, v147
	v_mul_f32_e32 v149, v148, v147
	v_fma_f32 v150, -v146, v149, v148
	v_fmac_f32_e32 v149, v150, v147
	v_fma_f32 v146, -v146, v149, v148
	v_div_fmas_f32 v146, v146, v147, v149
	v_div_fixup_f32 v140, v146, v151, v140
	v_mov_b32_e32 v151, 0x40a00000
	v_div_scale_f32 v146, s[26:27], v151, v151, v141
	v_rcp_f32_e32 v147, v146
	v_div_scale_f32 v148, vcc, v141, v151, v141
	v_fma_f32 v149, -v146, v147, 1.0
	v_fmac_f32_e32 v147, v149, v147
	v_mul_f32_e32 v149, v148, v147
	v_fma_f32 v150, -v146, v149, v148
	v_fmac_f32_e32 v149, v150, v147
	v_fma_f32 v146, -v146, v149, v148
	v_div_fmas_f32 v146, v146, v147, v149
	v_div_fixup_f32 v141, v146, v151, v141
	v_mov_b32_e32 v151, 0x40a00000
	v_div_scale_f32 v146, s[26:27], v151, v151, v142
	v_rcp_f32_e32 v147, v146
	v_div_scale_f32 v148, vcc, v142, v151, v142
	v_fma_f32 v149, -v146, v147, 1.0
	v_fmac_f32_e32 v147, v149, v147
	v_mul_f32_e32 v149, v148, v147
	v_fma_f32 v150, -v146, v149, v148
	v_fmac_f32_e32 v149, v150, v147
	v_fma_f32 v146, -v146, v149, v148
	v_div_fmas_f32 v146, v146, v147, v149
	v_div_fixup_f32 v142, v146, v151, v142
	v_mov_b32_e32 v151, 0x40a00000
	v_div_scale_f32 v146, s[26:27], v151, v151, v143
	v_rcp_f32_e32 v147, v146
	v_div_scale_f32 v148, vcc, v143, v151, v143
	v_fma_f32 v149, -v146, v147, 1.0
	v_fmac_f32_e32 v147, v149, v147
	v_mul_f32_e32 v149, v148, v147
	v_fma_f32 v150, -v146, v149, v148
	v_fmac_f32_e32 v149, v150, v147
	v_fma_f32 v146, -v146, v149, v148
	v_div_fmas_f32 v146, v146, v147, v149
	v_div_fixup_f32 v143, v146, v151, v143
	v_sub_f32_e32 v140, v140, v32
	v_sub_f32_e32 v141, v141, v33
	v_sub_f32_e32 v142, v142, v34
	v_sub_f32_e32 v143, v143, v35
	v_cvt_pk_bf16_f32 v160, v140, v141
	v_cvt_pk_bf16_f32 v161, v142, v143
	s_waitcnt vmcnt(10)
; DI float bflo(unsigned u) { return __uint_as_float(u << 16); }
; DI float bfhi(unsigned u) { return __uint_as_float(u & 0xffff0000u); }
; template <int WIN>
; DI void pool_elem(const Params& p, int row, int c) {
;     ...
;   unsigned uu = *(const unsigned*)(P2 + (size_t)row * 2048 + c);
;   const float u0 = bflo(uu), u1 = bfhi(uu);
;   float s0 = u0, s1 = u1, cnt;
;   if (row < NPR) {
;     const int t = row & 2047, b = row >> 11;
;     if (t >= WIN - 1) {
;       cnt = (float)WIN;
;       unsigned w[WIN - 1];
; #pragma unroll
;       for (int j = 1; j < WIN; ++j) w[j - 1] = *(const unsigned*)(P2 + (size_t)(row - j) * 2048 + c);
; #pragma unroll
;       for (int j = 1; j < WIN; ++j) { s0 += bflo(w[j - 1]); s1 += bfhi(w[j - 1]); }
;     } else {
;       cnt = (float)(t + 1);
;       for (int j = 1; j <= t; ++j) {
;         unsigned w = *(const unsigned*)(P2 + (size_t)(row - j) * 2048 + c);
;         s0 += bflo(w); s1 += bfhi(w);
;       }
;     }
;     ...
;   *(unsigned*)(p.MIX + (size_t)row * 1024 + c) = pack2(s0 / cnt - u0, s1 / cnt - u1);
	v_and_b32_e32 v39, 0xffff0000, v37
	v_lshlrev_b32_e32 v38, 16, v37
	v_and_b32_e32 v37, 0xffff0000, v36
	v_lshlrev_b32_e32 v36, 16, v36
	v_add_f32_e32 v140, v36, v32
	v_add_f32_e32 v141, v37, v33
	v_add_f32_e32 v142, v38, v34
	v_add_f32_e32 v143, v39, v35
	v_add_f32_e32 v140, v140, v28
	v_add_f32_e32 v141, v141, v29
	v_add_f32_e32 v142, v142, v30
	v_add_f32_e32 v143, v143, v31
	v_add_f32_e32 v140, v140, v24
	v_add_f32_e32 v141, v141, v25
	v_add_f32_e32 v142, v142, v26
	v_add_f32_e32 v143, v143, v27
	v_add_f32_e32 v140, v140, v20
	v_add_f32_e32 v141, v141, v21
	v_add_f32_e32 v142, v142, v22
	v_add_f32_e32 v143, v143, v23
	v_add_f32_e32 v140, v140, v16
	v_add_f32_e32 v141, v141, v17
	v_add_f32_e32 v142, v142, v18
	v_add_f32_e32 v143, v143, v19
	v_mov_b32_e32 v151, 0x40c00000
	v_div_scale_f32 v146, s[26:27], v151, v151, v140
	v_rcp_f32_e32 v147, v146
	v_div_scale_f32 v148, vcc, v140, v151, v140
	v_fma_f32 v149, -v146, v147, 1.0
	v_fmac_f32_e32 v147, v149, v147
	v_mul_f32_e32 v149, v148, v147
	v_fma_f32 v150, -v146, v149, v148
	v_fmac_f32_e32 v149, v150, v147
	v_fma_f32 v146, -v146, v149, v148
	v_div_fmas_f32 v146, v146, v147, v149
	v_div_fixup_f32 v140, v146, v151, v140
	v_mov_b32_e32 v151, 0x40c00000
	v_div_scale_f32 v146, s[26:27], v151, v151, v141
	v_rcp_f32_e32 v147, v146
	v_div_scale_f32 v148, vcc, v141, v151, v141
	v_fma_f32 v149, -v146, v147, 1.0
	v_fmac_f32_e32 v147, v149, v147
	v_mul_f32_e32 v149, v148, v147
	v_fma_f32 v150, -v146, v149, v148
	v_fmac_f32_e32 v149, v150, v147
	v_fma_f32 v146, -v146, v149, v148
	v_div_fmas_f32 v146, v146, v147, v149
	v_div_fixup_f32 v141, v146, v151, v141
	v_mov_b32_e32 v151, 0x40c00000
	v_div_scale_f32 v146, s[26:27], v151, v151, v142
	v_rcp_f32_e32 v147, v146
	v_div_scale_f32 v148, vcc, v142, v151, v142
	v_fma_f32 v149, -v146, v147, 1.0
	v_fmac_f32_e32 v147, v149, v147
	v_mul_f32_e32 v149, v148, v147
	v_fma_f32 v150, -v146, v149, v148
	v_fmac_f32_e32 v149, v150, v147
	v_fma_f32 v146, -v146, v149, v148
	v_div_fmas_f32 v146, v146, v147, v149
	v_div_fixup_f32 v142, v146, v151, v142
	v_mov_b32_e32 v151, 0x40c00000
	v_div_scale_f32 v146, s[26:27], v151, v151, v143
	v_rcp_f32_e32 v147, v146
	v_div_scale_f32 v148, vcc, v143, v151, v143
	v_fma_f32 v149, -v146, v147, 1.0
	v_fmac_f32_e32 v147, v149, v147
	v_mul_f32_e32 v149, v148, v147
	v_fma_f32 v150, -v146, v149, v148
	v_fmac_f32_e32 v149, v150, v147
	v_fma_f32 v146, -v146, v149, v148
	v_div_fmas_f32 v146, v146, v147, v149
	v_div_fixup_f32 v143, v146, v151, v143
	v_sub_f32_e32 v140, v140, v36
	v_sub_f32_e32 v141, v141, v37
	v_sub_f32_e32 v142, v142, v38
	v_sub_f32_e32 v143, v143, v39
	v_cvt_pk_bf16_f32 v162, v140, v141
	v_cvt_pk_bf16_f32 v163, v142, v143
	s_waitcnt vmcnt(9)
	v_and_b32_e32 v43, 0xffff0000, v41
	v_lshlrev_b32_e32 v42, 16, v41
	v_and_b32_e32 v41, 0xffff0000, v40
	v_lshlrev_b32_e32 v40, 16, v40
	v_add_f32_e32 v140, v40, v36
	v_add_f32_e32 v141, v41, v37
	v_add_f32_e32 v142, v42, v38
	v_add_f32_e32 v143, v43, v39
	v_add_f32_e32 v140, v140, v32
	v_add_f32_e32 v141, v141, v33
	v_add_f32_e32 v142, v142, v34
	v_add_f32_e32 v143, v143, v35
	v_add_f32_e32 v140, v140, v28
	v_add_f32_e32 v141, v141, v29
	v_add_f32_e32 v142, v142, v30
	v_add_f32_e32 v143, v143, v31
	v_add_f32_e32 v140, v140, v24
	v_add_f32_e32 v141, v141, v25
	v_add_f32_e32 v142, v142, v26
	v_add_f32_e32 v143, v143, v27
	v_add_f32_e32 v140, v140, v20
	v_add_f32_e32 v141, v141, v21
	v_add_f32_e32 v142, v142, v22
	v_add_f32_e32 v143, v143, v23
	v_add_f32_e32 v140, v140, v16
	v_add_f32_e32 v141, v141, v17
	v_add_f32_e32 v142, v142, v18
	v_add_f32_e32 v143, v143, v19
	v_mov_b32_e32 v151, 0x40e00000
	v_div_scale_f32 v146, s[26:27], v151, v151, v140
	v_rcp_f32_e32 v147, v146
	v_div_scale_f32 v148, vcc, v140, v151, v140
	v_fma_f32 v149, -v146, v147, 1.0
	v_fmac_f32_e32 v147, v149, v147
	v_mul_f32_e32 v149, v148, v147
	v_fma_f32 v150, -v146, v149, v148
	v_fmac_f32_e32 v149, v150, v147
	v_fma_f32 v146, -v146, v149, v148
	v_div_fmas_f32 v146, v146, v147, v149
	v_div_fixup_f32 v140, v146, v151, v140
	v_mov_b32_e32 v151, 0x40e00000
	v_div_scale_f32 v146, s[26:27], v151, v151, v141
	v_rcp_f32_e32 v147, v146
	v_div_scale_f32 v148, vcc, v141, v151, v141
	v_fma_f32 v149, -v146, v147, 1.0
	v_fmac_f32_e32 v147, v149, v147
	v_mul_f32_e32 v149, v148, v147
	v_fma_f32 v150, -v146, v149, v148
	v_fmac_f32_e32 v149, v150, v147
	v_fma_f32 v146, -v146, v149, v148
	v_div_fmas_f32 v146, v146, v147, v149
	v_div_fixup_f32 v141, v146, v151, v141
	v_mov_b32_e32 v151, 0x40e00000
	v_div_scale_f32 v146, s[26:27], v151, v151, v142
	v_rcp_f32_e32 v147, v146
	v_div_scale_f32 v148, vcc, v142, v151, v142
	v_fma_f32 v149, -v146, v147, 1.0
	v_fmac_f32_e32 v147, v149, v147
	v_mul_f32_e32 v149, v148, v147
	v_fma_f32 v150, -v146, v149, v148
	v_fmac_f32_e32 v149, v150, v147
	v_fma_f32 v146, -v146, v149, v148
	v_div_fmas_f32 v146, v146, v147, v149
	v_div_fixup_f32 v142, v146, v151, v142
	v_mov_b32_e32 v151, 0x40e00000
	v_div_scale_f32 v146, s[26:27], v151, v151, v143
	v_rcp_f32_e32 v147, v146
	v_div_scale_f32 v148, vcc, v143, v151, v143
	v_fma_f32 v149, -v146, v147, 1.0
	v_fmac_f32_e32 v147, v149, v147
	v_mul_f32_e32 v149, v148, v147
	v_fma_f32 v150, -v146, v149, v148
	v_fmac_f32_e32 v149, v150, v147
	v_fma_f32 v146, -v146, v149, v148
	v_div_fmas_f32 v146, v146, v147, v149
	v_div_fixup_f32 v143, v146, v151, v143
	v_sub_f32_e32 v140, v140, v40
	v_sub_f32_e32 v141, v141, v41
	v_sub_f32_e32 v142, v142, v42
	v_sub_f32_e32 v143, v143, v43
	v_cvt_pk_bf16_f32 v164, v140, v141
	v_cvt_pk_bf16_f32 v165, v142, v143
	s_waitcnt vmcnt(8)
; DI float bflo(unsigned u) { return __uint_as_float(u << 16); }
; DI float bfhi(unsigned u) { return __uint_as_float(u & 0xffff0000u); }
; template <int WIN>
; DI void pool_elem(const Params& p, int row, int c) {
;     ...
;   unsigned uu = *(const unsigned*)(P2 + (size_t)row * 2048 + c);
;   const float u0 = bflo(uu), u1 = bfhi(uu);
;   float s0 = u0, s1 = u1, cnt;
;   if (row < NPR) {
;     const int t = row & 2047, b = row >> 11;
;     if (t >= WIN - 1) {
;       cnt = (float)WIN;
;       unsigned w[WIN - 1];
; #pragma unroll
;       for (int j = 1; j < WIN; ++j) w[j - 1] = *(const unsigned*)(P2 + (size_t)(row - j) * 2048 + c);
; #pragma unroll
;       for (int j = 1; j < WIN; ++j) { s0 += bflo(w[j - 1]); s1 += bfhi(w[j - 1]); }
;     ...
;   *(unsigned*)(p.MIX + (size_t)row * 1024 + c) = pack2(s0 / cnt - u0, s1 / cnt - u1);
	v_and_b32_e32 v47, 0xffff0000, v45
	v_lshlrev_b32_e32 v46, 16, v45
	v_and_b32_e32 v45, 0xffff0000, v44
	v_lshlrev_b32_e32 v44, 16, v44
	v_add_f32_e32 v140, v44, v40
	v_add_f32_e32 v141, v45, v41
	v_add_f32_e32 v142, v46, v42
	v_add_f32_e32 v143, v47, v43
	v_add_f32_e32 v140, v140, v36
	v_add_f32_e32 v141, v141, v37
	v_add_f32_e32 v142, v142, v38
	v_add_f32_e32 v143, v143, v39
	v_add_f32_e32 v140, v140, v32
	v_add_f32_e32 v141, v141, v33
	v_add_f32_e32 v142, v142, v34
	v_add_f32_e32 v143, v143, v35
	v_add_f32_e32 v140, v140, v28
	v_add_f32_e32 v141, v141, v29
	v_add_f32_e32 v142, v142, v30
	v_add_f32_e32 v143, v143, v31
	v_add_f32_e32 v140, v140, v24
	v_add_f32_e32 v141, v141, v25
	v_add_f32_e32 v142, v142, v26
	v_add_f32_e32 v143, v143, v27
	v_add_f32_e32 v140, v140, v20
	v_add_f32_e32 v141, v141, v21
	v_add_f32_e32 v142, v142, v22
	v_add_f32_e32 v143, v143, v23
	v_add_f32_e32 v140, v140, v16
	v_add_f32_e32 v141, v141, v17
	v_add_f32_e32 v142, v142, v18
	v_add_f32_e32 v143, v143, v19
	v_mul_f32_e32 v140, 0x3e000000, v140
	v_mul_f32_e32 v141, 0x3e000000, v141
	v_mul_f32_e32 v142, 0x3e000000, v142
	v_mul_f32_e32 v143, 0x3e000000, v143
	v_sub_f32_e32 v140, v140, v44
	v_sub_f32_e32 v141, v141, v45
	v_sub_f32_e32 v142, v142, v46
	v_sub_f32_e32 v143, v143, v47
	v_cvt_pk_bf16_f32 v166, v140, v141
	v_cvt_pk_bf16_f32 v167, v142, v143
	s_waitcnt vmcnt(7)
	v_and_b32_e32 v51, 0xffff0000, v49
	v_lshlrev_b32_e32 v50, 16, v49
	v_and_b32_e32 v49, 0xffff0000, v48
	v_lshlrev_b32_e32 v48, 16, v48
	v_add_f32_e32 v140, v48, v44
	v_add_f32_e32 v141, v49, v45
	v_add_f32_e32 v142, v50, v46
	v_add_f32_e32 v143, v51, v47
	v_add_f32_e32 v140, v140, v40
	v_add_f32_e32 v141, v141, v41
	v_add_f32_e32 v142, v142, v42
	v_add_f32_e32 v143, v143, v43
	v_add_f32_e32 v140, v140, v36
	v_add_f32_e32 v141, v141, v37
	v_add_f32_e32 v142, v142, v38
	v_add_f32_e32 v143, v143, v39
	v_add_f32_e32 v140, v140, v32
	v_add_f32_e32 v141, v141, v33
	v_add_f32_e32 v142, v142, v34
	v_add_f32_e32 v143, v143, v35
	v_add_f32_e32 v140, v140, v28
	v_add_f32_e32 v141, v141, v29
	v_add_f32_e32 v142, v142, v30
	v_add_f32_e32 v143, v143, v31
	v_add_f32_e32 v140, v140, v24
	v_add_f32_e32 v141, v141, v25
	v_add_f32_e32 v142, v142, v26
	v_add_f32_e32 v143, v143, v27
	v_add_f32_e32 v140, v140, v20
	v_add_f32_e32 v141, v141, v21
	v_add_f32_e32 v142, v142, v22
	v_add_f32_e32 v143, v143, v23
	v_mul_f32_e32 v140, 0x3e000000, v140
	v_mul_f32_e32 v141, 0x3e000000, v141
	v_mul_f32_e32 v142, 0x3e000000, v142
	v_mul_f32_e32 v143, 0x3e000000, v143
	v_sub_f32_e32 v140, v140, v48
	v_sub_f32_e32 v141, v141, v49
	v_sub_f32_e32 v142, v142, v50
	v_sub_f32_e32 v143, v143, v51
	v_cvt_pk_bf16_f32 v168, v140, v141
	v_cvt_pk_bf16_f32 v169, v142, v143
	s_waitcnt vmcnt(6)
	v_and_b32_e32 v55, 0xffff0000, v53
	v_lshlrev_b32_e32 v54, 16, v53
	v_and_b32_e32 v53, 0xffff0000, v52
	v_lshlrev_b32_e32 v52, 16, v52
	v_add_f32_e32 v140, v52, v48
	v_add_f32_e32 v141, v53, v49
	v_add_f32_e32 v142, v54, v50
	v_add_f32_e32 v143, v55, v51
	v_add_f32_e32 v140, v140, v44
	v_add_f32_e32 v141, v141, v45
	v_add_f32_e32 v142, v142, v46
	v_add_f32_e32 v143, v143, v47
	v_add_f32_e32 v140, v140, v40
	v_add_f32_e32 v141, v141, v41
	v_add_f32_e32 v142, v142, v42
	v_add_f32_e32 v143, v143, v43
	v_add_f32_e32 v140, v140, v36
	v_add_f32_e32 v141, v141, v37
	v_add_f32_e32 v142, v142, v38
	v_add_f32_e32 v143, v143, v39
	v_add_f32_e32 v140, v140, v32
	v_add_f32_e32 v141, v141, v33
	v_add_f32_e32 v142, v142, v34
	v_add_f32_e32 v143, v143, v35
	v_add_f32_e32 v140, v140, v28
	v_add_f32_e32 v141, v141, v29
	v_add_f32_e32 v142, v142, v30
	v_add_f32_e32 v143, v143, v31
	v_add_f32_e32 v140, v140, v24
	v_add_f32_e32 v141, v141, v25
	v_add_f32_e32 v142, v142, v26
	v_add_f32_e32 v143, v143, v27
	v_mul_f32_e32 v140, 0x3e000000, v140
	v_mul_f32_e32 v141, 0x3e000000, v141
	v_mul_f32_e32 v142, 0x3e000000, v142
	v_mul_f32_e32 v143, 0x3e000000, v143
	v_sub_f32_e32 v140, v140, v52
	v_sub_f32_e32 v141, v141, v53
	v_sub_f32_e32 v142, v142, v54
	v_sub_f32_e32 v143, v143, v55
	v_cvt_pk_bf16_f32 v170, v140, v141
	v_cvt_pk_bf16_f32 v171, v142, v143
	s_waitcnt vmcnt(5)
	v_and_b32_e32 v59, 0xffff0000, v57
	v_lshlrev_b32_e32 v58, 16, v57
	v_and_b32_e32 v57, 0xffff0000, v56
	v_lshlrev_b32_e32 v56, 16, v56
	v_add_f32_e32 v140, v56, v52
	v_add_f32_e32 v141, v57, v53
	v_add_f32_e32 v142, v58, v54
	v_add_f32_e32 v143, v59, v55
	v_add_f32_e32 v140, v140, v48
	v_add_f32_e32 v141, v141, v49
	v_add_f32_e32 v142, v142, v50
	v_add_f32_e32 v143, v143, v51
	v_add_f32_e32 v140, v140, v44
	v_add_f32_e32 v141, v141, v45
	v_add_f32_e32 v142, v142, v46
	v_add_f32_e32 v143, v143, v47
	v_add_f32_e32 v140, v140, v40
	v_add_f32_e32 v141, v141, v41
	v_add_f32_e32 v142, v142, v42
	v_add_f32_e32 v143, v143, v43
	v_add_f32_e32 v140, v140, v36
	v_add_f32_e32 v141, v141, v37
	v_add_f32_e32 v142, v142, v38
	v_add_f32_e32 v143, v143, v39
	v_add_f32_e32 v140, v140, v32
	v_add_f32_e32 v141, v141, v33
	v_add_f32_e32 v142, v142, v34
	v_add_f32_e32 v143, v143, v35
	v_add_f32_e32 v140, v140, v28
	v_add_f32_e32 v141, v141, v29
	v_add_f32_e32 v142, v142, v30
	v_add_f32_e32 v143, v143, v31
	v_mul_f32_e32 v140, 0x3e000000, v140
	v_mul_f32_e32 v141, 0x3e000000, v141
	v_mul_f32_e32 v142, 0x3e000000, v142
	v_mul_f32_e32 v143, 0x3e000000, v143
	v_sub_f32_e32 v140, v140, v56
	v_sub_f32_e32 v141, v141, v57
	v_sub_f32_e32 v142, v142, v58
	v_sub_f32_e32 v143, v143, v59
	v_cvt_pk_bf16_f32 v172, v140, v141
	v_cvt_pk_bf16_f32 v173, v142, v143
	s_waitcnt vmcnt(4)
; DI float bflo(unsigned u) { return __uint_as_float(u << 16); }
; DI float bfhi(unsigned u) { return __uint_as_float(u & 0xffff0000u); }
; template <int WIN>
; DI void pool_elem(const Params& p, int row, int c) {
;     ...
;   unsigned uu = *(const unsigned*)(P2 + (size_t)row * 2048 + c);
;   const float u0 = bflo(uu), u1 = bfhi(uu);
;   float s0 = u0, s1 = u1, cnt;
;   if (row < NPR) {
;     const int t = row & 2047, b = row >> 11;
;     if (t >= WIN - 1) {
;       cnt = (float)WIN;
;       unsigned w[WIN - 1];
; #pragma unroll
;       for (int j = 1; j < WIN; ++j) w[j - 1] = *(const unsigned*)(P2 + (size_t)(row - j) * 2048 + c);
; #pragma unroll
;       for (int j = 1; j < WIN; ++j) { s0 += bflo(w[j - 1]); s1 += bfhi(w[j - 1]); }
;     ...
;   *(unsigned*)(p.MIX + (size_t)row * 1024 + c) = pack2(s0 / cnt - u0, s1 / cnt - u1);
	v_and_b32_e32 v63, 0xffff0000, v61
	v_lshlrev_b32_e32 v62, 16, v61
	v_and_b32_e32 v61, 0xffff0000, v60
	v_lshlrev_b32_e32 v60, 16, v60
	v_add_f32_e32 v140, v60, v56
	v_add_f32_e32 v141, v61, v57
	v_add_f32_e32 v142, v62, v58
	v_add_f32_e32 v143, v63, v59
	v_add_f32_e32 v140, v140, v52
	v_add_f32_e32 v141, v141, v53
	v_add_f32_e32 v142, v142, v54
	v_add_f32_e32 v143, v143, v55
	v_add_f32_e32 v140, v140, v48
	v_add_f32_e32 v141, v141, v49
	v_add_f32_e32 v142, v142, v50
	v_add_f32_e32 v143, v143, v51
	v_add_f32_e32 v140, v140, v44
	v_add_f32_e32 v141, v141, v45
	v_add_f32_e32 v142, v142, v46
	v_add_f32_e32 v143, v143, v47
	v_add_f32_e32 v140, v140, v40
	v_add_f32_e32 v141, v141, v41
	v_add_f32_e32 v142, v142, v42
	v_add_f32_e32 v143, v143, v43
	v_add_f32_e32 v140, v140, v36
	v_add_f32_e32 v141, v141, v37
	v_add_f32_e32 v142, v142, v38
	v_add_f32_e32 v143, v143, v39
	v_add_f32_e32 v140, v140, v32
	v_add_f32_e32 v141, v141, v33
	v_add_f32_e32 v142, v142, v34
	v_add_f32_e32 v143, v143, v35
	v_mul_f32_e32 v140, 0x3e000000, v140
	v_mul_f32_e32 v141, 0x3e000000, v141
	v_mul_f32_e32 v142, 0x3e000000, v142
	v_mul_f32_e32 v143, 0x3e000000, v143
	v_sub_f32_e32 v140, v140, v60
	v_sub_f32_e32 v141, v141, v61
	v_sub_f32_e32 v142, v142, v62
	v_sub_f32_e32 v143, v143, v63
	v_cvt_pk_bf16_f32 v174, v140, v141
	v_cvt_pk_bf16_f32 v175, v142, v143
	s_waitcnt vmcnt(3)
	v_and_b32_e32 v67, 0xffff0000, v65
	v_lshlrev_b32_e32 v66, 16, v65
	v_and_b32_e32 v65, 0xffff0000, v64
	v_lshlrev_b32_e32 v64, 16, v64
	v_add_f32_e32 v140, v64, v60
	v_add_f32_e32 v141, v65, v61
	v_add_f32_e32 v142, v66, v62
	v_add_f32_e32 v143, v67, v63
	v_add_f32_e32 v140, v140, v56
	v_add_f32_e32 v141, v141, v57
	v_add_f32_e32 v142, v142, v58
	v_add_f32_e32 v143, v143, v59
	v_add_f32_e32 v140, v140, v52
	v_add_f32_e32 v141, v141, v53
	v_add_f32_e32 v142, v142, v54
	v_add_f32_e32 v143, v143, v55
	v_add_f32_e32 v140, v140, v48
	v_add_f32_e32 v141, v141, v49
	v_add_f32_e32 v142, v142, v50
	v_add_f32_e32 v143, v143, v51
	v_add_f32_e32 v140, v140, v44
	v_add_f32_e32 v141, v141, v45
	v_add_f32_e32 v142, v142, v46
	v_add_f32_e32 v143, v143, v47
	v_add_f32_e32 v140, v140, v40
	v_add_f32_e32 v141, v141, v41
	v_add_f32_e32 v142, v142, v42
	v_add_f32_e32 v143, v143, v43
	v_add_f32_e32 v140, v140, v36
	v_add_f32_e32 v141, v141, v37
	v_add_f32_e32 v142, v142, v38
	v_add_f32_e32 v143, v143, v39
	v_mul_f32_e32 v140, 0x3e000000, v140
	v_mul_f32_e32 v141, 0x3e000000, v141
	v_mul_f32_e32 v142, 0x3e000000, v142
	v_mul_f32_e32 v143, 0x3e000000, v143
	v_sub_f32_e32 v140, v140, v64
	v_sub_f32_e32 v141, v141, v65
	v_sub_f32_e32 v142, v142, v66
	v_sub_f32_e32 v143, v143, v67
	v_cvt_pk_bf16_f32 v176, v140, v141
	v_cvt_pk_bf16_f32 v177, v142, v143
	s_waitcnt vmcnt(2)
	v_and_b32_e32 v71, 0xffff0000, v69
	v_lshlrev_b32_e32 v70, 16, v69
	v_and_b32_e32 v69, 0xffff0000, v68
	v_lshlrev_b32_e32 v68, 16, v68
	v_add_f32_e32 v140, v68, v64
	v_add_f32_e32 v141, v69, v65
	v_add_f32_e32 v142, v70, v66
	v_add_f32_e32 v143, v71, v67
	v_add_f32_e32 v140, v140, v60
	v_add_f32_e32 v141, v141, v61
	v_add_f32_e32 v142, v142, v62
	v_add_f32_e32 v143, v143, v63
	v_add_f32_e32 v140, v140, v56
	v_add_f32_e32 v141, v141, v57
	v_add_f32_e32 v142, v142, v58
	v_add_f32_e32 v143, v143, v59
	v_add_f32_e32 v140, v140, v52
	v_add_f32_e32 v141, v141, v53
	v_add_f32_e32 v142, v142, v54
	v_add_f32_e32 v143, v143, v55
	v_add_f32_e32 v140, v140, v48
	v_add_f32_e32 v141, v141, v49
	v_add_f32_e32 v142, v142, v50
	v_add_f32_e32 v143, v143, v51
	v_add_f32_e32 v140, v140, v44
	v_add_f32_e32 v141, v141, v45
	v_add_f32_e32 v142, v142, v46
	v_add_f32_e32 v143, v143, v47
	v_add_f32_e32 v140, v140, v40
	v_add_f32_e32 v141, v141, v41
	v_add_f32_e32 v142, v142, v42
	v_add_f32_e32 v143, v143, v43
	v_mul_f32_e32 v140, 0x3e000000, v140
	v_mul_f32_e32 v141, 0x3e000000, v141
	v_mul_f32_e32 v142, 0x3e000000, v142
	v_mul_f32_e32 v143, 0x3e000000, v143
	v_sub_f32_e32 v140, v140, v68
	v_sub_f32_e32 v141, v141, v69
	v_sub_f32_e32 v142, v142, v70
	v_sub_f32_e32 v143, v143, v71
	v_cvt_pk_bf16_f32 v178, v140, v141
	v_cvt_pk_bf16_f32 v179, v142, v143
	s_waitcnt vmcnt(1)
	v_and_b32_e32 v75, 0xffff0000, v73
	v_lshlrev_b32_e32 v74, 16, v73
	v_and_b32_e32 v73, 0xffff0000, v72
	v_lshlrev_b32_e32 v72, 16, v72
	v_add_f32_e32 v140, v72, v68
	v_add_f32_e32 v141, v73, v69
	v_add_f32_e32 v142, v74, v70
	v_add_f32_e32 v143, v75, v71
	v_add_f32_e32 v140, v140, v64
	v_add_f32_e32 v141, v141, v65
	v_add_f32_e32 v142, v142, v66
	v_add_f32_e32 v143, v143, v67
	v_add_f32_e32 v140, v140, v60
	v_add_f32_e32 v141, v141, v61
	v_add_f32_e32 v142, v142, v62
	v_add_f32_e32 v143, v143, v63
	v_add_f32_e32 v140, v140, v56
	v_add_f32_e32 v141, v141, v57
	v_add_f32_e32 v142, v142, v58
	v_add_f32_e32 v143, v143, v59
	v_add_f32_e32 v140, v140, v52
	v_add_f32_e32 v141, v141, v53
	v_add_f32_e32 v142, v142, v54
	v_add_f32_e32 v143, v143, v55
	v_add_f32_e32 v140, v140, v48
	v_add_f32_e32 v141, v141, v49
	v_add_f32_e32 v142, v142, v50
	v_add_f32_e32 v143, v143, v51
	v_add_f32_e32 v140, v140, v44
	v_add_f32_e32 v141, v141, v45
	v_add_f32_e32 v142, v142, v46
	v_add_f32_e32 v143, v143, v47
	v_mul_f32_e32 v140, 0x3e000000, v140
	v_mul_f32_e32 v141, 0x3e000000, v141
	v_mul_f32_e32 v142, 0x3e000000, v142
	v_mul_f32_e32 v143, 0x3e000000, v143
	v_sub_f32_e32 v140, v140, v72
	v_sub_f32_e32 v141, v141, v73
	v_sub_f32_e32 v142, v142, v74
	v_sub_f32_e32 v143, v143, v75
	v_cvt_pk_bf16_f32 v180, v140, v141
	v_cvt_pk_bf16_f32 v181, v142, v143
	s_waitcnt vmcnt(0)
; DI float bflo(unsigned u) { return __uint_as_float(u << 16); }
; DI float bfhi(unsigned u) { return __uint_as_float(u & 0xffff0000u); }
; template <int WIN>
; DI void pool_elem(const Params& p, int row, int c) {
;     ...
;   unsigned uu = *(const unsigned*)(P2 + (size_t)row * 2048 + c);
;   const float u0 = bflo(uu), u1 = bfhi(uu);
;   float s0 = u0, s1 = u1, cnt;
;   if (row < NPR) {
;     const int t = row & 2047, b = row >> 11;
;     if (t >= WIN - 1) {
;       cnt = (float)WIN;
;       unsigned w[WIN - 1];
; #pragma unroll
;       for (int j = 1; j < WIN; ++j) w[j - 1] = *(const unsigned*)(P2 + (size_t)(row - j) * 2048 + c);
; #pragma unroll
;       for (int j = 1; j < WIN; ++j) { s0 += bflo(w[j - 1]); s1 += bfhi(w[j - 1]); }
;     } else {
;       cnt = (float)(t + 1);
;       for (int j = 1; j <= t; ++j) {
;         unsigned w = *(const unsigned*)(P2 + (size_t)(row - j) * 2048 + c);
;         s0 += bflo(w); s1 += bfhi(w);
;       }
;     }
;     ...
;   *(unsigned*)(p.MIX + (size_t)row * 1024 + c) = pack2(s0 / cnt - u0, s1 / cnt - u1);
	v_and_b32_e32 v79, 0xffff0000, v77
	v_lshlrev_b32_e32 v78, 16, v77
	v_and_b32_e32 v77, 0xffff0000, v76
	v_lshlrev_b32_e32 v76, 16, v76
	v_add_f32_e32 v140, v76, v72
	v_add_f32_e32 v141, v77, v73
	v_add_f32_e32 v142, v78, v74
	v_add_f32_e32 v143, v79, v75
	v_add_f32_e32 v140, v140, v68
	v_add_f32_e32 v141, v141, v69
	v_add_f32_e32 v142, v142, v70
	v_add_f32_e32 v143, v143, v71
	v_add_f32_e32 v140, v140, v64
	v_add_f32_e32 v141, v141, v65
	v_add_f32_e32 v142, v142, v66
	v_add_f32_e32 v143, v143, v67
	v_add_f32_e32 v140, v140, v60
	v_add_f32_e32 v141, v141, v61
	v_add_f32_e32 v142, v142, v62
	v_add_f32_e32 v143, v143, v63
	v_add_f32_e32 v140, v140, v56
	v_add_f32_e32 v141, v141, v57
	v_add_f32_e32 v142, v142, v58
	v_add_f32_e32 v143, v143, v59
	v_add_f32_e32 v140, v140, v52
	v_add_f32_e32 v141, v141, v53
	v_add_f32_e32 v142, v142, v54
	v_add_f32_e32 v143, v143, v55
	v_add_f32_e32 v140, v140, v48
	v_add_f32_e32 v141, v141, v49
	v_add_f32_e32 v142, v142, v50
	v_add_f32_e32 v143, v143, v51
	v_mul_f32_e32 v140, 0x3e000000, v140
	v_mul_f32_e32 v141, 0x3e000000, v141
	v_mul_f32_e32 v142, 0x3e000000, v142
	v_mul_f32_e32 v143, 0x3e000000, v143
	v_sub_f32_e32 v140, v140, v76
	v_sub_f32_e32 v141, v141, v77
	v_sub_f32_e32 v142, v142, v78
	v_sub_f32_e32 v143, v143, v79
	v_cvt_pk_bf16_f32 v182, v140, v141
	v_cvt_pk_bf16_f32 v183, v142, v143
	global_store_dwordx2 v11, v[152:153], s[24:25]
	s_add_u32 s24, s24, 0x800
	s_addc_u32 s25, s25, 0
	global_store_dwordx2 v11, v[154:155], s[24:25]
	s_add_u32 s24, s24, 0x800
	s_addc_u32 s25, s25, 0
	global_store_dwordx2 v11, v[156:157], s[24:25]
	s_add_u32 s24, s24, 0x800
	s_addc_u32 s25, s25, 0
	global_store_dwordx2 v11, v[158:159], s[24:25]
	s_add_u32 s24, s24, 0x800
	s_addc_u32 s25, s25, 0
	global_store_dwordx2 v11, v[160:161], s[24:25]
	s_add_u32 s24, s24, 0x800
	s_addc_u32 s25, s25, 0
	global_store_dwordx2 v11, v[162:163], s[24:25]
	s_add_u32 s24, s24, 0x800
	s_addc_u32 s25, s25, 0
	global_store_dwordx2 v11, v[164:165], s[24:25]
	s_add_u32 s24, s24, 0x800
	s_addc_u32 s25, s25, 0
	global_store_dwordx2 v11, v[166:167], s[24:25]
	s_add_u32 s24, s24, 0x800
	s_addc_u32 s25, s25, 0
	global_store_dwordx2 v11, v[168:169], s[24:25]
	s_add_u32 s24, s24, 0x800
	s_addc_u32 s25, s25, 0
	global_store_dwordx2 v11, v[170:171], s[24:25]
	s_add_u32 s24, s24, 0x800
	s_addc_u32 s25, s25, 0
	global_store_dwordx2 v11, v[172:173], s[24:25]
	s_add_u32 s24, s24, 0x800
	s_addc_u32 s25, s25, 0
	global_store_dwordx2 v11, v[174:175], s[24:25]
	s_add_u32 s24, s24, 0x800
	s_addc_u32 s25, s25, 0
	global_store_dwordx2 v11, v[176:177], s[24:25]
	s_add_u32 s24, s24, 0x800
	s_addc_u32 s25, s25, 0
	global_store_dwordx2 v11, v[178:179], s[24:25]
	s_add_u32 s24, s24, 0x800
	s_addc_u32 s25, s25, 0
	global_store_dwordx2 v11, v[180:181], s[24:25]
	s_add_u32 s24, s24, 0x800
	s_addc_u32 s25, s25, 0
	global_store_dwordx2 v11, v[182:183], s[24:25]
	s_add_u32 s24, s24, 0x800
	s_addc_u32 s25, s25, 0
	s_branch .Lp13f_next
.Lp13f_f3:
	s_sub_u32 s26, s20, 0
	s_lshl_b32 s27, s26, 12
	s_lshr_b32 s28, s26, 20
	s_add_u32 s22, s8, s27
	s_addc_u32 s23, s9, s28
	global_load_dwordx2 v[16:17], v11, s[22:23]
	s_add_u32 s22, s22, 0x1000
	s_addc_u32 s23, s23, 0
	global_load_dwordx2 v[20:21], v11, s[22:23]
	s_add_u32 s22, s22, 0x1000
	s_addc_u32 s23, s23, 0
	global_load_dwordx2 v[24:25], v11, s[22:23]
	s_add_u32 s22, s22, 0x1000
	s_addc_u32 s23, s23, 0
	global_load_dwordx2 v[28:29], v11, s[22:23]
	s_add_u32 s22, s22, 0x1000
	s_addc_u32 s23, s23, 0
	global_load_dwordx2 v[32:33], v11, s[22:23]
	s_add_u32 s22, s22, 0x1000
	s_addc_u32 s23, s23, 0
	global_load_dwordx2 v[36:37], v11, s[22:23]
	s_add_u32 s22, s22, 0x1000
	s_addc_u32 s23, s23, 0
	global_load_dwordx2 v[40:41], v11, s[22:23]
	s_add_u32 s22, s22, 0x1000
	s_addc_u32 s23, s23, 0
	global_load_dwordx2 v[44:45], v11, s[22:23]
	s_add_u32 s22, s22, 0x1000
	s_addc_u32 s23, s23, 0
	global_load_dwordx2 v[48:49], v11, s[22:23]
	s_add_u32 s22, s22, 0x1000
	s_addc_u32 s23, s23, 0
	global_load_dwordx2 v[52:53], v11, s[22:23]
	s_add_u32 s22, s22, 0x1000
	s_addc_u32 s23, s23, 0
	global_load_dwordx2 v[56:57], v11, s[22:23]
	s_add_u32 s22, s22, 0x1000
	s_addc_u32 s23, s23, 0
	global_load_dwordx2 v[60:61], v11, s[22:23]
	s_add_u32 s22, s22, 0x1000
	s_addc_u32 s23, s23, 0
	global_load_dwordx2 v[64:65], v11, s[22:23]
	s_add_u32 s22, s22, 0x1000
	s_addc_u32 s23, s23, 0
	global_load_dwordx2 v[68:69], v11, s[22:23]
	s_add_u32 s22, s22, 0x1000
	s_addc_u32 s23, s23, 0
	global_load_dwordx2 v[72:73], v11, s[22:23]
	s_add_u32 s22, s22, 0x1000
	s_addc_u32 s23, s23, 0
	global_load_dwordx2 v[76:77], v11, s[22:23]
	s_add_u32 s22, s22, 0x1000
	s_addc_u32 s23, s23, 0
	s_waitcnt vmcnt(15)
	v_and_b32_e32 v19, 0xffff0000, v17
	v_lshlrev_b32_e32 v18, 16, v17
	v_and_b32_e32 v17, 0xffff0000, v16
	v_lshlrev_b32_e32 v16, 16, v16
	v_mov_b32_e32 v140, v16
	v_mov_b32_e32 v141, v17
	v_mov_b32_e32 v142, v18
	v_mov_b32_e32 v143, v19
	v_mul_f32_e32 v140, 1.0, v140
	v_mul_f32_e32 v141, 1.0, v141
	v_mul_f32_e32 v142, 1.0, v142
	v_mul_f32_e32 v143, 1.0, v143
	v_sub_f32_e32 v140, v140, v16
	v_sub_f32_e32 v141, v141, v17
	v_sub_f32_e32 v142, v142, v18
	v_sub_f32_e32 v143, v143, v19
	v_cvt_pk_bf16_f32 v152, v140, v141
	v_cvt_pk_bf16_f32 v153, v142, v143
	s_waitcnt vmcnt(14)
	v_and_b32_e32 v23, 0xffff0000, v21
	v_lshlrev_b32_e32 v22, 16, v21
	v_and_b32_e32 v21, 0xffff0000, v20
	v_lshlrev_b32_e32 v20, 16, v20
	v_add_f32_e32 v140, v20, v16
	v_add_f32_e32 v141, v21, v17
	v_add_f32_e32 v142, v22, v18
	v_add_f32_e32 v143, v23, v19
	v_mul_f32_e32 v140, 0.5, v140
	v_mul_f32_e32 v141, 0.5, v141
	v_mul_f32_e32 v142, 0.5, v142
	v_mul_f32_e32 v143, 0.5, v143
	v_sub_f32_e32 v140, v140, v20
	v_sub_f32_e32 v141, v141, v21
	v_sub_f32_e32 v142, v142, v22
	v_sub_f32_e32 v143, v143, v23
	v_cvt_pk_bf16_f32 v154, v140, v141
	v_cvt_pk_bf16_f32 v155, v142, v143
	s_waitcnt vmcnt(13)
; DI float bflo(unsigned u) { return __uint_as_float(u << 16); }
; DI float bfhi(unsigned u) { return __uint_as_float(u & 0xffff0000u); }
; template <int WIN>
; DI void pool_elem(const Params& p, int row, int c) {
;     ...
;   unsigned uu = *(const unsigned*)(P2 + (size_t)row * 2048 + c);
;   const float u0 = bflo(uu), u1 = bfhi(uu);
;   float s0 = u0, s1 = u1, cnt;
;   if (row < NPR) {
;     const int t = row & 2047, b = row >> 11;
;     if (t >= WIN - 1) {
;       cnt = (float)WIN;
;       unsigned w[WIN - 1];
; #pragma unroll
;       for (int j = 1; j < WIN; ++j) w[j - 1] = *(const unsigned*)(P2 + (size_t)(row - j) * 2048 + c);
; #pragma unroll
;       for (int j = 1; j < WIN; ++j) { s0 += bflo(w[j - 1]); s1 += bfhi(w[j - 1]); }
;     } else {
;       cnt = (float)(t + 1);
;       for (int j = 1; j <= t; ++j) {
;         unsigned w = *(const unsigned*)(P2 + (size_t)(row - j) * 2048 + c);
;         s0 += bflo(w); s1 += bfhi(w);
;       }
;     }
;     ...
;   *(unsigned*)(p.MIX + (size_t)row * 1024 + c) = pack2(s0 / cnt - u0, s1 / cnt - u1);
	v_and_b32_e32 v27, 0xffff0000, v25
	v_lshlrev_b32_e32 v26, 16, v25
	v_and_b32_e32 v25, 0xffff0000, v24
	v_lshlrev_b32_e32 v24, 16, v24
	v_add_f32_e32 v140, v24, v20
	v_add_f32_e32 v141, v25, v21
	v_add_f32_e32 v142, v26, v22
	v_add_f32_e32 v143, v27, v23
	v_add_f32_e32 v140, v140, v16
	v_add_f32_e32 v141, v141, v17
	v_add_f32_e32 v142, v142, v18
	v_add_f32_e32 v143, v143, v19
	v_mov_b32_e32 v151, 0x40400000
	v_div_scale_f32 v146, s[26:27], v151, v151, v140
	v_rcp_f32_e32 v147, v146
	v_div_scale_f32 v148, vcc, v140, v151, v140
	v_fma_f32 v149, -v146, v147, 1.0
	v_fmac_f32_e32 v147, v149, v147
	v_mul_f32_e32 v149, v148, v147
	v_fma_f32 v150, -v146, v149, v148
	v_fmac_f32_e32 v149, v150, v147
	v_fma_f32 v146, -v146, v149, v148
	v_div_fmas_f32 v146, v146, v147, v149
	v_div_fixup_f32 v140, v146, v151, v140
	v_mov_b32_e32 v151, 0x40400000
	v_div_scale_f32 v146, s[26:27], v151, v151, v141
	v_rcp_f32_e32 v147, v146
	v_div_scale_f32 v148, vcc, v141, v151, v141
	v_fma_f32 v149, -v146, v147, 1.0
	v_fmac_f32_e32 v147, v149, v147
	v_mul_f32_e32 v149, v148, v147
	v_fma_f32 v150, -v146, v149, v148
	v_fmac_f32_e32 v149, v150, v147
	v_fma_f32 v146, -v146, v149, v148
	v_div_fmas_f32 v146, v146, v147, v149
	v_div_fixup_f32 v141, v146, v151, v141
	v_mov_b32_e32 v151, 0x40400000
	v_div_scale_f32 v146, s[26:27], v151, v151, v142
	v_rcp_f32_e32 v147, v146
	v_div_scale_f32 v148, vcc, v142, v151, v142
	v_fma_f32 v149, -v146, v147, 1.0
	v_fmac_f32_e32 v147, v149, v147
	v_mul_f32_e32 v149, v148, v147
	v_fma_f32 v150, -v146, v149, v148
	v_fmac_f32_e32 v149, v150, v147
	v_fma_f32 v146, -v146, v149, v148
	v_div_fmas_f32 v146, v146, v147, v149
	v_div_fixup_f32 v142, v146, v151, v142
	v_mov_b32_e32 v151, 0x40400000
	v_div_scale_f32 v146, s[26:27], v151, v151, v143
	v_rcp_f32_e32 v147, v146
	v_div_scale_f32 v148, vcc, v143, v151, v143
	v_fma_f32 v149, -v146, v147, 1.0
	v_fmac_f32_e32 v147, v149, v147
	v_mul_f32_e32 v149, v148, v147
	v_fma_f32 v150, -v146, v149, v148
	v_fmac_f32_e32 v149, v150, v147
	v_fma_f32 v146, -v146, v149, v148
	v_div_fmas_f32 v146, v146, v147, v149
	v_div_fixup_f32 v143, v146, v151, v143
	v_sub_f32_e32 v140, v140, v24
	v_sub_f32_e32 v141, v141, v25
	v_sub_f32_e32 v142, v142, v26
	v_sub_f32_e32 v143, v143, v27
	v_cvt_pk_bf16_f32 v156, v140, v141
	v_cvt_pk_bf16_f32 v157, v142, v143
	s_waitcnt vmcnt(12)
	v_and_b32_e32 v31, 0xffff0000, v29
	v_lshlrev_b32_e32 v30, 16, v29
	v_and_b32_e32 v29, 0xffff0000, v28
	v_lshlrev_b32_e32 v28, 16, v28
	v_add_f32_e32 v140, v28, v24
	v_add_f32_e32 v141, v29, v25
	v_add_f32_e32 v142, v30, v26
	v_add_f32_e32 v143, v31, v27
	v_add_f32_e32 v140, v140, v20
	v_add_f32_e32 v141, v141, v21
	v_add_f32_e32 v142, v142, v22
	v_add_f32_e32 v143, v143, v23
	v_add_f32_e32 v140, v140, v16
	v_add_f32_e32 v141, v141, v17
	v_add_f32_e32 v142, v142, v18
	v_add_f32_e32 v143, v143, v19
	v_mul_f32_e32 v140, 0x3e800000, v140
	v_mul_f32_e32 v141, 0x3e800000, v141
	v_mul_f32_e32 v142, 0x3e800000, v142
	v_mul_f32_e32 v143, 0x3e800000, v143
	v_sub_f32_e32 v140, v140, v28
	v_sub_f32_e32 v141, v141, v29
	v_sub_f32_e32 v142, v142, v30
	v_sub_f32_e32 v143, v143, v31
	v_cvt_pk_bf16_f32 v158, v140, v141
	v_cvt_pk_bf16_f32 v159, v142, v143
	s_waitcnt vmcnt(11)
	v_and_b32_e32 v35, 0xffff0000, v33
	v_lshlrev_b32_e32 v34, 16, v33
	v_and_b32_e32 v33, 0xffff0000, v32
	v_lshlrev_b32_e32 v32, 16, v32
	v_add_f32_e32 v140, v32, v28
	v_add_f32_e32 v141, v33, v29
	v_add_f32_e32 v142, v34, v30
	v_add_f32_e32 v143, v35, v31
	v_add_f32_e32 v140, v140, v24
	v_add_f32_e32 v141, v141, v25
	v_add_f32_e32 v142, v142, v26
	v_add_f32_e32 v143, v143, v27
	v_add_f32_e32 v140, v140, v20
	v_add_f32_e32 v141, v141, v21
	v_add_f32_e32 v142, v142, v22
	v_add_f32_e32 v143, v143, v23
	v_add_f32_e32 v140, v140, v16
	v_add_f32_e32 v141, v141, v17
	v_add_f32_e32 v142, v142, v18
	v_add_f32_e32 v143, v143, v19
	v_mov_b32_e32 v151, 0x40a00000
	v_div_scale_f32 v146, s[26:27], v151, v151, v140
	v_rcp_f32_e32 v147, v146
	v_div_scale_f32 v148, vcc, v140, v151, v140
	v_fma_f32 v149, -v146, v147, 1.0
	v_fmac_f32_e32 v147, v149, v147
	v_mul_f32_e32 v149, v148, v147
	v_fma_f32 v150, -v146, v149, v148
	v_fmac_f32_e32 v149, v150, v147
	v_fma_f32 v146, -v146, v149, v148
	v_div_fmas_f32 v146, v146, v147, v149
	v_div_fixup_f32 v140, v146, v151, v140
	v_mov_b32_e32 v151, 0x40a00000
	v_div_scale_f32 v146, s[26:27], v151, v151, v141
	v_rcp_f32_e32 v147, v146
	v_div_scale_f32 v148, vcc, v141, v151, v141
	v_fma_f32 v149, -v146, v147, 1.0
	v_fmac_f32_e32 v147, v149, v147
	v_mul_f32_e32 v149, v148, v147
	v_fma_f32 v150, -v146, v149, v148
	v_fmac_f32_e32 v149, v150, v147
	v_fma_f32 v146, -v146, v149, v148
	v_div_fmas_f32 v146, v146, v147, v149
	v_div_fixup_f32 v141, v146, v151, v141
	v_mov_b32_e32 v151, 0x40a00000
	v_div_scale_f32 v146, s[26:27], v151, v151, v142
	v_rcp_f32_e32 v147, v146
	v_div_scale_f32 v148, vcc, v142, v151, v142
	v_fma_f32 v149, -v146, v147, 1.0
	v_fmac_f32_e32 v147, v149, v147
	v_mul_f32_e32 v149, v148, v147
	v_fma_f32 v150, -v146, v149, v148
	v_fmac_f32_e32 v149, v150, v147
	v_fma_f32 v146, -v146, v149, v148
	v_div_fmas_f32 v146, v146, v147, v149
	v_div_fixup_f32 v142, v146, v151, v142
	v_mov_b32_e32 v151, 0x40a00000
	v_div_scale_f32 v146, s[26:27], v151, v151, v143
	v_rcp_f32_e32 v147, v146
	v_div_scale_f32 v148, vcc, v143, v151, v143
	v_fma_f32 v149, -v146, v147, 1.0
	v_fmac_f32_e32 v147, v149, v147
	v_mul_f32_e32 v149, v148, v147
	v_fma_f32 v150, -v146, v149, v148
	v_fmac_f32_e32 v149, v150, v147
	v_fma_f32 v146, -v146, v149, v148
	v_div_fmas_f32 v146, v146, v147, v149
	v_div_fixup_f32 v143, v146, v151, v143
	v_sub_f32_e32 v140, v140, v32
	v_sub_f32_e32 v141, v141, v33
	v_sub_f32_e32 v142, v142, v34
	v_sub_f32_e32 v143, v143, v35
	v_cvt_pk_bf16_f32 v160, v140, v141
	v_cvt_pk_bf16_f32 v161, v142, v143
	s_waitcnt vmcnt(10)
; DI float bflo(unsigned u) { return __uint_as_float(u << 16); }
; DI float bfhi(unsigned u) { return __uint_as_float(u & 0xffff0000u); }
; template <int WIN>
; DI void pool_elem(const Params& p, int row, int c) {
;     ...
;   unsigned uu = *(const unsigned*)(P2 + (size_t)row * 2048 + c);
;   const float u0 = bflo(uu), u1 = bfhi(uu);
;   float s0 = u0, s1 = u1, cnt;
;   if (row < NPR) {
;     const int t = row & 2047, b = row >> 11;
;     if (t >= WIN - 1) {
;       cnt = (float)WIN;
;       unsigned w[WIN - 1];
; #pragma unroll
;       for (int j = 1; j < WIN; ++j) w[j - 1] = *(const unsigned*)(P2 + (size_t)(row - j) * 2048 + c);
; #pragma unroll
;       for (int j = 1; j < WIN; ++j) { s0 += bflo(w[j - 1]); s1 += bfhi(w[j - 1]); }
;     } else {
;       cnt = (float)(t + 1);
;       for (int j = 1; j <= t; ++j) {
;         unsigned w = *(const unsigned*)(P2 + (size_t)(row - j) * 2048 + c);
;         s0 += bflo(w); s1 += bfhi(w);
;       }
;     }
;     ...
;   *(unsigned*)(p.MIX + (size_t)row * 1024 + c) = pack2(s0 / cnt - u0, s1 / cnt - u1);
	v_and_b32_e32 v39, 0xffff0000, v37
	v_lshlrev_b32_e32 v38, 16, v37
	v_and_b32_e32 v37, 0xffff0000, v36
	v_lshlrev_b32_e32 v36, 16, v36
	v_add_f32_e32 v140, v36, v32
	v_add_f32_e32 v141, v37, v33
	v_add_f32_e32 v142, v38, v34
	v_add_f32_e32 v143, v39, v35
	v_add_f32_e32 v140, v140, v28
	v_add_f32_e32 v141, v141, v29
	v_add_f32_e32 v142, v142, v30
	v_add_f32_e32 v143, v143, v31
	v_add_f32_e32 v140, v140, v24
	v_add_f32_e32 v141, v141, v25
	v_add_f32_e32 v142, v142, v26
	v_add_f32_e32 v143, v143, v27
	v_add_f32_e32 v140, v140, v20
	v_add_f32_e32 v141, v141, v21
	v_add_f32_e32 v142, v142, v22
	v_add_f32_e32 v143, v143, v23
	v_add_f32_e32 v140, v140, v16
	v_add_f32_e32 v141, v141, v17
	v_add_f32_e32 v142, v142, v18
	v_add_f32_e32 v143, v143, v19
	v_mov_b32_e32 v151, 0x40c00000
	v_div_scale_f32 v146, s[26:27], v151, v151, v140
	v_rcp_f32_e32 v147, v146
	v_div_scale_f32 v148, vcc, v140, v151, v140
	v_fma_f32 v149, -v146, v147, 1.0
	v_fmac_f32_e32 v147, v149, v147
	v_mul_f32_e32 v149, v148, v147
	v_fma_f32 v150, -v146, v149, v148
	v_fmac_f32_e32 v149, v150, v147
	v_fma_f32 v146, -v146, v149, v148
	v_div_fmas_f32 v146, v146, v147, v149
	v_div_fixup_f32 v140, v146, v151, v140
	v_mov_b32_e32 v151, 0x40c00000
	v_div_scale_f32 v146, s[26:27], v151, v151, v141
	v_rcp_f32_e32 v147, v146
	v_div_scale_f32 v148, vcc, v141, v151, v141
	v_fma_f32 v149, -v146, v147, 1.0
	v_fmac_f32_e32 v147, v149, v147
	v_mul_f32_e32 v149, v148, v147
	v_fma_f32 v150, -v146, v149, v148
	v_fmac_f32_e32 v149, v150, v147
	v_fma_f32 v146, -v146, v149, v148
	v_div_fmas_f32 v146, v146, v147, v149
	v_div_fixup_f32 v141, v146, v151, v141
	v_mov_b32_e32 v151, 0x40c00000
	v_div_scale_f32 v146, s[26:27], v151, v151, v142
	v_rcp_f32_e32 v147, v146
	v_div_scale_f32 v148, vcc, v142, v151, v142
	v_fma_f32 v149, -v146, v147, 1.0
	v_fmac_f32_e32 v147, v149, v147
	v_mul_f32_e32 v149, v148, v147
	v_fma_f32 v150, -v146, v149, v148
	v_fmac_f32_e32 v149, v150, v147
	v_fma_f32 v146, -v146, v149, v148
	v_div_fmas_f32 v146, v146, v147, v149
	v_div_fixup_f32 v142, v146, v151, v142
	v_mov_b32_e32 v151, 0x40c00000
	v_div_scale_f32 v146, s[26:27], v151, v151, v143
	v_rcp_f32_e32 v147, v146
	v_div_scale_f32 v148, vcc, v143, v151, v143
	v_fma_f32 v149, -v146, v147, 1.0
	v_fmac_f32_e32 v147, v149, v147
	v_mul_f32_e32 v149, v148, v147
	v_fma_f32 v150, -v146, v149, v148
	v_fmac_f32_e32 v149, v150, v147
	v_fma_f32 v146, -v146, v149, v148
	v_div_fmas_f32 v146, v146, v147, v149
	v_div_fixup_f32 v143, v146, v151, v143
	v_sub_f32_e32 v140, v140, v36
	v_sub_f32_e32 v141, v141, v37
	v_sub_f32_e32 v142, v142, v38
	v_sub_f32_e32 v143, v143, v39
	v_cvt_pk_bf16_f32 v162, v140, v141
	v_cvt_pk_bf16_f32 v163, v142, v143
	s_waitcnt vmcnt(9)
	v_and_b32_e32 v43, 0xffff0000, v41
	v_lshlrev_b32_e32 v42, 16, v41
	v_and_b32_e32 v41, 0xffff0000, v40
	v_lshlrev_b32_e32 v40, 16, v40
	v_add_f32_e32 v140, v40, v36
	v_add_f32_e32 v141, v41, v37
	v_add_f32_e32 v142, v42, v38
	v_add_f32_e32 v143, v43, v39
	v_add_f32_e32 v140, v140, v32
	v_add_f32_e32 v141, v141, v33
	v_add_f32_e32 v142, v142, v34
	v_add_f32_e32 v143, v143, v35
	v_add_f32_e32 v140, v140, v28
	v_add_f32_e32 v141, v141, v29
	v_add_f32_e32 v142, v142, v30
	v_add_f32_e32 v143, v143, v31
	v_add_f32_e32 v140, v140, v24
	v_add_f32_e32 v141, v141, v25
	v_add_f32_e32 v142, v142, v26
	v_add_f32_e32 v143, v143, v27
	v_add_f32_e32 v140, v140, v20
	v_add_f32_e32 v141, v141, v21
	v_add_f32_e32 v142, v142, v22
	v_add_f32_e32 v143, v143, v23
	v_add_f32_e32 v140, v140, v16
	v_add_f32_e32 v141, v141, v17
	v_add_f32_e32 v142, v142, v18
	v_add_f32_e32 v143, v143, v19
	v_mov_b32_e32 v151, 0x40e00000
	v_div_scale_f32 v146, s[26:27], v151, v151, v140
	v_rcp_f32_e32 v147, v146
	v_div_scale_f32 v148, vcc, v140, v151, v140
	v_fma_f32 v149, -v146, v147, 1.0
	v_fmac_f32_e32 v147, v149, v147
	v_mul_f32_e32 v149, v148, v147
	v_fma_f32 v150, -v146, v149, v148
	v_fmac_f32_e32 v149, v150, v147
	v_fma_f32 v146, -v146, v149, v148
	v_div_fmas_f32 v146, v146, v147, v149
	v_div_fixup_f32 v140, v146, v151, v140
	v_mov_b32_e32 v151, 0x40e00000
	v_div_scale_f32 v146, s[26:27], v151, v151, v141
	v_rcp_f32_e32 v147, v146
	v_div_scale_f32 v148, vcc, v141, v151, v141
	v_fma_f32 v149, -v146, v147, 1.0
	v_fmac_f32_e32 v147, v149, v147
	v_mul_f32_e32 v149, v148, v147
	v_fma_f32 v150, -v146, v149, v148
	v_fmac_f32_e32 v149, v150, v147
	v_fma_f32 v146, -v146, v149, v148
	v_div_fmas_f32 v146, v146, v147, v149
	v_div_fixup_f32 v141, v146, v151, v141
	v_mov_b32_e32 v151, 0x40e00000
	v_div_scale_f32 v146, s[26:27], v151, v151, v142
	v_rcp_f32_e32 v147, v146
	v_div_scale_f32 v148, vcc, v142, v151, v142
	v_fma_f32 v149, -v146, v147, 1.0
	v_fmac_f32_e32 v147, v149, v147
	v_mul_f32_e32 v149, v148, v147
	v_fma_f32 v150, -v146, v149, v148
	v_fmac_f32_e32 v149, v150, v147
	v_fma_f32 v146, -v146, v149, v148
	v_div_fmas_f32 v146, v146, v147, v149
	v_div_fixup_f32 v142, v146, v151, v142
	v_mov_b32_e32 v151, 0x40e00000
	v_div_scale_f32 v146, s[26:27], v151, v151, v143
	v_rcp_f32_e32 v147, v146
	v_div_scale_f32 v148, vcc, v143, v151, v143
	v_fma_f32 v149, -v146, v147, 1.0
	v_fmac_f32_e32 v147, v149, v147
	v_mul_f32_e32 v149, v148, v147
	v_fma_f32 v150, -v146, v149, v148
	v_fmac_f32_e32 v149, v150, v147
	v_fma_f32 v146, -v146, v149, v148
	v_div_fmas_f32 v146, v146, v147, v149
	v_div_fixup_f32 v143, v146, v151, v143
	v_sub_f32_e32 v140, v140, v40
	v_sub_f32_e32 v141, v141, v41
	v_sub_f32_e32 v142, v142, v42
	v_sub_f32_e32 v143, v143, v43
	v_cvt_pk_bf16_f32 v164, v140, v141
	v_cvt_pk_bf16_f32 v165, v142, v143
	s_waitcnt vmcnt(8)
; DI float bflo(unsigned u) { return __uint_as_float(u << 16); }
; DI float bfhi(unsigned u) { return __uint_as_float(u & 0xffff0000u); }
; template <int WIN>
; DI void pool_elem(const Params& p, int row, int c) {
;     ...
;   unsigned uu = *(const unsigned*)(P2 + (size_t)row * 2048 + c);
;   const float u0 = bflo(uu), u1 = bfhi(uu);
;   float s0 = u0, s1 = u1, cnt;
;   if (row < NPR) {
;     const int t = row & 2047, b = row >> 11;
;     if (t >= WIN - 1) {
;       cnt = (float)WIN;
;       unsigned w[WIN - 1];
; #pragma unroll
;       for (int j = 1; j < WIN; ++j) w[j - 1] = *(const unsigned*)(P2 + (size_t)(row - j) * 2048 + c);
; #pragma unroll
;       for (int j = 1; j < WIN; ++j) { s0 += bflo(w[j - 1]); s1 += bfhi(w[j - 1]); }
;     } else {
;       cnt = (float)(t + 1);
;       for (int j = 1; j <= t; ++j) {
;         unsigned w = *(const unsigned*)(P2 + (size_t)(row - j) * 2048 + c);
;         s0 += bflo(w); s1 += bfhi(w);
;       }
;     }
;     ...
;   *(unsigned*)(p.MIX + (size_t)row * 1024 + c) = pack2(s0 / cnt - u0, s1 / cnt - u1);
	v_and_b32_e32 v47, 0xffff0000, v45
	v_lshlrev_b32_e32 v46, 16, v45
	v_and_b32_e32 v45, 0xffff0000, v44
	v_lshlrev_b32_e32 v44, 16, v44
	v_add_f32_e32 v140, v44, v40
	v_add_f32_e32 v141, v45, v41
	v_add_f32_e32 v142, v46, v42
	v_add_f32_e32 v143, v47, v43
	v_add_f32_e32 v140, v140, v36
	v_add_f32_e32 v141, v141, v37
	v_add_f32_e32 v142, v142, v38
	v_add_f32_e32 v143, v143, v39
	v_add_f32_e32 v140, v140, v32
	v_add_f32_e32 v141, v141, v33
	v_add_f32_e32 v142, v142, v34
	v_add_f32_e32 v143, v143, v35
	v_add_f32_e32 v140, v140, v28
	v_add_f32_e32 v141, v141, v29
	v_add_f32_e32 v142, v142, v30
	v_add_f32_e32 v143, v143, v31
	v_add_f32_e32 v140, v140, v24
	v_add_f32_e32 v141, v141, v25
	v_add_f32_e32 v142, v142, v26
	v_add_f32_e32 v143, v143, v27
	v_add_f32_e32 v140, v140, v20
	v_add_f32_e32 v141, v141, v21
	v_add_f32_e32 v142, v142, v22
	v_add_f32_e32 v143, v143, v23
	v_add_f32_e32 v140, v140, v16
	v_add_f32_e32 v141, v141, v17
	v_add_f32_e32 v142, v142, v18
	v_add_f32_e32 v143, v143, v19
	v_mul_f32_e32 v140, 0x3e000000, v140
	v_mul_f32_e32 v141, 0x3e000000, v141
	v_mul_f32_e32 v142, 0x3e000000, v142
	v_mul_f32_e32 v143, 0x3e000000, v143
	v_sub_f32_e32 v140, v140, v44
	v_sub_f32_e32 v141, v141, v45
	v_sub_f32_e32 v142, v142, v46
	v_sub_f32_e32 v143, v143, v47
	v_cvt_pk_bf16_f32 v166, v140, v141
	v_cvt_pk_bf16_f32 v167, v142, v143
	s_waitcnt vmcnt(7)
	v_and_b32_e32 v51, 0xffff0000, v49
	v_lshlrev_b32_e32 v50, 16, v49
	v_and_b32_e32 v49, 0xffff0000, v48
	v_lshlrev_b32_e32 v48, 16, v48
	v_add_f32_e32 v140, v48, v44
	v_add_f32_e32 v141, v49, v45
	v_add_f32_e32 v142, v50, v46
	v_add_f32_e32 v143, v51, v47
	v_add_f32_e32 v140, v140, v40
	v_add_f32_e32 v141, v141, v41
	v_add_f32_e32 v142, v142, v42
	v_add_f32_e32 v143, v143, v43
	v_add_f32_e32 v140, v140, v36
	v_add_f32_e32 v141, v141, v37
	v_add_f32_e32 v142, v142, v38
	v_add_f32_e32 v143, v143, v39
	v_add_f32_e32 v140, v140, v32
	v_add_f32_e32 v141, v141, v33
	v_add_f32_e32 v142, v142, v34
	v_add_f32_e32 v143, v143, v35
	v_add_f32_e32 v140, v140, v28
	v_add_f32_e32 v141, v141, v29
	v_add_f32_e32 v142, v142, v30
	v_add_f32_e32 v143, v143, v31
	v_add_f32_e32 v140, v140, v24
	v_add_f32_e32 v141, v141, v25
	v_add_f32_e32 v142, v142, v26
	v_add_f32_e32 v143, v143, v27
	v_add_f32_e32 v140, v140, v20
	v_add_f32_e32 v141, v141, v21
	v_add_f32_e32 v142, v142, v22
	v_add_f32_e32 v143, v143, v23
	v_add_f32_e32 v140, v140, v16
	v_add_f32_e32 v141, v141, v17
	v_add_f32_e32 v142, v142, v18
	v_add_f32_e32 v143, v143, v19
	v_mov_b32_e32 v151, 0x41100000
	v_div_scale_f32 v146, s[26:27], v151, v151, v140
	v_rcp_f32_e32 v147, v146
	v_div_scale_f32 v148, vcc, v140, v151, v140
	v_fma_f32 v149, -v146, v147, 1.0
	v_fmac_f32_e32 v147, v149, v147
	v_mul_f32_e32 v149, v148, v147
	v_fma_f32 v150, -v146, v149, v148
	v_fmac_f32_e32 v149, v150, v147
	v_fma_f32 v146, -v146, v149, v148
	v_div_fmas_f32 v146, v146, v147, v149
	v_div_fixup_f32 v140, v146, v151, v140
	v_mov_b32_e32 v151, 0x41100000
	v_div_scale_f32 v146, s[26:27], v151, v151, v141
	v_rcp_f32_e32 v147, v146
	v_div_scale_f32 v148, vcc, v141, v151, v141
	v_fma_f32 v149, -v146, v147, 1.0
	v_fmac_f32_e32 v147, v149, v147
	v_mul_f32_e32 v149, v148, v147
	v_fma_f32 v150, -v146, v149, v148
	v_fmac_f32_e32 v149, v150, v147
	v_fma_f32 v146, -v146, v149, v148
	v_div_fmas_f32 v146, v146, v147, v149
	v_div_fixup_f32 v141, v146, v151, v141
	v_mov_b32_e32 v151, 0x41100000
	v_div_scale_f32 v146, s[26:27], v151, v151, v142
	v_rcp_f32_e32 v147, v146
	v_div_scale_f32 v148, vcc, v142, v151, v142
	v_fma_f32 v149, -v146, v147, 1.0
	v_fmac_f32_e32 v147, v149, v147
	v_mul_f32_e32 v149, v148, v147
	v_fma_f32 v150, -v146, v149, v148
	v_fmac_f32_e32 v149, v150, v147
	v_fma_f32 v146, -v146, v149, v148
	v_div_fmas_f32 v146, v146, v147, v149
	v_div_fixup_f32 v142, v146, v151, v142
	v_mov_b32_e32 v151, 0x41100000
	v_div_scale_f32 v146, s[26:27], v151, v151, v143
	v_rcp_f32_e32 v147, v146
	v_div_scale_f32 v148, vcc, v143, v151, v143
	v_fma_f32 v149, -v146, v147, 1.0
	v_fmac_f32_e32 v147, v149, v147
	v_mul_f32_e32 v149, v148, v147
	v_fma_f32 v150, -v146, v149, v148
	v_fmac_f32_e32 v149, v150, v147
	v_fma_f32 v146, -v146, v149, v148
	v_div_fmas_f32 v146, v146, v147, v149
	v_div_fixup_f32 v143, v146, v151, v143
	v_sub_f32_e32 v140, v140, v48
	v_sub_f32_e32 v141, v141, v49
	v_sub_f32_e32 v142, v142, v50
	v_sub_f32_e32 v143, v143, v51
	v_cvt_pk_bf16_f32 v168, v140, v141
	v_cvt_pk_bf16_f32 v169, v142, v143
	s_waitcnt vmcnt(6)
; DI float bflo(unsigned u) { return __uint_as_float(u << 16); }
; DI float bfhi(unsigned u) { return __uint_as_float(u & 0xffff0000u); }
; template <int WIN>
; DI void pool_elem(const Params& p, int row, int c) {
;     ...
;   unsigned uu = *(const unsigned*)(P2 + (size_t)row * 2048 + c);
;   const float u0 = bflo(uu), u1 = bfhi(uu);
;   float s0 = u0, s1 = u1, cnt;
;   if (row < NPR) {
;     const int t = row & 2047, b = row >> 11;
;     if (t >= WIN - 1) {
;       cnt = (float)WIN;
;       unsigned w[WIN - 1];
; #pragma unroll
;       for (int j = 1; j < WIN; ++j) w[j - 1] = *(const unsigned*)(P2 + (size_t)(row - j) * 2048 + c);
; #pragma unroll
;       for (int j = 1; j < WIN; ++j) { s0 += bflo(w[j - 1]); s1 += bfhi(w[j - 1]); }
;     } else {
;       cnt = (float)(t + 1);
;       for (int j = 1; j <= t; ++j) {
;         unsigned w = *(const unsigned*)(P2 + (size_t)(row - j) * 2048 + c);
;         s0 += bflo(w); s1 += bfhi(w);
;       }
;     }
;     ...
;   *(unsigned*)(p.MIX + (size_t)row * 1024 + c) = pack2(s0 / cnt - u0, s1 / cnt - u1);
	v_and_b32_e32 v55, 0xffff0000, v53
	v_lshlrev_b32_e32 v54, 16, v53
	v_and_b32_e32 v53, 0xffff0000, v52
	v_lshlrev_b32_e32 v52, 16, v52
	v_add_f32_e32 v140, v52, v48
	v_add_f32_e32 v141, v53, v49
	v_add_f32_e32 v142, v54, v50
	v_add_f32_e32 v143, v55, v51
	v_add_f32_e32 v140, v140, v44
	v_add_f32_e32 v141, v141, v45
	v_add_f32_e32 v142, v142, v46
	v_add_f32_e32 v143, v143, v47
	v_add_f32_e32 v140, v140, v40
	v_add_f32_e32 v141, v141, v41
	v_add_f32_e32 v142, v142, v42
	v_add_f32_e32 v143, v143, v43
	v_add_f32_e32 v140, v140, v36
	v_add_f32_e32 v141, v141, v37
	v_add_f32_e32 v142, v142, v38
	v_add_f32_e32 v143, v143, v39
	v_add_f32_e32 v140, v140, v32
	v_add_f32_e32 v141, v141, v33
	v_add_f32_e32 v142, v142, v34
	v_add_f32_e32 v143, v143, v35
	v_add_f32_e32 v140, v140, v28
	v_add_f32_e32 v141, v141, v29
	v_add_f32_e32 v142, v142, v30
	v_add_f32_e32 v143, v143, v31
	v_add_f32_e32 v140, v140, v24
	v_add_f32_e32 v141, v141, v25
	v_add_f32_e32 v142, v142, v26
	v_add_f32_e32 v143, v143, v27
	v_add_f32_e32 v140, v140, v20
	v_add_f32_e32 v141, v141, v21
	v_add_f32_e32 v142, v142, v22
	v_add_f32_e32 v143, v143, v23
	v_add_f32_e32 v140, v140, v16
	v_add_f32_e32 v141, v141, v17
	v_add_f32_e32 v142, v142, v18
	v_add_f32_e32 v143, v143, v19
	v_mov_b32_e32 v151, 0x41200000
	v_div_scale_f32 v146, s[26:27], v151, v151, v140
	v_rcp_f32_e32 v147, v146
	v_div_scale_f32 v148, vcc, v140, v151, v140
	v_fma_f32 v149, -v146, v147, 1.0
	v_fmac_f32_e32 v147, v149, v147
	v_mul_f32_e32 v149, v148, v147
	v_fma_f32 v150, -v146, v149, v148
	v_fmac_f32_e32 v149, v150, v147
	v_fma_f32 v146, -v146, v149, v148
	v_div_fmas_f32 v146, v146, v147, v149
	v_div_fixup_f32 v140, v146, v151, v140
	v_mov_b32_e32 v151, 0x41200000
	v_div_scale_f32 v146, s[26:27], v151, v151, v141
	v_rcp_f32_e32 v147, v146
	v_div_scale_f32 v148, vcc, v141, v151, v141
	v_fma_f32 v149, -v146, v147, 1.0
	v_fmac_f32_e32 v147, v149, v147
	v_mul_f32_e32 v149, v148, v147
	v_fma_f32 v150, -v146, v149, v148
	v_fmac_f32_e32 v149, v150, v147
	v_fma_f32 v146, -v146, v149, v148
	v_div_fmas_f32 v146, v146, v147, v149
	v_div_fixup_f32 v141, v146, v151, v141
	v_mov_b32_e32 v151, 0x41200000
	v_div_scale_f32 v146, s[26:27], v151, v151, v142
	v_rcp_f32_e32 v147, v146
	v_div_scale_f32 v148, vcc, v142, v151, v142
	v_fma_f32 v149, -v146, v147, 1.0
	v_fmac_f32_e32 v147, v149, v147
	v_mul_f32_e32 v149, v148, v147
	v_fma_f32 v150, -v146, v149, v148
	v_fmac_f32_e32 v149, v150, v147
	v_fma_f32 v146, -v146, v149, v148
	v_div_fmas_f32 v146, v146, v147, v149
	v_div_fixup_f32 v142, v146, v151, v142
	v_mov_b32_e32 v151, 0x41200000
	v_div_scale_f32 v146, s[26:27], v151, v151, v143
	v_rcp_f32_e32 v147, v146
	v_div_scale_f32 v148, vcc, v143, v151, v143
	v_fma_f32 v149, -v146, v147, 1.0
	v_fmac_f32_e32 v147, v149, v147
	v_mul_f32_e32 v149, v148, v147
	v_fma_f32 v150, -v146, v149, v148
	v_fmac_f32_e32 v149, v150, v147
	v_fma_f32 v146, -v146, v149, v148
	v_div_fmas_f32 v146, v146, v147, v149
	v_div_fixup_f32 v143, v146, v151, v143
	v_sub_f32_e32 v140, v140, v52
	v_sub_f32_e32 v141, v141, v53
	v_sub_f32_e32 v142, v142, v54
	v_sub_f32_e32 v143, v143, v55
	v_cvt_pk_bf16_f32 v170, v140, v141
	v_cvt_pk_bf16_f32 v171, v142, v143
	s_waitcnt vmcnt(5)
	v_and_b32_e32 v59, 0xffff0000, v57
	v_lshlrev_b32_e32 v58, 16, v57
	v_and_b32_e32 v57, 0xffff0000, v56
	v_lshlrev_b32_e32 v56, 16, v56
	v_add_f32_e32 v140, v56, v52
	v_add_f32_e32 v141, v57, v53
	v_add_f32_e32 v142, v58, v54
	v_add_f32_e32 v143, v59, v55
	v_add_f32_e32 v140, v140, v48
	v_add_f32_e32 v141, v141, v49
	v_add_f32_e32 v142, v142, v50
	v_add_f32_e32 v143, v143, v51
	v_add_f32_e32 v140, v140, v44
	v_add_f32_e32 v141, v141, v45
	v_add_f32_e32 v142, v142, v46
	v_add_f32_e32 v143, v143, v47
	v_add_f32_e32 v140, v140, v40
	v_add_f32_e32 v141, v141, v41
	v_add_f32_e32 v142, v142, v42
	v_add_f32_e32 v143, v143, v43
	v_add_f32_e32 v140, v140, v36
	v_add_f32_e32 v141, v141, v37
	v_add_f32_e32 v142, v142, v38
	v_add_f32_e32 v143, v143, v39
	v_add_f32_e32 v140, v140, v32
	v_add_f32_e32 v141, v141, v33
	v_add_f32_e32 v142, v142, v34
	v_add_f32_e32 v143, v143, v35
	v_add_f32_e32 v140, v140, v28
	v_add_f32_e32 v141, v141, v29
	v_add_f32_e32 v142, v142, v30
	v_add_f32_e32 v143, v143, v31
	v_add_f32_e32 v140, v140, v24
	v_add_f32_e32 v141, v141, v25
	v_add_f32_e32 v142, v142, v26
	v_add_f32_e32 v143, v143, v27
	v_add_f32_e32 v140, v140, v20
	v_add_f32_e32 v141, v141, v21
	v_add_f32_e32 v142, v142, v22
	v_add_f32_e32 v143, v143, v23
	v_add_f32_e32 v140, v140, v16
	v_add_f32_e32 v141, v141, v17
	v_add_f32_e32 v142, v142, v18
	v_add_f32_e32 v143, v143, v19
	v_mov_b32_e32 v151, 0x41300000
	v_div_scale_f32 v146, s[26:27], v151, v151, v140
	v_rcp_f32_e32 v147, v146
	v_div_scale_f32 v148, vcc, v140, v151, v140
	v_fma_f32 v149, -v146, v147, 1.0
	v_fmac_f32_e32 v147, v149, v147
	v_mul_f32_e32 v149, v148, v147
	v_fma_f32 v150, -v146, v149, v148
	v_fmac_f32_e32 v149, v150, v147
	v_fma_f32 v146, -v146, v149, v148
	v_div_fmas_f32 v146, v146, v147, v149
	v_div_fixup_f32 v140, v146, v151, v140
	v_mov_b32_e32 v151, 0x41300000
	v_div_scale_f32 v146, s[26:27], v151, v151, v141
	v_rcp_f32_e32 v147, v146
	v_div_scale_f32 v148, vcc, v141, v151, v141
	v_fma_f32 v149, -v146, v147, 1.0
	v_fmac_f32_e32 v147, v149, v147
	v_mul_f32_e32 v149, v148, v147
	v_fma_f32 v150, -v146, v149, v148
	v_fmac_f32_e32 v149, v150, v147
	v_fma_f32 v146, -v146, v149, v148
	v_div_fmas_f32 v146, v146, v147, v149
	v_div_fixup_f32 v141, v146, v151, v141
	v_mov_b32_e32 v151, 0x41300000
	v_div_scale_f32 v146, s[26:27], v151, v151, v142
	v_rcp_f32_e32 v147, v146
	v_div_scale_f32 v148, vcc, v142, v151, v142
	v_fma_f32 v149, -v146, v147, 1.0
	v_fmac_f32_e32 v147, v149, v147
	v_mul_f32_e32 v149, v148, v147
	v_fma_f32 v150, -v146, v149, v148
	v_fmac_f32_e32 v149, v150, v147
	v_fma_f32 v146, -v146, v149, v148
	v_div_fmas_f32 v146, v146, v147, v149
	v_div_fixup_f32 v142, v146, v151, v142
	v_mov_b32_e32 v151, 0x41300000
	v_div_scale_f32 v146, s[26:27], v151, v151, v143
	v_rcp_f32_e32 v147, v146
	v_div_scale_f32 v148, vcc, v143, v151, v143
	v_fma_f32 v149, -v146, v147, 1.0
	v_fmac_f32_e32 v147, v149, v147
	v_mul_f32_e32 v149, v148, v147
	v_fma_f32 v150, -v146, v149, v148
	v_fmac_f32_e32 v149, v150, v147
	v_fma_f32 v146, -v146, v149, v148
	v_div_fmas_f32 v146, v146, v147, v149
	v_div_fixup_f32 v143, v146, v151, v143
	v_sub_f32_e32 v140, v140, v56
	v_sub_f32_e32 v141, v141, v57
	v_sub_f32_e32 v142, v142, v58
	v_sub_f32_e32 v143, v143, v59
	v_cvt_pk_bf16_f32 v172, v140, v141
	v_cvt_pk_bf16_f32 v173, v142, v143
	s_waitcnt vmcnt(4)
; DI float bflo(unsigned u) { return __uint_as_float(u << 16); }
; DI float bfhi(unsigned u) { return __uint_as_float(u & 0xffff0000u); }
; template <int WIN>
; DI void pool_elem(const Params& p, int row, int c) {
;     ...
;   unsigned uu = *(const unsigned*)(P2 + (size_t)row * 2048 + c);
;   const float u0 = bflo(uu), u1 = bfhi(uu);
;   float s0 = u0, s1 = u1, cnt;
;   if (row < NPR) {
;     const int t = row & 2047, b = row >> 11;
;     if (t >= WIN - 1) {
;       cnt = (float)WIN;
;       unsigned w[WIN - 1];
; #pragma unroll
;       for (int j = 1; j < WIN; ++j) w[j - 1] = *(const unsigned*)(P2 + (size_t)(row - j) * 2048 + c);
; #pragma unroll
;       for (int j = 1; j < WIN; ++j) { s0 += bflo(w[j - 1]); s1 += bfhi(w[j - 1]); }
;     } else {
;       cnt = (float)(t + 1);
;       for (int j = 1; j <= t; ++j) {
;         unsigned w = *(const unsigned*)(P2 + (size_t)(row - j) * 2048 + c);
;         s0 += bflo(w); s1 += bfhi(w);
;       }
;     }
;     ...
;   *(unsigned*)(p.MIX + (size_t)row * 1024 + c) = pack2(s0 / cnt - u0, s1 / cnt - u1);
	v_and_b32_e32 v63, 0xffff0000, v61
	v_lshlrev_b32_e32 v62, 16, v61
	v_and_b32_e32 v61, 0xffff0000, v60
	v_lshlrev_b32_e32 v60, 16, v60
	v_add_f32_e32 v140, v60, v56
	v_add_f32_e32 v141, v61, v57
	v_add_f32_e32 v142, v62, v58
	v_add_f32_e32 v143, v63, v59
	v_add_f32_e32 v140, v140, v52
	v_add_f32_e32 v141, v141, v53
	v_add_f32_e32 v142, v142, v54
	v_add_f32_e32 v143, v143, v55
	v_add_f32_e32 v140, v140, v48
	v_add_f32_e32 v141, v141, v49
	v_add_f32_e32 v142, v142, v50
	v_add_f32_e32 v143, v143, v51
	v_add_f32_e32 v140, v140, v44
	v_add_f32_e32 v141, v141, v45
	v_add_f32_e32 v142, v142, v46
	v_add_f32_e32 v143, v143, v47
	v_add_f32_e32 v140, v140, v40
	v_add_f32_e32 v141, v141, v41
	v_add_f32_e32 v142, v142, v42
	v_add_f32_e32 v143, v143, v43
	v_add_f32_e32 v140, v140, v36
	v_add_f32_e32 v141, v141, v37
	v_add_f32_e32 v142, v142, v38
	v_add_f32_e32 v143, v143, v39
	v_add_f32_e32 v140, v140, v32
	v_add_f32_e32 v141, v141, v33
	v_add_f32_e32 v142, v142, v34
	v_add_f32_e32 v143, v143, v35
	v_add_f32_e32 v140, v140, v28
	v_add_f32_e32 v141, v141, v29
	v_add_f32_e32 v142, v142, v30
	v_add_f32_e32 v143, v143, v31
	v_add_f32_e32 v140, v140, v24
	v_add_f32_e32 v141, v141, v25
	v_add_f32_e32 v142, v142, v26
	v_add_f32_e32 v143, v143, v27
	v_add_f32_e32 v140, v140, v20
	v_add_f32_e32 v141, v141, v21
	v_add_f32_e32 v142, v142, v22
	v_add_f32_e32 v143, v143, v23
	v_add_f32_e32 v140, v140, v16
	v_add_f32_e32 v141, v141, v17
	v_add_f32_e32 v142, v142, v18
	v_add_f32_e32 v143, v143, v19
	v_mov_b32_e32 v151, 0x41400000
	v_div_scale_f32 v146, s[26:27], v151, v151, v140
	v_rcp_f32_e32 v147, v146
	v_div_scale_f32 v148, vcc, v140, v151, v140
	v_fma_f32 v149, -v146, v147, 1.0
	v_fmac_f32_e32 v147, v149, v147
	v_mul_f32_e32 v149, v148, v147
	v_fma_f32 v150, -v146, v149, v148
	v_fmac_f32_e32 v149, v150, v147
	v_fma_f32 v146, -v146, v149, v148
	v_div_fmas_f32 v146, v146, v147, v149
	v_div_fixup_f32 v140, v146, v151, v140
	v_mov_b32_e32 v151, 0x41400000
	v_div_scale_f32 v146, s[26:27], v151, v151, v141
	v_rcp_f32_e32 v147, v146
	v_div_scale_f32 v148, vcc, v141, v151, v141
	v_fma_f32 v149, -v146, v147, 1.0
	v_fmac_f32_e32 v147, v149, v147
	v_mul_f32_e32 v149, v148, v147
	v_fma_f32 v150, -v146, v149, v148
	v_fmac_f32_e32 v149, v150, v147
	v_fma_f32 v146, -v146, v149, v148
	v_div_fmas_f32 v146, v146, v147, v149
	v_div_fixup_f32 v141, v146, v151, v141
	v_mov_b32_e32 v151, 0x41400000
	v_div_scale_f32 v146, s[26:27], v151, v151, v142
	v_rcp_f32_e32 v147, v146
	v_div_scale_f32 v148, vcc, v142, v151, v142
	v_fma_f32 v149, -v146, v147, 1.0
	v_fmac_f32_e32 v147, v149, v147
	v_mul_f32_e32 v149, v148, v147
	v_fma_f32 v150, -v146, v149, v148
	v_fmac_f32_e32 v149, v150, v147
	v_fma_f32 v146, -v146, v149, v148
	v_div_fmas_f32 v146, v146, v147, v149
	v_div_fixup_f32 v142, v146, v151, v142
	v_mov_b32_e32 v151, 0x41400000
	v_div_scale_f32 v146, s[26:27], v151, v151, v143
	v_rcp_f32_e32 v147, v146
	v_div_scale_f32 v148, vcc, v143, v151, v143
	v_fma_f32 v149, -v146, v147, 1.0
	v_fmac_f32_e32 v147, v149, v147
	v_mul_f32_e32 v149, v148, v147
	v_fma_f32 v150, -v146, v149, v148
	v_fmac_f32_e32 v149, v150, v147
	v_fma_f32 v146, -v146, v149, v148
	v_div_fmas_f32 v146, v146, v147, v149
	v_div_fixup_f32 v143, v146, v151, v143
	v_sub_f32_e32 v140, v140, v60
	v_sub_f32_e32 v141, v141, v61
	v_sub_f32_e32 v142, v142, v62
	v_sub_f32_e32 v143, v143, v63
	v_cvt_pk_bf16_f32 v174, v140, v141
	v_cvt_pk_bf16_f32 v175, v142, v143
	s_waitcnt vmcnt(3)
	v_and_b32_e32 v67, 0xffff0000, v65
	v_lshlrev_b32_e32 v66, 16, v65
	v_and_b32_e32 v65, 0xffff0000, v64
	v_lshlrev_b32_e32 v64, 16, v64
	v_add_f32_e32 v140, v64, v60
	v_add_f32_e32 v141, v65, v61
	v_add_f32_e32 v142, v66, v62
	v_add_f32_e32 v143, v67, v63
	v_add_f32_e32 v140, v140, v56
	v_add_f32_e32 v141, v141, v57
	v_add_f32_e32 v142, v142, v58
	v_add_f32_e32 v143, v143, v59
	v_add_f32_e32 v140, v140, v52
	v_add_f32_e32 v141, v141, v53
	v_add_f32_e32 v142, v142, v54
	v_add_f32_e32 v143, v143, v55
	v_add_f32_e32 v140, v140, v48
	v_add_f32_e32 v141, v141, v49
	v_add_f32_e32 v142, v142, v50
	v_add_f32_e32 v143, v143, v51
	v_add_f32_e32 v140, v140, v44
	v_add_f32_e32 v141, v141, v45
	v_add_f32_e32 v142, v142, v46
	v_add_f32_e32 v143, v143, v47
	v_add_f32_e32 v140, v140, v40
	v_add_f32_e32 v141, v141, v41
	v_add_f32_e32 v142, v142, v42
	v_add_f32_e32 v143, v143, v43
	v_add_f32_e32 v140, v140, v36
	v_add_f32_e32 v141, v141, v37
	v_add_f32_e32 v142, v142, v38
	v_add_f32_e32 v143, v143, v39
	v_add_f32_e32 v140, v140, v32
	v_add_f32_e32 v141, v141, v33
	v_add_f32_e32 v142, v142, v34
	v_add_f32_e32 v143, v143, v35
	v_add_f32_e32 v140, v140, v28
	v_add_f32_e32 v141, v141, v29
	v_add_f32_e32 v142, v142, v30
	v_add_f32_e32 v143, v143, v31
	v_add_f32_e32 v140, v140, v24
	v_add_f32_e32 v141, v141, v25
	v_add_f32_e32 v142, v142, v26
	v_add_f32_e32 v143, v143, v27
	v_add_f32_e32 v140, v140, v20
	v_add_f32_e32 v141, v141, v21
	v_add_f32_e32 v142, v142, v22
	v_add_f32_e32 v143, v143, v23
	v_add_f32_e32 v140, v140, v16
	v_add_f32_e32 v141, v141, v17
	v_add_f32_e32 v142, v142, v18
	v_add_f32_e32 v143, v143, v19
	v_mov_b32_e32 v151, 0x41500000
	v_div_scale_f32 v146, s[26:27], v151, v151, v140
	v_rcp_f32_e32 v147, v146
	v_div_scale_f32 v148, vcc, v140, v151, v140
	v_fma_f32 v149, -v146, v147, 1.0
	v_fmac_f32_e32 v147, v149, v147
	v_mul_f32_e32 v149, v148, v147
	v_fma_f32 v150, -v146, v149, v148
	v_fmac_f32_e32 v149, v150, v147
	v_fma_f32 v146, -v146, v149, v148
	v_div_fmas_f32 v146, v146, v147, v149
	v_div_fixup_f32 v140, v146, v151, v140
	v_mov_b32_e32 v151, 0x41500000
	v_div_scale_f32 v146, s[26:27], v151, v151, v141
	v_rcp_f32_e32 v147, v146
	v_div_scale_f32 v148, vcc, v141, v151, v141
	v_fma_f32 v149, -v146, v147, 1.0
	v_fmac_f32_e32 v147, v149, v147
	v_mul_f32_e32 v149, v148, v147
	v_fma_f32 v150, -v146, v149, v148
	v_fmac_f32_e32 v149, v150, v147
	v_fma_f32 v146, -v146, v149, v148
	v_div_fmas_f32 v146, v146, v147, v149
	v_div_fixup_f32 v141, v146, v151, v141
	v_mov_b32_e32 v151, 0x41500000
	v_div_scale_f32 v146, s[26:27], v151, v151, v142
	v_rcp_f32_e32 v147, v146
	v_div_scale_f32 v148, vcc, v142, v151, v142
	v_fma_f32 v149, -v146, v147, 1.0
	v_fmac_f32_e32 v147, v149, v147
	v_mul_f32_e32 v149, v148, v147
	v_fma_f32 v150, -v146, v149, v148
	v_fmac_f32_e32 v149, v150, v147
	v_fma_f32 v146, -v146, v149, v148
	v_div_fmas_f32 v146, v146, v147, v149
	v_div_fixup_f32 v142, v146, v151, v142
	v_mov_b32_e32 v151, 0x41500000
	v_div_scale_f32 v146, s[26:27], v151, v151, v143
	v_rcp_f32_e32 v147, v146
	v_div_scale_f32 v148, vcc, v143, v151, v143
	v_fma_f32 v149, -v146, v147, 1.0
	v_fmac_f32_e32 v147, v149, v147
	v_mul_f32_e32 v149, v148, v147
	v_fma_f32 v150, -v146, v149, v148
	v_fmac_f32_e32 v149, v150, v147
	v_fma_f32 v146, -v146, v149, v148
	v_div_fmas_f32 v146, v146, v147, v149
	v_div_fixup_f32 v143, v146, v151, v143
	v_sub_f32_e32 v140, v140, v64
	v_sub_f32_e32 v141, v141, v65
	v_sub_f32_e32 v142, v142, v66
	v_sub_f32_e32 v143, v143, v67
	v_cvt_pk_bf16_f32 v176, v140, v141
	v_cvt_pk_bf16_f32 v177, v142, v143
	s_waitcnt vmcnt(2)
; DI float bflo(unsigned u) { return __uint_as_float(u << 16); }
; DI float bfhi(unsigned u) { return __uint_as_float(u & 0xffff0000u); }
; template <int WIN>
; DI void pool_elem(const Params& p, int row, int c) {
;     ...
;   if (row < NPR) {
;     const int t = row & 2047, b = row >> 11;
;     if (t >= WIN - 1) {
;       cnt = (float)WIN;
;       unsigned w[WIN - 1];
; #pragma unroll
;       for (int j = 1; j < WIN; ++j) w[j - 1] = *(const unsigned*)(P2 + (size_t)(row - j) * 2048 + c);
; #pragma unroll
;       for (int j = 1; j < WIN; ++j) { s0 += bflo(w[j - 1]); s1 += bfhi(w[j - 1]); }
;     } else {
;       cnt = (float)(t + 1);
;       for (int j = 1; j <= t; ++j) {
;         unsigned w = *(const unsigned*)(P2 + (size_t)(row - j) * 2048 + c);
;         s0 += bflo(w); s1 += bfhi(w);
;       }
;     }
;     ...
;   *(unsigned*)(p.MIX + (size_t)row * 1024 + c) = pack2(s0 / cnt - u0, s1 / cnt - u1);
	v_and_b32_e32 v71, 0xffff0000, v69
	v_lshlrev_b32_e32 v70, 16, v69
	v_and_b32_e32 v69, 0xffff0000, v68
	v_lshlrev_b32_e32 v68, 16, v68
	v_add_f32_e32 v140, v68, v64
	v_add_f32_e32 v141, v69, v65
	v_add_f32_e32 v142, v70, v66
	v_add_f32_e32 v143, v71, v67
	v_add_f32_e32 v140, v140, v60
	v_add_f32_e32 v141, v141, v61
	v_add_f32_e32 v142, v142, v62
	v_add_f32_e32 v143, v143, v63
	v_add_f32_e32 v140, v140, v56
	v_add_f32_e32 v141, v141, v57
	v_add_f32_e32 v142, v142, v58
	v_add_f32_e32 v143, v143, v59
	v_add_f32_e32 v140, v140, v52
	v_add_f32_e32 v141, v141, v53
	v_add_f32_e32 v142, v142, v54
	v_add_f32_e32 v143, v143, v55
	v_add_f32_e32 v140, v140, v48
	v_add_f32_e32 v141, v141, v49
	v_add_f32_e32 v142, v142, v50
	v_add_f32_e32 v143, v143, v51
	v_add_f32_e32 v140, v140, v44
	v_add_f32_e32 v141, v141, v45
	v_add_f32_e32 v142, v142, v46
	v_add_f32_e32 v143, v143, v47
	v_add_f32_e32 v140, v140, v40
	v_add_f32_e32 v141, v141, v41
	v_add_f32_e32 v142, v142, v42
	v_add_f32_e32 v143, v143, v43
	v_add_f32_e32 v140, v140, v36
	v_add_f32_e32 v141, v141, v37
	v_add_f32_e32 v142, v142, v38
	v_add_f32_e32 v143, v143, v39
	v_add_f32_e32 v140, v140, v32
	v_add_f32_e32 v141, v141, v33
	v_add_f32_e32 v142, v142, v34
	v_add_f32_e32 v143, v143, v35
	v_add_f32_e32 v140, v140, v28
	v_add_f32_e32 v141, v141, v29
	v_add_f32_e32 v142, v142, v30
	v_add_f32_e32 v143, v143, v31
	v_add_f32_e32 v140, v140, v24
	v_add_f32_e32 v141, v141, v25
	v_add_f32_e32 v142, v142, v26
	v_add_f32_e32 v143, v143, v27
	v_add_f32_e32 v140, v140, v20
	v_add_f32_e32 v141, v141, v21
	v_add_f32_e32 v142, v142, v22
	v_add_f32_e32 v143, v143, v23
	v_add_f32_e32 v140, v140, v16
	v_add_f32_e32 v141, v141, v17
	v_add_f32_e32 v142, v142, v18
	v_add_f32_e32 v143, v143, v19
	v_mov_b32_e32 v151, 0x41600000
	v_div_scale_f32 v146, s[26:27], v151, v151, v140
	v_rcp_f32_e32 v147, v146
	v_div_scale_f32 v148, vcc, v140, v151, v140
	v_fma_f32 v149, -v146, v147, 1.0
	v_fmac_f32_e32 v147, v149, v147
	v_mul_f32_e32 v149, v148, v147
	v_fma_f32 v150, -v146, v149, v148
	v_fmac_f32_e32 v149, v150, v147
	v_fma_f32 v146, -v146, v149, v148
	v_div_fmas_f32 v146, v146, v147, v149
	v_div_fixup_f32 v140, v146, v151, v140
	v_mov_b32_e32 v151, 0x41600000
	v_div_scale_f32 v146, s[26:27], v151, v151, v141
	v_rcp_f32_e32 v147, v146
	v_div_scale_f32 v148, vcc, v141, v151, v141
	v_fma_f32 v149, -v146, v147, 1.0
	v_fmac_f32_e32 v147, v149, v147
	v_mul_f32_e32 v149, v148, v147
	v_fma_f32 v150, -v146, v149, v148
	v_fmac_f32_e32 v149, v150, v147
	v_fma_f32 v146, -v146, v149, v148
	v_div_fmas_f32 v146, v146, v147, v149
	v_div_fixup_f32 v141, v146, v151, v141
	v_mov_b32_e32 v151, 0x41600000
	v_div_scale_f32 v146, s[26:27], v151, v151, v142
	v_rcp_f32_e32 v147, v146
	v_div_scale_f32 v148, vcc, v142, v151, v142
	v_fma_f32 v149, -v146, v147, 1.0
	v_fmac_f32_e32 v147, v149, v147
	v_mul_f32_e32 v149, v148, v147
	v_fma_f32 v150, -v146, v149, v148
	v_fmac_f32_e32 v149, v150, v147
	v_fma_f32 v146, -v146, v149, v148
	v_div_fmas_f32 v146, v146, v147, v149
	v_div_fixup_f32 v142, v146, v151, v142
	v_mov_b32_e32 v151, 0x41600000
	v_div_scale_f32 v146, s[26:27], v151, v151, v143
	v_rcp_f32_e32 v147, v146
	v_div_scale_f32 v148, vcc, v143, v151, v143
	v_fma_f32 v149, -v146, v147, 1.0
	v_fmac_f32_e32 v147, v149, v147
	v_mul_f32_e32 v149, v148, v147
	v_fma_f32 v150, -v146, v149, v148
	v_fmac_f32_e32 v149, v150, v147
	v_fma_f32 v146, -v146, v149, v148
	v_div_fmas_f32 v146, v146, v147, v149
	v_div_fixup_f32 v143, v146, v151, v143
	v_sub_f32_e32 v140, v140, v68
	v_sub_f32_e32 v141, v141, v69
	v_sub_f32_e32 v142, v142, v70
	v_sub_f32_e32 v143, v143, v71
	v_cvt_pk_bf16_f32 v178, v140, v141
	v_cvt_pk_bf16_f32 v179, v142, v143
	s_waitcnt vmcnt(1)
	v_and_b32_e32 v75, 0xffff0000, v73
	v_lshlrev_b32_e32 v74, 16, v73
	v_and_b32_e32 v73, 0xffff0000, v72
	v_lshlrev_b32_e32 v72, 16, v72
	v_add_f32_e32 v140, v72, v68
	v_add_f32_e32 v141, v73, v69
	v_add_f32_e32 v142, v74, v70
	v_add_f32_e32 v143, v75, v71
	v_add_f32_e32 v140, v140, v64
	v_add_f32_e32 v141, v141, v65
	v_add_f32_e32 v142, v142, v66
	v_add_f32_e32 v143, v143, v67
	v_add_f32_e32 v140, v140, v60
	v_add_f32_e32 v141, v141, v61
	v_add_f32_e32 v142, v142, v62
	v_add_f32_e32 v143, v143, v63
	v_add_f32_e32 v140, v140, v56
	v_add_f32_e32 v141, v141, v57
	v_add_f32_e32 v142, v142, v58
	v_add_f32_e32 v143, v143, v59
	v_add_f32_e32 v140, v140, v52
	v_add_f32_e32 v141, v141, v53
	v_add_f32_e32 v142, v142, v54
	v_add_f32_e32 v143, v143, v55
	v_add_f32_e32 v140, v140, v48
	v_add_f32_e32 v141, v141, v49
	v_add_f32_e32 v142, v142, v50
	v_add_f32_e32 v143, v143, v51
	v_add_f32_e32 v140, v140, v44
	v_add_f32_e32 v141, v141, v45
	v_add_f32_e32 v142, v142, v46
	v_add_f32_e32 v143, v143, v47
	v_add_f32_e32 v140, v140, v40
	v_add_f32_e32 v141, v141, v41
	v_add_f32_e32 v142, v142, v42
	v_add_f32_e32 v143, v143, v43
	v_add_f32_e32 v140, v140, v36
	v_add_f32_e32 v141, v141, v37
	v_add_f32_e32 v142, v142, v38
	v_add_f32_e32 v143, v143, v39
	v_add_f32_e32 v140, v140, v32
	v_add_f32_e32 v141, v141, v33
	v_add_f32_e32 v142, v142, v34
	v_add_f32_e32 v143, v143, v35
	v_add_f32_e32 v140, v140, v28
	v_add_f32_e32 v141, v141, v29
	v_add_f32_e32 v142, v142, v30
	v_add_f32_e32 v143, v143, v31
	v_add_f32_e32 v140, v140, v24
	v_add_f32_e32 v141, v141, v25
	v_add_f32_e32 v142, v142, v26
	v_add_f32_e32 v143, v143, v27
	v_add_f32_e32 v140, v140, v20
	v_add_f32_e32 v141, v141, v21
	v_add_f32_e32 v142, v142, v22
	v_add_f32_e32 v143, v143, v23
	v_add_f32_e32 v140, v140, v16
	v_add_f32_e32 v141, v141, v17
	v_add_f32_e32 v142, v142, v18
	v_add_f32_e32 v143, v143, v19
	v_mov_b32_e32 v151, 0x41700000
	v_div_scale_f32 v146, s[26:27], v151, v151, v140
; DI float bflo(unsigned u) { return __uint_as_float(u << 16); }
; DI float bfhi(unsigned u) { return __uint_as_float(u & 0xffff0000u); }
; template <int WIN>
; DI void pool_elem(const Params& p, int row, int c) {
;     ...
;   if (row < NPR) {
;     const int t = row & 2047, b = row >> 11;
;     if (t >= WIN - 1) {
;       cnt = (float)WIN;
;       unsigned w[WIN - 1];
; #pragma unroll
;       for (int j = 1; j < WIN; ++j) w[j - 1] = *(const unsigned*)(P2 + (size_t)(row - j) * 2048 + c);
; #pragma unroll
;       for (int j = 1; j < WIN; ++j) { s0 += bflo(w[j - 1]); s1 += bfhi(w[j - 1]); }
;     } else {
;       cnt = (float)(t + 1);
;       for (int j = 1; j <= t; ++j) {
;         unsigned w = *(const unsigned*)(P2 + (size_t)(row - j) * 2048 + c);
;         s0 += bflo(w); s1 += bfhi(w);
;       }
;     }
;     ...
;   *(unsigned*)(p.MIX + (size_t)row * 1024 + c) = pack2(s0 / cnt - u0, s1 / cnt - u1);
	v_rcp_f32_e32 v147, v146
	v_div_scale_f32 v148, vcc, v140, v151, v140
	v_fma_f32 v149, -v146, v147, 1.0
	v_fmac_f32_e32 v147, v149, v147
	v_mul_f32_e32 v149, v148, v147
	v_fma_f32 v150, -v146, v149, v148
	v_fmac_f32_e32 v149, v150, v147
	v_fma_f32 v146, -v146, v149, v148
	v_div_fmas_f32 v146, v146, v147, v149
	v_div_fixup_f32 v140, v146, v151, v140
	v_mov_b32_e32 v151, 0x41700000
	v_div_scale_f32 v146, s[26:27], v151, v151, v141
	v_rcp_f32_e32 v147, v146
	v_div_scale_f32 v148, vcc, v141, v151, v141
	v_fma_f32 v149, -v146, v147, 1.0
	v_fmac_f32_e32 v147, v149, v147
	v_mul_f32_e32 v149, v148, v147
	v_fma_f32 v150, -v146, v149, v148
	v_fmac_f32_e32 v149, v150, v147
	v_fma_f32 v146, -v146, v149, v148
	v_div_fmas_f32 v146, v146, v147, v149
	v_div_fixup_f32 v141, v146, v151, v141
	v_mov_b32_e32 v151, 0x41700000
	v_div_scale_f32 v146, s[26:27], v151, v151, v142
	v_rcp_f32_e32 v147, v146
	v_div_scale_f32 v148, vcc, v142, v151, v142
	v_fma_f32 v149, -v146, v147, 1.0
	v_fmac_f32_e32 v147, v149, v147
	v_mul_f32_e32 v149, v148, v147
	v_fma_f32 v150, -v146, v149, v148
	v_fmac_f32_e32 v149, v150, v147
	v_fma_f32 v146, -v146, v149, v148
	v_div_fmas_f32 v146, v146, v147, v149
	v_div_fixup_f32 v142, v146, v151, v142
	v_mov_b32_e32 v151, 0x41700000
	v_div_scale_f32 v146, s[26:27], v151, v151, v143
	v_rcp_f32_e32 v147, v146
	v_div_scale_f32 v148, vcc, v143, v151, v143
	v_fma_f32 v149, -v146, v147, 1.0
	v_fmac_f32_e32 v147, v149, v147
	v_mul_f32_e32 v149, v148, v147
	v_fma_f32 v150, -v146, v149, v148
	v_fmac_f32_e32 v149, v150, v147
	v_fma_f32 v146, -v146, v149, v148
	v_div_fmas_f32 v146, v146, v147, v149
	v_div_fixup_f32 v143, v146, v151, v143
	v_sub_f32_e32 v140, v140, v72
	v_sub_f32_e32 v141, v141, v73
	v_sub_f32_e32 v142, v142, v74
	v_sub_f32_e32 v143, v143, v75
	v_cvt_pk_bf16_f32 v180, v140, v141
	v_cvt_pk_bf16_f32 v181, v142, v143
	s_waitcnt vmcnt(0)
	v_and_b32_e32 v79, 0xffff0000, v77
	v_lshlrev_b32_e32 v78, 16, v77
	v_and_b32_e32 v77, 0xffff0000, v76
	v_lshlrev_b32_e32 v76, 16, v76
	v_add_f32_e32 v140, v76, v72
	v_add_f32_e32 v141, v77, v73
	v_add_f32_e32 v142, v78, v74
	v_add_f32_e32 v143, v79, v75
	v_add_f32_e32 v140, v140, v68
	v_add_f32_e32 v141, v141, v69
	v_add_f32_e32 v142, v142, v70
	v_add_f32_e32 v143, v143, v71
	v_add_f32_e32 v140, v140, v64
	v_add_f32_e32 v141, v141, v65
	v_add_f32_e32 v142, v142, v66
	v_add_f32_e32 v143, v143, v67
	v_add_f32_e32 v140, v140, v60
	v_add_f32_e32 v141, v141, v61
	v_add_f32_e32 v142, v142, v62
	v_add_f32_e32 v143, v143, v63
	v_add_f32_e32 v140, v140, v56
	v_add_f32_e32 v141, v141, v57
	v_add_f32_e32 v142, v142, v58
	v_add_f32_e32 v143, v143, v59
	v_add_f32_e32 v140, v140, v52
	v_add_f32_e32 v141, v141, v53
	v_add_f32_e32 v142, v142, v54
	v_add_f32_e32 v143, v143, v55
	v_add_f32_e32 v140, v140, v48
	v_add_f32_e32 v141, v141, v49
	v_add_f32_e32 v142, v142, v50
	v_add_f32_e32 v143, v143, v51
	v_add_f32_e32 v140, v140, v44
	v_add_f32_e32 v141, v141, v45
	v_add_f32_e32 v142, v142, v46
	v_add_f32_e32 v143, v143, v47
	v_add_f32_e32 v140, v140, v40
	v_add_f32_e32 v141, v141, v41
	v_add_f32_e32 v142, v142, v42
	v_add_f32_e32 v143, v143, v43
	v_add_f32_e32 v140, v140, v36
	v_add_f32_e32 v141, v141, v37
	v_add_f32_e32 v142, v142, v38
	v_add_f32_e32 v143, v143, v39
	v_add_f32_e32 v140, v140, v32
	v_add_f32_e32 v141, v141, v33
	v_add_f32_e32 v142, v142, v34
	v_add_f32_e32 v143, v143, v35
	v_add_f32_e32 v140, v140, v28
	v_add_f32_e32 v141, v141, v29
	v_add_f32_e32 v142, v142, v30
	v_add_f32_e32 v143, v143, v31
	v_add_f32_e32 v140, v140, v24
	v_add_f32_e32 v141, v141, v25
	v_add_f32_e32 v142, v142, v26
	v_add_f32_e32 v143, v143, v27
	v_add_f32_e32 v140, v140, v20
	v_add_f32_e32 v141, v141, v21
	v_add_f32_e32 v142, v142, v22
	v_add_f32_e32 v143, v143, v23
	v_add_f32_e32 v140, v140, v16
	v_add_f32_e32 v141, v141, v17
	v_add_f32_e32 v142, v142, v18
	v_add_f32_e32 v143, v143, v19
	v_mul_f32_e32 v140, 0x3d800000, v140
	v_mul_f32_e32 v141, 0x3d800000, v141
	v_mul_f32_e32 v142, 0x3d800000, v142
	v_mul_f32_e32 v143, 0x3d800000, v143
	v_sub_f32_e32 v140, v140, v76
	v_sub_f32_e32 v141, v141, v77
	v_sub_f32_e32 v142, v142, v78
	v_sub_f32_e32 v143, v143, v79
	v_cvt_pk_bf16_f32 v182, v140, v141
	v_cvt_pk_bf16_f32 v183, v142, v143
	global_store_dwordx2 v11, v[152:153], s[24:25]
	s_add_u32 s24, s24, 0x800
	s_addc_u32 s25, s25, 0
	global_store_dwordx2 v11, v[154:155], s[24:25]
	s_add_u32 s24, s24, 0x800
	s_addc_u32 s25, s25, 0
	global_store_dwordx2 v11, v[156:157], s[24:25]
	s_add_u32 s24, s24, 0x800
	s_addc_u32 s25, s25, 0
	global_store_dwordx2 v11, v[158:159], s[24:25]
	s_add_u32 s24, s24, 0x800
	s_addc_u32 s25, s25, 0
	global_store_dwordx2 v11, v[160:161], s[24:25]
	s_add_u32 s24, s24, 0x800
	s_addc_u32 s25, s25, 0
	global_store_dwordx2 v11, v[162:163], s[24:25]
	s_add_u32 s24, s24, 0x800
	s_addc_u32 s25, s25, 0
	global_store_dwordx2 v11, v[164:165], s[24:25]
	s_add_u32 s24, s24, 0x800
	s_addc_u32 s25, s25, 0
	global_store_dwordx2 v11, v[166:167], s[24:25]
	s_add_u32 s24, s24, 0x800
	s_addc_u32 s25, s25, 0
	global_store_dwordx2 v11, v[168:169], s[24:25]
	s_add_u32 s24, s24, 0x800
	s_addc_u32 s25, s25, 0
	global_store_dwordx2 v11, v[170:171], s[24:25]
	s_add_u32 s24, s24, 0x800
	s_addc_u32 s25, s25, 0
	global_store_dwordx2 v11, v[172:173], s[24:25]
	s_add_u32 s24, s24, 0x800
	s_addc_u32 s25, s25, 0
	global_store_dwordx2 v11, v[174:175], s[24:25]
	s_add_u32 s24, s24, 0x800
	s_addc_u32 s25, s25, 0
	global_store_dwordx2 v11, v[176:177], s[24:25]
	s_add_u32 s24, s24, 0x800
	s_addc_u32 s25, s25, 0
	global_store_dwordx2 v11, v[178:179], s[24:25]
	s_add_u32 s24, s24, 0x800
	s_addc_u32 s25, s25, 0
	global_store_dwordx2 v11, v[180:181], s[24:25]
	s_add_u32 s24, s24, 0x800
	s_addc_u32 s25, s25, 0
	global_store_dwordx2 v11, v[182:183], s[24:25]
	s_add_u32 s24, s24, 0x800
	s_addc_u32 s25, s25, 0
	s_branch .Lp13f_next
